# GEMM K-loops: closing barrier issued right after the MFMA burst; SALU/VALU bookkeeping moved behind it
# speedup vs baseline: 1.0053x; 1.0053x over previous
.LBB0_297:
	s_add_u32 s22, s20, 0xfffc0080
	s_addc_u32 s23, s21, -1
	s_add_i32 s49, 0, 0x10000
	v_add_u32_e32 v145, s49, v142
	ds_read_b128 v[146:149], v145
	ds_read_b128 v[150:153], v145 offset:1024
	ds_read_b128 v[154:157], v145 offset:2048
	ds_read_b128 v[158:161], v145 offset:3072
	s_cmp_eq_u32 s48, 12
	s_cselect_b32 s25, s9, s23
	s_cselect_b32 s24, s44, s22
	s_cselect_b32 s23, s7, s47
	s_cselect_b32 s22, s45, s46
	s_add_i32 m0, s19, 0xc000
	ds_read_b128 v[162:165], v144
	ds_read_b128 v[166:169], v144 offset:1024
	ds_read_b128 v[170:173], v144 offset:2048
	ds_read_b128 v[174:177], v144 offset:3072
	ds_read_b128 v[190:193], v144 offset:4096
	ds_read_b128 v[194:197], v144 offset:5120
	ds_read_b128 v[198:201], v144 offset:6144
	ds_read_b128 v[202:205], v144 offset:7168
	global_load_lds_dwordx4 v138, s[20:21]
	s_add_i32 m0, s19, 0xe000
	s_nop 0
	global_load_lds_dwordx4 v140, s[20:21]
	s_waitcnt lgkmcnt(8)
	s_barrier
	s_waitcnt lgkmcnt(0)
	s_waitcnt lgkmcnt(0)
	v_mfma_f32_16x16x32_bf16 v[126:129], v[146:149], v[162:165], v[126:129]
	v_mfma_f32_16x16x32_bf16 v[118:121], v[154:157], v[162:165], v[118:121]
	v_mfma_f32_16x16x32_bf16 v[110:113], v[146:149], v[170:173], v[110:113]
	v_mfma_f32_16x16x32_bf16 v[102:105], v[154:157], v[170:173], v[102:105]
	v_mfma_f32_16x16x32_bf16 v[94:97], v[146:149], v[190:193], v[94:97]
	v_mfma_f32_16x16x32_bf16 v[86:89], v[154:157], v[190:193], v[86:89]
	v_mfma_f32_16x16x32_bf16 v[78:81], v[146:149], v[198:201], v[78:81]
	v_mfma_f32_16x16x32_bf16 v[70:73], v[154:157], v[198:201], v[70:73]
	v_mfma_f32_16x16x32_bf16 v[126:129], v[150:153], v[166:169], v[126:129]
	v_mfma_f32_16x16x32_bf16 v[118:121], v[158:161], v[166:169], v[118:121]
	v_mfma_f32_16x16x32_bf16 v[110:113], v[150:153], v[174:177], v[110:113]
	v_mfma_f32_16x16x32_bf16 v[102:105], v[158:161], v[174:177], v[102:105]
	v_mfma_f32_16x16x32_bf16 v[94:97], v[150:153], v[194:197], v[94:97]
	v_mfma_f32_16x16x32_bf16 v[86:89], v[158:161], v[194:197], v[86:89]
	v_mfma_f32_16x16x32_bf16 v[78:81], v[150:153], v[202:205], v[78:81]
	v_mfma_f32_16x16x32_bf16 v[70:73], v[158:161], v[202:205], v[70:73]
	s_barrier
	s_add_i32 s54, 0, 0x14000
	s_add_i32 s49, s49, s35
	v_add_u32_e32 v145, s54, v142
	s_add_u32 s64, s22, 0x80
	s_addc_u32 s65, s23, 0
	s_mov_b32 m0, s49
	ds_read_b128 v[206:209], v145
	ds_read_b128 v[210:213], v145 offset:1024
	ds_read_b128 v[214:217], v145 offset:2048
	ds_read_b128 v[218:221], v145 offset:3072
	global_load_lds_dwordx4 v134, s[22:23]
	s_add_i32 m0, s49, 0x2000
	s_nop 0
	global_load_lds_dwordx4 v130, s[22:23]
	s_barrier
	s_waitcnt lgkmcnt(0)
	s_waitcnt lgkmcnt(0)
	v_mfma_f32_16x16x32_bf16 v[122:125], v[206:209], v[162:165], v[122:125]
	v_mfma_f32_16x16x32_bf16 v[114:117], v[214:217], v[162:165], v[114:117]
	v_mfma_f32_16x16x32_bf16 v[106:109], v[206:209], v[170:173], v[106:109]
	v_mfma_f32_16x16x32_bf16 v[98:101], v[214:217], v[170:173], v[98:101]
	v_mfma_f32_16x16x32_bf16 v[90:93], v[206:209], v[190:193], v[90:93]
	v_mfma_f32_16x16x32_bf16 v[82:85], v[214:217], v[190:193], v[82:85]
	v_mfma_f32_16x16x32_bf16 v[74:77], v[206:209], v[198:201], v[74:77]
	v_mfma_f32_16x16x32_bf16 v[66:69], v[214:217], v[198:201], v[66:69]
	v_mfma_f32_16x16x32_bf16 v[122:125], v[210:213], v[166:169], v[122:125]
	v_mfma_f32_16x16x32_bf16 v[114:117], v[218:221], v[166:169], v[114:117]
	v_mfma_f32_16x16x32_bf16 v[106:109], v[210:213], v[174:177], v[106:109]
	v_mfma_f32_16x16x32_bf16 v[98:101], v[218:221], v[174:177], v[98:101]
	v_mfma_f32_16x16x32_bf16 v[90:93], v[210:213], v[194:197], v[90:93]
	v_mfma_f32_16x16x32_bf16 v[82:85], v[218:221], v[194:197], v[82:85]
	v_mfma_f32_16x16x32_bf16 v[74:77], v[210:213], v[202:205], v[74:77]
	v_mfma_f32_16x16x32_bf16 v[66:69], v[218:221], v[202:205], v[66:69]
	s_barrier
	s_mov_b32 m0, s19
	s_add_u32 s62, s24, 0x80
	s_addc_u32 s63, s25, 0
	ds_read_b128 v[162:165], v144 offset:16384
	ds_read_b128 v[166:169], v144 offset:17408
	ds_read_b128 v[170:173], v144 offset:18432
	ds_read_b128 v[174:177], v144 offset:19456
	ds_read_b128 v[190:193], v144 offset:20480
	ds_read_b128 v[194:197], v144 offset:21504
	ds_read_b128 v[198:201], v144 offset:22528
	ds_read_b128 v[202:205], v144 offset:23552
	global_load_lds_dwordx4 v136, s[24:25]
	s_mov_b32 m0, s36
	s_nop 0
	global_load_lds_dwordx4 v132, s[24:25]
	s_barrier
	s_waitcnt lgkmcnt(0)
	s_waitcnt lgkmcnt(0)
	v_mfma_f32_16x16x32_bf16 v[62:65], v[146:149], v[162:165], v[62:65]
	v_mfma_f32_16x16x32_bf16 v[54:57], v[154:157], v[162:165], v[54:57]
	v_mfma_f32_16x16x32_bf16 v[46:49], v[146:149], v[170:173], v[46:49]
	v_mfma_f32_16x16x32_bf16 v[38:41], v[154:157], v[170:173], v[38:41]
	v_mfma_f32_16x16x32_bf16 v[30:33], v[146:149], v[190:193], v[30:33]
	v_mfma_f32_16x16x32_bf16 v[22:25], v[154:157], v[190:193], v[22:25]
	v_mfma_f32_16x16x32_bf16 v[14:17], v[146:149], v[198:201], v[14:17]
	v_mfma_f32_16x16x32_bf16 v[6:9], v[154:157], v[198:201], v[6:9]
	v_mfma_f32_16x16x32_bf16 v[62:65], v[150:153], v[166:169], v[62:65]
	v_mfma_f32_16x16x32_bf16 v[54:57], v[158:161], v[166:169], v[54:57]
	v_mfma_f32_16x16x32_bf16 v[46:49], v[150:153], v[174:177], v[46:49]
	v_mfma_f32_16x16x32_bf16 v[38:41], v[158:161], v[174:177], v[38:41]
	v_mfma_f32_16x16x32_bf16 v[30:33], v[150:153], v[194:197], v[30:33]
	v_mfma_f32_16x16x32_bf16 v[22:25], v[158:161], v[194:197], v[22:25]
	v_mfma_f32_16x16x32_bf16 v[14:17], v[150:153], v[202:205], v[14:17]
	v_mfma_f32_16x16x32_bf16 v[6:9], v[158:161], v[202:205], v[6:9]
	s_barrier
	s_add_u32 s50, s22, 0x40000
	s_addc_u32 s51, s23, 0
	s_add_i32 s49, s54, s35
	s_mov_b32 m0, s49
	s_nop 0
	global_load_lds_dwordx4 v134, s[50:51]
	s_add_i32 m0, s49, 0x2000
	s_nop 0
	global_load_lds_dwordx4 v130, s[50:51]
	s_waitcnt vmcnt(6)
	s_barrier
	v_mfma_f32_16x16x32_bf16 v[58:61], v[206:209], v[162:165], v[58:61]
	v_mfma_f32_16x16x32_bf16 v[50:53], v[214:217], v[162:165], v[50:53]
	v_mfma_f32_16x16x32_bf16 v[42:45], v[206:209], v[170:173], v[42:45]
	v_mfma_f32_16x16x32_bf16 v[34:37], v[214:217], v[170:173], v[34:37]
	v_mfma_f32_16x16x32_bf16 v[26:29], v[206:209], v[190:193], v[26:29]
	v_mfma_f32_16x16x32_bf16 v[18:21], v[214:217], v[190:193], v[18:21]
	v_mfma_f32_16x16x32_bf16 v[10:13], v[206:209], v[198:201], v[10:13]
	v_mfma_f32_16x16x32_bf16 v[2:5], v[214:217], v[198:201], v[2:5]
	v_mfma_f32_16x16x32_bf16 v[58:61], v[210:213], v[166:169], v[58:61]
	v_mfma_f32_16x16x32_bf16 v[50:53], v[218:221], v[166:169], v[50:53]
	v_mfma_f32_16x16x32_bf16 v[42:45], v[210:213], v[174:177], v[42:45]
	v_mfma_f32_16x16x32_bf16 v[34:37], v[218:221], v[174:177], v[34:37]
	v_mfma_f32_16x16x32_bf16 v[26:29], v[210:213], v[194:197], v[26:29]
	v_mfma_f32_16x16x32_bf16 v[18:21], v[218:221], v[194:197], v[18:21]
	v_mfma_f32_16x16x32_bf16 v[10:13], v[210:213], v[202:205], v[10:13]
	v_mfma_f32_16x16x32_bf16 v[2:5], v[218:221], v[202:205], v[2:5]
	s_barrier
	s_add_i32 s49, 0, 0x18000
	v_add_u32_e32 v145, s49, v142
	ds_read_b128 v[146:149], v145
	ds_read_b128 v[150:153], v145 offset:1024
	ds_read_b128 v[154:157], v145 offset:2048
	ds_read_b128 v[158:161], v145 offset:3072
	s_add_u32 s24, s24, 0x40000
	s_addc_u32 s25, s25, 0
	s_mov_b32 m0, s37
	ds_read_b128 v[162:165], v144 offset:32768
	ds_read_b128 v[166:169], v144 offset:33792
	ds_read_b128 v[170:173], v144 offset:34816
	ds_read_b128 v[174:177], v144 offset:35840
	ds_read_b128 v[190:193], v144 offset:36864
	ds_read_b128 v[194:197], v144 offset:37888
	ds_read_b128 v[198:201], v144 offset:38912
	ds_read_b128 v[202:205], v144 offset:39936
	global_load_lds_dwordx4 v136, s[24:25]
	s_mov_b32 m0, s38
	s_nop 0
	global_load_lds_dwordx4 v132, s[24:25]
	s_waitcnt lgkmcnt(8)
	s_barrier
	s_waitcnt lgkmcnt(0)
	s_waitcnt lgkmcnt(0)
	v_mfma_f32_16x16x32_bf16 v[126:129], v[146:149], v[162:165], v[126:129]
	v_mfma_f32_16x16x32_bf16 v[118:121], v[154:157], v[162:165], v[118:121]
	v_mfma_f32_16x16x32_bf16 v[110:113], v[146:149], v[170:173], v[110:113]
	v_mfma_f32_16x16x32_bf16 v[102:105], v[154:157], v[170:173], v[102:105]
	v_mfma_f32_16x16x32_bf16 v[94:97], v[146:149], v[190:193], v[94:97]
	v_mfma_f32_16x16x32_bf16 v[86:89], v[154:157], v[190:193], v[86:89]
	v_mfma_f32_16x16x32_bf16 v[78:81], v[146:149], v[198:201], v[78:81]
	v_mfma_f32_16x16x32_bf16 v[70:73], v[154:157], v[198:201], v[70:73]
	v_mfma_f32_16x16x32_bf16 v[126:129], v[150:153], v[166:169], v[126:129]
	v_mfma_f32_16x16x32_bf16 v[118:121], v[158:161], v[166:169], v[118:121]
	v_mfma_f32_16x16x32_bf16 v[110:113], v[150:153], v[174:177], v[110:113]
	v_mfma_f32_16x16x32_bf16 v[102:105], v[158:161], v[174:177], v[102:105]
	v_mfma_f32_16x16x32_bf16 v[94:97], v[150:153], v[194:197], v[94:97]
	v_mfma_f32_16x16x32_bf16 v[86:89], v[158:161], v[194:197], v[86:89]
	v_mfma_f32_16x16x32_bf16 v[78:81], v[150:153], v[202:205], v[78:81]
	v_mfma_f32_16x16x32_bf16 v[70:73], v[158:161], v[202:205], v[70:73]
	s_barrier
	s_add_i32 s24, 0, 0x1c000
	s_add_i32 s25, s49, s35
	v_add_u32_e32 v145, s24, v142
	s_mov_b32 m0, s25
	ds_read_b128 v[206:209], v145
	ds_read_b128 v[210:213], v145 offset:1024
	ds_read_b128 v[214:217], v145 offset:2048
	ds_read_b128 v[218:221], v145 offset:3072
	global_load_lds_dwordx4 v134, s[64:65]
	s_add_i32 m0, s25, 0x2000
	s_nop 0
	global_load_lds_dwordx4 v130, s[64:65]
	s_barrier
	s_waitcnt lgkmcnt(0)
	s_waitcnt lgkmcnt(0)
	v_mfma_f32_16x16x32_bf16 v[122:125], v[206:209], v[162:165], v[122:125]
	v_mfma_f32_16x16x32_bf16 v[114:117], v[214:217], v[162:165], v[114:117]
	v_mfma_f32_16x16x32_bf16 v[106:109], v[206:209], v[170:173], v[106:109]
	v_mfma_f32_16x16x32_bf16 v[98:101], v[214:217], v[170:173], v[98:101]
	v_mfma_f32_16x16x32_bf16 v[90:93], v[206:209], v[190:193], v[90:93]
	v_mfma_f32_16x16x32_bf16 v[82:85], v[214:217], v[190:193], v[82:85]
	v_mfma_f32_16x16x32_bf16 v[74:77], v[206:209], v[198:201], v[74:77]
	v_mfma_f32_16x16x32_bf16 v[66:69], v[214:217], v[198:201], v[66:69]
	v_mfma_f32_16x16x32_bf16 v[122:125], v[210:213], v[166:169], v[122:125]
	v_mfma_f32_16x16x32_bf16 v[114:117], v[218:221], v[166:169], v[114:117]
	v_mfma_f32_16x16x32_bf16 v[106:109], v[210:213], v[174:177], v[106:109]
	v_mfma_f32_16x16x32_bf16 v[98:101], v[218:221], v[174:177], v[98:101]
	v_mfma_f32_16x16x32_bf16 v[90:93], v[210:213], v[194:197], v[90:93]
	v_mfma_f32_16x16x32_bf16 v[82:85], v[218:221], v[194:197], v[82:85]
	v_mfma_f32_16x16x32_bf16 v[74:77], v[210:213], v[202:205], v[74:77]
	v_mfma_f32_16x16x32_bf16 v[66:69], v[218:221], v[202:205], v[66:69]
	s_barrier
	s_mov_b32 m0, s39
	ds_read_b128 v[162:165], v144 offset:49152
	ds_read_b128 v[166:169], v144 offset:50176
	ds_read_b128 v[170:173], v144 offset:51200
	ds_read_b128 v[174:177], v144 offset:52224
	ds_read_b128 v[190:193], v144 offset:53248
	ds_read_b128 v[194:197], v144 offset:54272
	ds_read_b128 v[198:201], v144 offset:55296
	ds_read_b128 v[202:205], v144 offset:56320
	global_load_lds_dwordx4 v136, s[62:63]
	s_mov_b32 m0, s40
	s_nop 0
	global_load_lds_dwordx4 v132, s[62:63]
	s_barrier
	s_waitcnt lgkmcnt(0)
	s_waitcnt lgkmcnt(0)
	v_mfma_f32_16x16x32_bf16 v[62:65], v[146:149], v[162:165], v[62:65]
	v_mfma_f32_16x16x32_bf16 v[54:57], v[154:157], v[162:165], v[54:57]
	v_mfma_f32_16x16x32_bf16 v[46:49], v[146:149], v[170:173], v[46:49]
	v_mfma_f32_16x16x32_bf16 v[38:41], v[154:157], v[170:173], v[38:41]
	v_mfma_f32_16x16x32_bf16 v[30:33], v[146:149], v[190:193], v[30:33]
	v_mfma_f32_16x16x32_bf16 v[22:25], v[154:157], v[190:193], v[22:25]
	v_mfma_f32_16x16x32_bf16 v[14:17], v[146:149], v[198:201], v[14:17]
	v_mfma_f32_16x16x32_bf16 v[6:9], v[154:157], v[198:201], v[6:9]
	v_mfma_f32_16x16x32_bf16 v[62:65], v[150:153], v[166:169], v[62:65]
	v_mfma_f32_16x16x32_bf16 v[54:57], v[158:161], v[166:169], v[54:57]
	v_mfma_f32_16x16x32_bf16 v[46:49], v[150:153], v[174:177], v[46:49]
	v_mfma_f32_16x16x32_bf16 v[38:41], v[158:161], v[174:177], v[38:41]
	v_mfma_f32_16x16x32_bf16 v[30:33], v[150:153], v[194:197], v[30:33]
	v_mfma_f32_16x16x32_bf16 v[22:25], v[158:161], v[194:197], v[22:25]
	v_mfma_f32_16x16x32_bf16 v[14:17], v[150:153], v[202:205], v[14:17]
	v_mfma_f32_16x16x32_bf16 v[6:9], v[158:161], v[202:205], v[6:9]
	s_barrier
	s_add_u32 s22, s22, 0x40080
	s_addc_u32 s23, s23, 0
	s_add_i32 s24, s24, s35
	s_mov_b32 m0, s24
	s_nop 0
	global_load_lds_dwordx4 v134, s[22:23]
	s_add_i32 m0, s24, 0x2000
	s_nop 0
	global_load_lds_dwordx4 v130, s[22:23]
	s_waitcnt vmcnt(6)
	s_barrier
	v_mfma_f32_16x16x32_bf16 v[58:61], v[206:209], v[162:165], v[58:61]
	v_mfma_f32_16x16x32_bf16 v[50:53], v[214:217], v[162:165], v[50:53]
	v_mfma_f32_16x16x32_bf16 v[42:45], v[206:209], v[170:173], v[42:45]
	v_mfma_f32_16x16x32_bf16 v[34:37], v[214:217], v[170:173], v[34:37]
	v_mfma_f32_16x16x32_bf16 v[26:29], v[206:209], v[190:193], v[26:29]
	v_mfma_f32_16x16x32_bf16 v[18:21], v[214:217], v[190:193], v[18:21]
	v_mfma_f32_16x16x32_bf16 v[10:13], v[206:209], v[198:201], v[10:13]
	v_mfma_f32_16x16x32_bf16 v[2:5], v[214:217], v[198:201], v[2:5]
	v_mfma_f32_16x16x32_bf16 v[58:61], v[210:213], v[166:169], v[58:61]
	v_mfma_f32_16x16x32_bf16 v[50:53], v[218:221], v[166:169], v[50:53]
	v_mfma_f32_16x16x32_bf16 v[42:45], v[210:213], v[174:177], v[42:45]
	v_mfma_f32_16x16x32_bf16 v[34:37], v[218:221], v[174:177], v[34:37]
	v_mfma_f32_16x16x32_bf16 v[26:29], v[210:213], v[194:197], v[26:29]
	v_mfma_f32_16x16x32_bf16 v[18:21], v[218:221], v[194:197], v[18:21]
	v_mfma_f32_16x16x32_bf16 v[10:13], v[210:213], v[202:205], v[10:13]
	v_mfma_f32_16x16x32_bf16 v[2:5], v[218:221], v[202:205], v[2:5]
	s_barrier
	s_add_i32 s48, s48, 2
	s_add_u32 s20, s20, 0x100
	s_addc_u32 s21, s21, 0
	s_add_u32 s46, s46, 0x100
	s_addc_u32 s47, s47, 0
	s_cmp_gt_u32 s48, 13
	s_cbranch_scc0 .LBB0_297
	v_mul_f32_e32 v148, 0xbfb8aa3b, v126
	v_mul_f32_e32 v149, 0xbfb8aa3b, v127
	v_exp_f32_e32 v148, v148
	v_exp_f32_e32 v149, v149
	v_lshl_or_b32 v146, s43, 7, v143
	v_lshl_add_u32 v145, s18, 8, v1
	v_add_f32_e32 v148, 1.0, v148
	v_add_f32_e32 v149, 1.0, v149
	v_rcp_f32_e32 v148, v148
	v_rcp_f32_e32 v149, v149
	v_ashrrev_i32_e32 v147, 31, v146
	s_movk_i32 s7, 0x1700
	s_and_b64 vcc, exec, s[4:5]
	v_pk_mul_f32 v[126:127], v[126:127], v[148:149]
	s_mov_b32 s43, s6
	v_pk_mul_f32 v[122:123], v[126:127], v[122:123]
	v_mul_f32_e32 v126, 0xbfb8aa3b, v128
	v_mul_f32_e32 v127, 0xbfb8aa3b, v129
	v_exp_f32_e32 v126, v126
	v_exp_f32_e32 v127, v127
	s_mov_b32 s18, s8
	s_mov_b64 s[22:23], s[14:15]
	v_add_f32_e32 v126, 1.0, v126
	v_add_f32_e32 v127, 1.0, v127
	v_rcp_f32_e32 v126, v126
	v_rcp_f32_e32 v127, v127
	s_nop 0
	v_pk_mul_f32 v[126:127], v[128:129], v[126:127]
	s_nop 0
	v_pk_mul_f32 v[124:125], v[126:127], v[124:125]
	v_mul_f32_e32 v126, 0xbfb8aa3b, v118
	v_mul_f32_e32 v127, 0xbfb8aa3b, v119
	v_exp_f32_e32 v126, v126
	v_exp_f32_e32 v127, v127
	v_add_f32_e32 v126, 1.0, v126
	v_add_f32_e32 v127, 1.0, v127
	v_rcp_f32_e32 v126, v126
	v_rcp_f32_e32 v127, v127
	s_nop 0
	v_pk_mul_f32 v[118:119], v[118:119], v[126:127]
	s_nop 0
	v_pk_mul_f32 v[114:115], v[118:119], v[114:115]
	v_mul_f32_e32 v118, 0xbfb8aa3b, v120
	v_mul_f32_e32 v119, 0xbfb8aa3b, v121
	v_exp_f32_e32 v118, v118
	v_exp_f32_e32 v119, v119
	v_add_f32_e32 v118, 1.0, v118
	v_add_f32_e32 v119, 1.0, v119
	v_rcp_f32_e32 v118, v118
	v_rcp_f32_e32 v119, v119
	s_nop 0
	v_pk_mul_f32 v[118:119], v[120:121], v[118:119]
	s_nop 0
	v_pk_mul_f32 v[116:117], v[118:119], v[116:117]
	v_cvt_pk_bf16_f32 v120, v114, v115
	v_mov_b64_e32 v[114:115], s[2:3]
	v_cvt_pk_bf16_f32 v118, v122, v123
	v_cvt_pk_bf16_f32 v121, v116, v117
	v_mad_i64_i32 v[122:123], s[20:21], v145, s7, v[114:115]
	v_lshlrev_b64 v[116:117], 1, v[146:147]
	v_cvt_pk_bf16_f32 v119, v124, v125
	v_lshl_add_u64 v[122:123], v[122:123], 0, v[116:117]
	global_store_dwordx4 v[122:123], v[118:121], off
	s_nop 1
	v_mul_f32_e32 v118, 0xbfb8aa3b, v110
	v_mul_f32_e32 v119, 0xbfb8aa3b, v111
	v_exp_f32_e32 v118, v118
	v_exp_f32_e32 v119, v119
	v_add_f32_e32 v118, 1.0, v118
	v_add_f32_e32 v119, 1.0, v119
	v_rcp_f32_e32 v118, v118
	v_rcp_f32_e32 v119, v119
	s_nop 0
	v_pk_mul_f32 v[110:111], v[110:111], v[118:119]
	s_nop 0
	v_pk_mul_f32 v[106:107], v[110:111], v[106:107]
	v_mul_f32_e32 v110, 0xbfb8aa3b, v112
	v_mul_f32_e32 v111, 0xbfb8aa3b, v113
	v_exp_f32_e32 v110, v110
	v_exp_f32_e32 v111, v111
	v_add_f32_e32 v110, 1.0, v110
	v_add_f32_e32 v111, 1.0, v111
	v_rcp_f32_e32 v110, v110
	v_rcp_f32_e32 v111, v111
	s_nop 0
	v_pk_mul_f32 v[110:111], v[112:113], v[110:111]
	s_nop 0
	v_pk_mul_f32 v[108:109], v[110:111], v[108:109]
	v_mul_f32_e32 v110, 0xbfb8aa3b, v102
	v_mul_f32_e32 v111, 0xbfb8aa3b, v103
	v_exp_f32_e32 v110, v110
	v_exp_f32_e32 v111, v111
	v_add_f32_e32 v110, 1.0, v110
	v_add_f32_e32 v111, 1.0, v111
	v_rcp_f32_e32 v110, v110
	v_rcp_f32_e32 v111, v111
	s_nop 0
	v_pk_mul_f32 v[102:103], v[102:103], v[110:111]
	s_nop 0
	v_pk_mul_f32 v[102:103], v[102:103], v[98:99]
	v_mul_f32_e32 v98, 0xbfb8aa3b, v104
	v_mul_f32_e32 v99, 0xbfb8aa3b, v105
	v_exp_f32_e32 v98, v98
	v_exp_f32_e32 v99, v99
	v_add_f32_e32 v98, 1.0, v98
	v_add_f32_e32 v99, 1.0, v99
	v_rcp_f32_e32 v98, v98
	v_rcp_f32_e32 v99, v99
	s_nop 0
	v_pk_mul_f32 v[98:99], v[104:105], v[98:99]
	s_nop 0
	v_pk_mul_f32 v[104:105], v[98:99], v[100:101]
	v_cvt_pk_bf16_f32 v100, v102, v103
	v_or_b32_e32 v102, 16, v145
	v_mad_i64_i32 v[102:103], s[20:21], v102, s7, v[114:115]
	v_cvt_pk_bf16_f32 v98, v106, v107
	v_cvt_pk_bf16_f32 v99, v108, v109
	v_cvt_pk_bf16_f32 v101, v104, v105
	v_lshl_add_u64 v[102:103], v[102:103], 0, v[116:117]
	global_store_dwordx4 v[102:103], v[98:101], off
	s_nop 1
	v_mul_f32_e32 v98, 0xbfb8aa3b, v94
	v_mul_f32_e32 v99, 0xbfb8aa3b, v95
	v_exp_f32_e32 v98, v98
	v_exp_f32_e32 v99, v99
	v_add_f32_e32 v98, 1.0, v98
	v_add_f32_e32 v99, 1.0, v99
	v_rcp_f32_e32 v98, v98
	v_rcp_f32_e32 v99, v99
	s_nop 0
	v_pk_mul_f32 v[94:95], v[94:95], v[98:99]
	s_nop 0
	v_pk_mul_f32 v[90:91], v[94:95], v[90:91]
	v_mul_f32_e32 v94, 0xbfb8aa3b, v96
	v_mul_f32_e32 v95, 0xbfb8aa3b, v97
	v_exp_f32_e32 v94, v94
	v_exp_f32_e32 v95, v95
	v_add_f32_e32 v94, 1.0, v94
	v_add_f32_e32 v95, 1.0, v95
	v_rcp_f32_e32 v94, v94
	v_rcp_f32_e32 v95, v95
	s_nop 0
	v_pk_mul_f32 v[94:95], v[96:97], v[94:95]
	s_nop 0
	v_pk_mul_f32 v[92:93], v[94:95], v[92:93]
	v_mul_f32_e32 v94, 0xbfb8aa3b, v86
	v_mul_f32_e32 v95, 0xbfb8aa3b, v87
	v_exp_f32_e32 v94, v94
	v_exp_f32_e32 v95, v95
	v_add_f32_e32 v94, 1.0, v94
	v_add_f32_e32 v95, 1.0, v95
	v_rcp_f32_e32 v94, v94
	v_rcp_f32_e32 v95, v95
	s_nop 0
	v_pk_mul_f32 v[86:87], v[86:87], v[94:95]
	s_nop 0
	v_pk_mul_f32 v[86:87], v[86:87], v[82:83]
	v_mul_f32_e32 v82, 0xbfb8aa3b, v88
	v_mul_f32_e32 v83, 0xbfb8aa3b, v89
	v_exp_f32_e32 v82, v82
	v_exp_f32_e32 v83, v83
	v_add_f32_e32 v82, 1.0, v82
	v_add_f32_e32 v83, 1.0, v83
	v_rcp_f32_e32 v82, v82
	v_rcp_f32_e32 v83, v83
	s_nop 0
	v_pk_mul_f32 v[82:83], v[88:89], v[82:83]
	s_nop 0
	v_pk_mul_f32 v[88:89], v[82:83], v[84:85]
	v_cvt_pk_bf16_f32 v84, v86, v87
	v_or_b32_e32 v86, 32, v145
	v_mad_i64_i32 v[86:87], s[20:21], v86, s7, v[114:115]
	v_cvt_pk_bf16_f32 v82, v90, v91
	v_cvt_pk_bf16_f32 v83, v92, v93
	v_cvt_pk_bf16_f32 v85, v88, v89
	v_lshl_add_u64 v[86:87], v[86:87], 0, v[116:117]
	global_store_dwordx4 v[86:87], v[82:85], off
	s_nop 1
	v_mul_f32_e32 v82, 0xbfb8aa3b, v78
	v_mul_f32_e32 v83, 0xbfb8aa3b, v79
	v_exp_f32_e32 v82, v82
	v_exp_f32_e32 v83, v83
	v_add_f32_e32 v82, 1.0, v82
	v_add_f32_e32 v83, 1.0, v83
	v_rcp_f32_e32 v82, v82
	v_rcp_f32_e32 v83, v83
	s_nop 0
	v_pk_mul_f32 v[78:79], v[78:79], v[82:83]
	s_nop 0
	v_pk_mul_f32 v[74:75], v[78:79], v[74:75]
	v_mul_f32_e32 v78, 0xbfb8aa3b, v80
	v_mul_f32_e32 v79, 0xbfb8aa3b, v81
	v_exp_f32_e32 v78, v78
	v_exp_f32_e32 v79, v79
	v_add_f32_e32 v78, 1.0, v78
	v_add_f32_e32 v79, 1.0, v79
	v_rcp_f32_e32 v78, v78
	v_rcp_f32_e32 v79, v79
	s_nop 0
	v_pk_mul_f32 v[78:79], v[80:81], v[78:79]
	s_nop 0
	v_pk_mul_f32 v[76:77], v[78:79], v[76:77]
	v_mul_f32_e32 v78, 0xbfb8aa3b, v70
	v_mul_f32_e32 v79, 0xbfb8aa3b, v71
	v_exp_f32_e32 v78, v78
	v_exp_f32_e32 v79, v79
	v_add_f32_e32 v78, 1.0, v78
	v_add_f32_e32 v79, 1.0, v79
	v_rcp_f32_e32 v78, v78
	v_rcp_f32_e32 v79, v79
	s_nop 0
	v_pk_mul_f32 v[70:71], v[70:71], v[78:79]
	s_nop 0
	v_pk_mul_f32 v[70:71], v[70:71], v[66:67]
	v_mul_f32_e32 v66, 0xbfb8aa3b, v72
	v_mul_f32_e32 v67, 0xbfb8aa3b, v73
	v_exp_f32_e32 v66, v66
	v_exp_f32_e32 v67, v67
	v_add_f32_e32 v66, 1.0, v66
	v_add_f32_e32 v67, 1.0, v67
	v_rcp_f32_e32 v66, v66
	v_rcp_f32_e32 v67, v67
	s_nop 0
	v_pk_mul_f32 v[66:67], v[72:73], v[66:67]
	s_nop 0
	v_pk_mul_f32 v[72:73], v[66:67], v[68:69]
	v_cvt_pk_bf16_f32 v68, v70, v71
	v_or_b32_e32 v70, 48, v145
	v_mad_i64_i32 v[70:71], s[20:21], v70, s7, v[114:115]
	v_cvt_pk_bf16_f32 v66, v74, v75
	v_cvt_pk_bf16_f32 v67, v76, v77
	v_cvt_pk_bf16_f32 v69, v72, v73
	v_lshl_add_u64 v[70:71], v[70:71], 0, v[116:117]
	global_store_dwordx4 v[70:71], v[66:69], off
	s_nop 1
	v_mul_f32_e32 v66, 0xbfb8aa3b, v62
	v_mul_f32_e32 v67, 0xbfb8aa3b, v63
	v_exp_f32_e32 v66, v66
	v_exp_f32_e32 v67, v67
	v_add_u32_e32 v68, 0x80, v145
	v_add_f32_e32 v66, 1.0, v66
	v_add_f32_e32 v67, 1.0, v67
	v_rcp_f32_e32 v66, v66
	v_rcp_f32_e32 v67, v67
	s_nop 0
	v_pk_mul_f32 v[62:63], v[62:63], v[66:67]
	s_nop 0
	v_pk_mul_f32 v[58:59], v[62:63], v[58:59]
	v_mul_f32_e32 v62, 0xbfb8aa3b, v64
	v_mul_f32_e32 v63, 0xbfb8aa3b, v65
	v_exp_f32_e32 v62, v62
	v_exp_f32_e32 v63, v63
	v_add_f32_e32 v62, 1.0, v62
	v_add_f32_e32 v63, 1.0, v63
	v_rcp_f32_e32 v62, v62
	v_rcp_f32_e32 v63, v63
	s_nop 0
	v_pk_mul_f32 v[62:63], v[64:65], v[62:63]
	s_nop 0
	v_pk_mul_f32 v[60:61], v[62:63], v[60:61]
	v_mul_f32_e32 v62, 0xbfb8aa3b, v54
	v_mul_f32_e32 v63, 0xbfb8aa3b, v55
	v_exp_f32_e32 v62, v62
	v_exp_f32_e32 v63, v63
	v_add_f32_e32 v62, 1.0, v62
	v_add_f32_e32 v63, 1.0, v63
	v_rcp_f32_e32 v62, v62
	v_rcp_f32_e32 v63, v63
	s_nop 0
	v_pk_mul_f32 v[54:55], v[54:55], v[62:63]
	s_nop 0
	v_pk_mul_f32 v[54:55], v[54:55], v[50:51]
	v_mul_f32_e32 v50, 0xbfb8aa3b, v56
	v_mul_f32_e32 v51, 0xbfb8aa3b, v57
	v_exp_f32_e32 v50, v50
	v_exp_f32_e32 v51, v51
	v_add_f32_e32 v50, 1.0, v50
	v_add_f32_e32 v51, 1.0, v51
	v_rcp_f32_e32 v50, v50
	v_rcp_f32_e32 v51, v51
	s_nop 0
	v_pk_mul_f32 v[50:51], v[56:57], v[50:51]
	s_nop 0
	v_pk_mul_f32 v[56:57], v[50:51], v[52:53]
	v_cvt_pk_bf16_f32 v52, v54, v55
	v_mad_i64_i32 v[54:55], s[20:21], v68, s7, v[114:115]
	v_cvt_pk_bf16_f32 v50, v58, v59
	v_cvt_pk_bf16_f32 v51, v60, v61
	v_cvt_pk_bf16_f32 v53, v56, v57
	v_lshl_add_u64 v[54:55], v[54:55], 0, v[116:117]
	global_store_dwordx4 v[54:55], v[50:53], off
	s_nop 1
	v_mul_f32_e32 v50, 0xbfb8aa3b, v46
	v_mul_f32_e32 v51, 0xbfb8aa3b, v47
	v_exp_f32_e32 v50, v50
	v_exp_f32_e32 v51, v51
	v_add_f32_e32 v50, 1.0, v50
	v_add_f32_e32 v51, 1.0, v51
	v_rcp_f32_e32 v50, v50
	v_rcp_f32_e32 v51, v51
	s_nop 0
	v_pk_mul_f32 v[46:47], v[46:47], v[50:51]
	s_nop 0
	v_pk_mul_f32 v[42:43], v[46:47], v[42:43]
	v_mul_f32_e32 v46, 0xbfb8aa3b, v48
	v_mul_f32_e32 v47, 0xbfb8aa3b, v49
	v_exp_f32_e32 v46, v46
	v_exp_f32_e32 v47, v47
	v_add_f32_e32 v46, 1.0, v46
	v_add_f32_e32 v47, 1.0, v47
	v_rcp_f32_e32 v46, v46
	v_rcp_f32_e32 v47, v47
	s_nop 0
	v_pk_mul_f32 v[46:47], v[48:49], v[46:47]
	s_nop 0
	v_pk_mul_f32 v[44:45], v[46:47], v[44:45]
	v_mul_f32_e32 v46, 0xbfb8aa3b, v38
	v_mul_f32_e32 v47, 0xbfb8aa3b, v39
	v_exp_f32_e32 v46, v46
	v_exp_f32_e32 v47, v47
	v_add_f32_e32 v46, 1.0, v46
	v_add_f32_e32 v47, 1.0, v47
	v_rcp_f32_e32 v46, v46
	v_rcp_f32_e32 v47, v47
	s_nop 0
	v_pk_mul_f32 v[38:39], v[38:39], v[46:47]
	s_nop 0
	v_pk_mul_f32 v[38:39], v[38:39], v[34:35]
	v_mul_f32_e32 v34, 0xbfb8aa3b, v40
	v_mul_f32_e32 v35, 0xbfb8aa3b, v41
	v_exp_f32_e32 v34, v34
	v_exp_f32_e32 v35, v35
	v_add_f32_e32 v34, 1.0, v34
	v_add_f32_e32 v35, 1.0, v35
	v_rcp_f32_e32 v34, v34
	v_rcp_f32_e32 v35, v35
	s_nop 0
	v_pk_mul_f32 v[34:35], v[40:41], v[34:35]
	s_nop 0
	v_pk_mul_f32 v[40:41], v[34:35], v[36:37]
	v_cvt_pk_bf16_f32 v36, v38, v39
	v_add_u32_e32 v38, 0x90, v145
	v_mad_i64_i32 v[38:39], s[20:21], v38, s7, v[114:115]
	v_cvt_pk_bf16_f32 v34, v42, v43
	v_cvt_pk_bf16_f32 v35, v44, v45
	v_cvt_pk_bf16_f32 v37, v40, v41
	v_lshl_add_u64 v[38:39], v[38:39], 0, v[116:117]
	global_store_dwordx4 v[38:39], v[34:37], off
	s_nop 1
	v_mul_f32_e32 v34, 0xbfb8aa3b, v30
	v_mul_f32_e32 v35, 0xbfb8aa3b, v31
	v_exp_f32_e32 v34, v34
	v_exp_f32_e32 v35, v35
	v_add_f32_e32 v34, 1.0, v34
	v_add_f32_e32 v35, 1.0, v35
	v_rcp_f32_e32 v34, v34
	v_rcp_f32_e32 v35, v35
	s_nop 0
	v_pk_mul_f32 v[30:31], v[30:31], v[34:35]
	s_nop 0
	v_pk_mul_f32 v[26:27], v[30:31], v[26:27]
	v_mul_f32_e32 v30, 0xbfb8aa3b, v32
	v_mul_f32_e32 v31, 0xbfb8aa3b, v33
	v_exp_f32_e32 v30, v30
	v_exp_f32_e32 v31, v31
	v_add_f32_e32 v30, 1.0, v30
	v_add_f32_e32 v31, 1.0, v31
	v_rcp_f32_e32 v30, v30
	v_rcp_f32_e32 v31, v31
	s_nop 0
	v_pk_mul_f32 v[30:31], v[32:33], v[30:31]
	s_nop 0
	v_pk_mul_f32 v[28:29], v[30:31], v[28:29]
	v_mul_f32_e32 v30, 0xbfb8aa3b, v22
	v_mul_f32_e32 v31, 0xbfb8aa3b, v23
	v_exp_f32_e32 v30, v30
	v_exp_f32_e32 v31, v31
	v_add_f32_e32 v30, 1.0, v30
	v_add_f32_e32 v31, 1.0, v31
	v_rcp_f32_e32 v30, v30
	v_rcp_f32_e32 v31, v31
	s_nop 0
	v_pk_mul_f32 v[22:23], v[22:23], v[30:31]
	s_nop 0
	v_pk_mul_f32 v[22:23], v[22:23], v[18:19]
	v_mul_f32_e32 v18, 0xbfb8aa3b, v24
	v_mul_f32_e32 v19, 0xbfb8aa3b, v25
	v_exp_f32_e32 v18, v18
	v_exp_f32_e32 v19, v19
	v_add_f32_e32 v18, 1.0, v18
	v_add_f32_e32 v19, 1.0, v19
	v_rcp_f32_e32 v18, v18
	v_rcp_f32_e32 v19, v19
	s_nop 0
	v_pk_mul_f32 v[18:19], v[24:25], v[18:19]
	s_nop 0
	v_pk_mul_f32 v[24:25], v[18:19], v[20:21]
	v_cvt_pk_bf16_f32 v20, v22, v23
	v_add_u32_e32 v22, 0xa0, v145
	v_mad_i64_i32 v[22:23], s[20:21], v22, s7, v[114:115]
	v_cvt_pk_bf16_f32 v18, v26, v27
	v_cvt_pk_bf16_f32 v19, v28, v29
	v_cvt_pk_bf16_f32 v21, v24, v25
	v_lshl_add_u64 v[22:23], v[22:23], 0, v[116:117]
	global_store_dwordx4 v[22:23], v[18:21], off
	s_nop 1
	v_mul_f32_e32 v18, 0xbfb8aa3b, v14
	v_mul_f32_e32 v19, 0xbfb8aa3b, v15
	v_exp_f32_e32 v18, v18
	v_exp_f32_e32 v19, v19
	v_add_f32_e32 v18, 1.0, v18
	v_add_f32_e32 v19, 1.0, v19
	v_rcp_f32_e32 v18, v18
	v_rcp_f32_e32 v19, v19
	s_nop 0
	v_pk_mul_f32 v[14:15], v[14:15], v[18:19]
	s_nop 0
	v_pk_mul_f32 v[10:11], v[14:15], v[10:11]
	v_mul_f32_e32 v14, 0xbfb8aa3b, v16
	v_mul_f32_e32 v15, 0xbfb8aa3b, v17
	v_exp_f32_e32 v14, v14
	v_exp_f32_e32 v15, v15
	v_add_f32_e32 v14, 1.0, v14
	v_add_f32_e32 v15, 1.0, v15
	v_rcp_f32_e32 v14, v14
	v_rcp_f32_e32 v15, v15
	s_nop 0
	v_pk_mul_f32 v[14:15], v[16:17], v[14:15]
	s_nop 0
	v_pk_mul_f32 v[12:13], v[14:15], v[12:13]
	v_mul_f32_e32 v14, 0xbfb8aa3b, v6
	v_mul_f32_e32 v15, 0xbfb8aa3b, v7
	v_exp_f32_e32 v14, v14
	v_exp_f32_e32 v15, v15
	v_add_f32_e32 v14, 1.0, v14
	v_add_f32_e32 v15, 1.0, v15
	v_rcp_f32_e32 v14, v14
	v_rcp_f32_e32 v15, v15
	s_nop 0
	v_pk_mul_f32 v[6:7], v[6:7], v[14:15]
	s_nop 0
	v_pk_mul_f32 v[6:7], v[6:7], v[2:3]
	v_mul_f32_e32 v2, 0xbfb8aa3b, v8
	v_mul_f32_e32 v3, 0xbfb8aa3b, v9
	v_exp_f32_e32 v2, v2
	v_exp_f32_e32 v3, v3
	v_add_f32_e32 v2, 1.0, v2
	v_add_f32_e32 v3, 1.0, v3
	v_rcp_f32_e32 v2, v2
	v_rcp_f32_e32 v3, v3
	s_nop 0
	v_pk_mul_f32 v[2:3], v[8:9], v[2:3]
	s_nop 0
	v_pk_mul_f32 v[8:9], v[2:3], v[4:5]
	v_cvt_pk_bf16_f32 v4, v6, v7
	v_add_u32_e32 v6, 0xb0, v145
	v_mad_i64_i32 v[6:7], s[20:21], v6, s7, v[114:115]
	v_cvt_pk_bf16_f32 v2, v10, v11
	v_cvt_pk_bf16_f32 v3, v12, v13
	v_cvt_pk_bf16_f32 v5, v8, v9
	v_lshl_add_u64 v[6:7], v[6:7], 0, v[116:117]
	s_mov_b64 s[20:21], s[12:13]
	global_store_dwordx4 v[6:7], v[2:5], off
	s_cbranch_vccz .LBB0_294
	s_waitcnt vmcnt(0)
	s_cmpk_gt_u32 s28, 0xff
	s_cbranch_scc1 .LBB0_301
	s_barrier

.LBB0_374:
	s_add_u32 s16, s14, 0x100
	s_addc_u32 s17, s15, 0
	s_add_i32 s49, 0, 0x10000
	v_add_u32_e32 v154, s49, v164
	ds_read_b128 v[142:145], v154
	ds_read_b128 v[146:149], v154 offset:1024
	ds_read_b128 v[150:153], v154 offset:2048
	ds_read_b128 v[154:157], v154 offset:3072
	s_cmp_eq_u32 s48, 40
	s_cselect_b32 s21, s7, s17
	s_cselect_b32 s20, s6, s16
	s_cselect_b32 s19, s9, s47
	s_cselect_b32 s18, s8, s46
	v_lshl_add_u64 v[162:163], s[14:15], 0, v[138:139]
	s_add_i32 m0, s35, 0xc000
	ds_read_b128 v[158:161], v166
	ds_read_b128 v[168:171], v166 offset:1024
	ds_read_b128 v[172:175], v166 offset:2048
	ds_read_b128 v[190:193], v166 offset:3072
	ds_read_b128 v[194:197], v166 offset:4096
	ds_read_b128 v[198:201], v166 offset:5120
	ds_read_b128 v[202:205], v166 offset:6144
	ds_read_b128 v[206:209], v166 offset:7168
	global_load_lds_dwordx4 v[162:163], off
	v_lshl_add_u64 v[162:163], s[14:15], 0, v[140:141]
	s_add_i32 m0, s35, 0xe000
	s_nop 0
	global_load_lds_dwordx4 v[162:163], off
	s_waitcnt lgkmcnt(8)
	s_barrier
	s_waitcnt lgkmcnt(0)
	s_waitcnt lgkmcnt(0)
	v_mfma_f32_16x16x32_bf16 v[126:129], v[142:145], v[158:161], v[126:129]
	v_mfma_f32_16x16x32_bf16 v[122:125], v[150:153], v[158:161], v[122:125]
	v_mfma_f32_16x16x32_bf16 v[110:113], v[142:145], v[172:175], v[110:113]
	v_mfma_f32_16x16x32_bf16 v[106:109], v[150:153], v[172:175], v[106:109]
	v_mfma_f32_16x16x32_bf16 v[94:97], v[142:145], v[194:197], v[94:97]
	v_mfma_f32_16x16x32_bf16 v[90:93], v[150:153], v[194:197], v[90:93]
	v_mfma_f32_16x16x32_bf16 v[78:81], v[142:145], v[202:205], v[78:81]
	v_mfma_f32_16x16x32_bf16 v[74:77], v[150:153], v[202:205], v[74:77]
	v_mfma_f32_16x16x32_bf16 v[126:129], v[146:149], v[168:171], v[126:129]
	v_mfma_f32_16x16x32_bf16 v[122:125], v[154:157], v[168:171], v[122:125]
	v_mfma_f32_16x16x32_bf16 v[110:113], v[146:149], v[190:193], v[110:113]
	v_mfma_f32_16x16x32_bf16 v[106:109], v[154:157], v[190:193], v[106:109]
	v_mfma_f32_16x16x32_bf16 v[94:97], v[146:149], v[198:201], v[94:97]
	v_mfma_f32_16x16x32_bf16 v[90:93], v[154:157], v[198:201], v[90:93]
	v_mfma_f32_16x16x32_bf16 v[78:81], v[146:149], v[206:209], v[78:81]
	v_mfma_f32_16x16x32_bf16 v[74:77], v[154:157], v[206:209], v[74:77]
	s_barrier
	s_add_i32 s50, 0, 0x14000
	v_add_u32_e32 v162, s50, v164
	s_add_i32 s14, s49, s34
	ds_read_b128 v[210:213], v162
	ds_read_b128 v[214:217], v162 offset:1024
	ds_read_b128 v[218:221], v162 offset:2048
	ds_read_b128 v[222:225], v162 offset:3072
	s_add_u32 s64, s18, 0x80
	s_addc_u32 s65, s19, 0
	s_mov_b32 m0, s14
	s_nop 0
	global_load_lds_dwordx4 v132, s[18:19]
	s_add_i32 m0, s14, 0x2000
	s_nop 0
	global_load_lds_dwordx4 v136, s[18:19]
	s_barrier
	s_waitcnt lgkmcnt(0)
	s_waitcnt lgkmcnt(0)
	v_mfma_f32_16x16x32_bf16 v[118:121], v[210:213], v[158:161], v[118:121]
	v_mfma_f32_16x16x32_bf16 v[114:117], v[218:221], v[158:161], v[114:117]
	v_mfma_f32_16x16x32_bf16 v[102:105], v[210:213], v[172:175], v[102:105]
	v_mfma_f32_16x16x32_bf16 v[98:101], v[218:221], v[172:175], v[98:101]
	v_mfma_f32_16x16x32_bf16 v[86:89], v[210:213], v[194:197], v[86:89]
	v_mfma_f32_16x16x32_bf16 v[82:85], v[218:221], v[194:197], v[82:85]
	v_mfma_f32_16x16x32_bf16 v[70:73], v[210:213], v[202:205], v[70:73]
	v_mfma_f32_16x16x32_bf16 v[66:69], v[218:221], v[202:205], v[66:69]
	v_mfma_f32_16x16x32_bf16 v[118:121], v[214:217], v[168:171], v[118:121]
	v_mfma_f32_16x16x32_bf16 v[114:117], v[222:225], v[168:171], v[114:117]
	v_mfma_f32_16x16x32_bf16 v[102:105], v[214:217], v[190:193], v[102:105]
	v_mfma_f32_16x16x32_bf16 v[98:101], v[222:225], v[190:193], v[98:101]
	v_mfma_f32_16x16x32_bf16 v[86:89], v[214:217], v[198:201], v[86:89]
	v_mfma_f32_16x16x32_bf16 v[82:85], v[222:225], v[198:201], v[82:85]
	v_mfma_f32_16x16x32_bf16 v[70:73], v[214:217], v[206:209], v[70:73]
	v_mfma_f32_16x16x32_bf16 v[66:69], v[222:225], v[206:209], v[66:69]
	s_barrier
	s_mov_b32 m0, s35
	s_add_u32 s62, s20, 0x80
	s_addc_u32 s63, s21, 0
	ds_read_b128 v[158:161], v166 offset:16384
	ds_read_b128 v[168:171], v166 offset:17408
	ds_read_b128 v[172:175], v166 offset:18432
	ds_read_b128 v[190:193], v166 offset:19456
	ds_read_b128 v[194:197], v166 offset:20480
	ds_read_b128 v[198:201], v166 offset:21504
	ds_read_b128 v[202:205], v166 offset:22528
	ds_read_b128 v[206:209], v166 offset:23552
	global_load_lds_dwordx4 v130, s[20:21]
	s_mov_b32 m0, s36
	s_nop 0
	global_load_lds_dwordx4 v134, s[20:21]
	s_barrier
	s_waitcnt lgkmcnt(0)
	s_waitcnt lgkmcnt(0)
	v_mfma_f32_16x16x32_bf16 v[62:65], v[142:145], v[158:161], v[62:65]
	v_mfma_f32_16x16x32_bf16 v[58:61], v[150:153], v[158:161], v[58:61]
	v_mfma_f32_16x16x32_bf16 v[46:49], v[142:145], v[172:175], v[46:49]
	v_mfma_f32_16x16x32_bf16 v[42:45], v[150:153], v[172:175], v[42:45]
	v_mfma_f32_16x16x32_bf16 v[30:33], v[142:145], v[194:197], v[30:33]
	v_mfma_f32_16x16x32_bf16 v[26:29], v[150:153], v[194:197], v[26:29]
	v_mfma_f32_16x16x32_bf16 v[14:17], v[142:145], v[202:205], v[14:17]
	v_mfma_f32_16x16x32_bf16 v[10:13], v[150:153], v[202:205], v[10:13]
	v_mfma_f32_16x16x32_bf16 v[62:65], v[146:149], v[168:171], v[62:65]
	v_mfma_f32_16x16x32_bf16 v[58:61], v[154:157], v[168:171], v[58:61]
	v_mfma_f32_16x16x32_bf16 v[46:49], v[146:149], v[190:193], v[46:49]
	v_mfma_f32_16x16x32_bf16 v[42:45], v[154:157], v[190:193], v[42:45]
	v_mfma_f32_16x16x32_bf16 v[30:33], v[146:149], v[198:201], v[30:33]
	v_mfma_f32_16x16x32_bf16 v[26:29], v[154:157], v[198:201], v[26:29]
	v_mfma_f32_16x16x32_bf16 v[14:17], v[146:149], v[206:209], v[14:17]
	v_mfma_f32_16x16x32_bf16 v[10:13], v[154:157], v[206:209], v[10:13]
	s_barrier
	s_add_u32 s14, s18, 0xb0000
	s_addc_u32 s15, s19, 0
	s_add_i32 s49, s50, s34
	s_mov_b32 m0, s49
	s_nop 0
	global_load_lds_dwordx4 v132, s[14:15]
	s_add_i32 m0, s49, 0x2000
	s_nop 0
	global_load_lds_dwordx4 v136, s[14:15]
	s_waitcnt vmcnt(6)
	s_barrier
	v_mfma_f32_16x16x32_bf16 v[54:57], v[210:213], v[158:161], v[54:57]
	v_mfma_f32_16x16x32_bf16 v[50:53], v[218:221], v[158:161], v[50:53]
	v_mfma_f32_16x16x32_bf16 v[38:41], v[210:213], v[172:175], v[38:41]
	v_mfma_f32_16x16x32_bf16 v[34:37], v[218:221], v[172:175], v[34:37]
	v_mfma_f32_16x16x32_bf16 v[22:25], v[210:213], v[194:197], v[22:25]
	v_mfma_f32_16x16x32_bf16 v[18:21], v[218:221], v[194:197], v[18:21]
	v_mfma_f32_16x16x32_bf16 v[6:9], v[210:213], v[202:205], v[6:9]
	v_mfma_f32_16x16x32_bf16 v[2:5], v[218:221], v[202:205], v[2:5]
	v_mfma_f32_16x16x32_bf16 v[54:57], v[214:217], v[168:171], v[54:57]
	v_mfma_f32_16x16x32_bf16 v[50:53], v[222:225], v[168:171], v[50:53]
	v_mfma_f32_16x16x32_bf16 v[38:41], v[214:217], v[190:193], v[38:41]
	v_mfma_f32_16x16x32_bf16 v[34:37], v[222:225], v[190:193], v[34:37]
	v_mfma_f32_16x16x32_bf16 v[22:25], v[214:217], v[198:201], v[22:25]
	v_mfma_f32_16x16x32_bf16 v[18:21], v[222:225], v[198:201], v[18:21]
	v_mfma_f32_16x16x32_bf16 v[6:9], v[214:217], v[206:209], v[6:9]
	v_mfma_f32_16x16x32_bf16 v[2:5], v[222:225], v[206:209], v[2:5]
	s_barrier
	s_add_i32 s49, 0, 0x18000
	v_add_u32_e32 v154, s49, v164
	ds_read_b128 v[142:145], v154
	ds_read_b128 v[146:149], v154 offset:1024
	ds_read_b128 v[150:153], v154 offset:2048
	ds_read_b128 v[154:157], v154 offset:3072
	s_add_u32 s14, s20, 0xb8000
	s_addc_u32 s15, s21, 0
	s_mov_b32 m0, s37
	ds_read_b128 v[158:161], v166 offset:32768
	ds_read_b128 v[168:171], v166 offset:33792
	ds_read_b128 v[172:175], v166 offset:34816
	ds_read_b128 v[190:193], v166 offset:35840
	ds_read_b128 v[194:197], v166 offset:36864
	ds_read_b128 v[198:201], v166 offset:37888
	ds_read_b128 v[202:205], v166 offset:38912
	ds_read_b128 v[206:209], v166 offset:39936
	global_load_lds_dwordx4 v130, s[14:15]
	s_mov_b32 m0, s38
	s_nop 0
	global_load_lds_dwordx4 v134, s[14:15]
	s_waitcnt lgkmcnt(8)
	s_barrier
	s_waitcnt lgkmcnt(0)
	s_waitcnt lgkmcnt(0)
	v_mfma_f32_16x16x32_bf16 v[126:129], v[142:145], v[158:161], v[126:129]
	v_mfma_f32_16x16x32_bf16 v[122:125], v[150:153], v[158:161], v[122:125]
	v_mfma_f32_16x16x32_bf16 v[110:113], v[142:145], v[172:175], v[110:113]
	v_mfma_f32_16x16x32_bf16 v[106:109], v[150:153], v[172:175], v[106:109]
	v_mfma_f32_16x16x32_bf16 v[94:97], v[142:145], v[194:197], v[94:97]
	v_mfma_f32_16x16x32_bf16 v[90:93], v[150:153], v[194:197], v[90:93]
	v_mfma_f32_16x16x32_bf16 v[78:81], v[142:145], v[202:205], v[78:81]
	v_mfma_f32_16x16x32_bf16 v[74:77], v[150:153], v[202:205], v[74:77]
	v_mfma_f32_16x16x32_bf16 v[126:129], v[146:149], v[168:171], v[126:129]
	v_mfma_f32_16x16x32_bf16 v[122:125], v[154:157], v[168:171], v[122:125]
	v_mfma_f32_16x16x32_bf16 v[110:113], v[146:149], v[190:193], v[110:113]
	v_mfma_f32_16x16x32_bf16 v[106:109], v[154:157], v[190:193], v[106:109]
	v_mfma_f32_16x16x32_bf16 v[94:97], v[146:149], v[198:201], v[94:97]
	v_mfma_f32_16x16x32_bf16 v[90:93], v[154:157], v[198:201], v[90:93]
	v_mfma_f32_16x16x32_bf16 v[78:81], v[146:149], v[206:209], v[78:81]
	v_mfma_f32_16x16x32_bf16 v[74:77], v[154:157], v[206:209], v[74:77]
	s_barrier
	s_add_i32 s20, 0, 0x1c000
	s_add_i32 s14, s49, s34
	v_add_u32_e32 v167, s20, v164
	s_mov_b32 m0, s14
	ds_read_b128 v[210:213], v167
	ds_read_b128 v[214:217], v167 offset:1024
	ds_read_b128 v[218:221], v167 offset:2048
	ds_read_b128 v[222:225], v167 offset:3072
	global_load_lds_dwordx4 v132, s[64:65]
	s_add_i32 m0, s14, 0x2000
	s_nop 0
	global_load_lds_dwordx4 v136, s[64:65]
	s_barrier
	s_waitcnt lgkmcnt(0)
	s_waitcnt lgkmcnt(0)
	v_mfma_f32_16x16x32_bf16 v[118:121], v[210:213], v[158:161], v[118:121]
	v_mfma_f32_16x16x32_bf16 v[114:117], v[218:221], v[158:161], v[114:117]
	v_mfma_f32_16x16x32_bf16 v[102:105], v[210:213], v[172:175], v[102:105]
	v_mfma_f32_16x16x32_bf16 v[98:101], v[218:221], v[172:175], v[98:101]
	v_mfma_f32_16x16x32_bf16 v[86:89], v[210:213], v[194:197], v[86:89]
	v_mfma_f32_16x16x32_bf16 v[82:85], v[218:221], v[194:197], v[82:85]
	v_mfma_f32_16x16x32_bf16 v[70:73], v[210:213], v[202:205], v[70:73]
	v_mfma_f32_16x16x32_bf16 v[66:69], v[218:221], v[202:205], v[66:69]
	v_mfma_f32_16x16x32_bf16 v[118:121], v[214:217], v[168:171], v[118:121]
	v_mfma_f32_16x16x32_bf16 v[114:117], v[222:225], v[168:171], v[114:117]
	v_mfma_f32_16x16x32_bf16 v[102:105], v[214:217], v[190:193], v[102:105]
	v_mfma_f32_16x16x32_bf16 v[98:101], v[222:225], v[190:193], v[98:101]
	v_mfma_f32_16x16x32_bf16 v[86:89], v[214:217], v[198:201], v[86:89]
	v_mfma_f32_16x16x32_bf16 v[82:85], v[222:225], v[198:201], v[82:85]
	v_mfma_f32_16x16x32_bf16 v[70:73], v[214:217], v[206:209], v[70:73]
	v_mfma_f32_16x16x32_bf16 v[66:69], v[222:225], v[206:209], v[66:69]
	s_barrier
	s_mov_b32 m0, s39
	ds_read_b128 v[158:161], v166 offset:49152
	ds_read_b128 v[168:171], v166 offset:50176
	ds_read_b128 v[172:175], v166 offset:51200
	ds_read_b128 v[190:193], v166 offset:52224
	ds_read_b128 v[194:197], v166 offset:53248
	ds_read_b128 v[198:201], v166 offset:54272
	ds_read_b128 v[202:205], v166 offset:55296
	ds_read_b128 v[206:209], v166 offset:56320
	global_load_lds_dwordx4 v130, s[62:63]
	s_mov_b32 m0, s40
	s_nop 0
	global_load_lds_dwordx4 v134, s[62:63]
	s_barrier
	s_waitcnt lgkmcnt(0)
	s_waitcnt lgkmcnt(0)
	v_mfma_f32_16x16x32_bf16 v[62:65], v[142:145], v[158:161], v[62:65]
	v_mfma_f32_16x16x32_bf16 v[58:61], v[150:153], v[158:161], v[58:61]
	v_mfma_f32_16x16x32_bf16 v[46:49], v[142:145], v[172:175], v[46:49]
	v_mfma_f32_16x16x32_bf16 v[42:45], v[150:153], v[172:175], v[42:45]
	v_mfma_f32_16x16x32_bf16 v[30:33], v[142:145], v[194:197], v[30:33]
	v_mfma_f32_16x16x32_bf16 v[26:29], v[150:153], v[194:197], v[26:29]
	v_mfma_f32_16x16x32_bf16 v[14:17], v[142:145], v[202:205], v[14:17]
	v_mfma_f32_16x16x32_bf16 v[10:13], v[150:153], v[202:205], v[10:13]
	v_mfma_f32_16x16x32_bf16 v[62:65], v[146:149], v[168:171], v[62:65]
	v_mfma_f32_16x16x32_bf16 v[58:61], v[154:157], v[168:171], v[58:61]
	v_mfma_f32_16x16x32_bf16 v[46:49], v[146:149], v[190:193], v[46:49]
	v_mfma_f32_16x16x32_bf16 v[42:45], v[154:157], v[190:193], v[42:45]
	v_mfma_f32_16x16x32_bf16 v[30:33], v[146:149], v[198:201], v[30:33]
	v_mfma_f32_16x16x32_bf16 v[26:29], v[154:157], v[198:201], v[26:29]
	v_mfma_f32_16x16x32_bf16 v[14:17], v[146:149], v[206:209], v[14:17]
	v_mfma_f32_16x16x32_bf16 v[10:13], v[154:157], v[206:209], v[10:13]
	s_barrier
	s_add_u32 s14, s18, 0xb0080
	s_addc_u32 s15, s19, 0
	s_add_i32 s18, s20, s34
	s_mov_b32 m0, s18
	s_nop 0
	global_load_lds_dwordx4 v132, s[14:15]
	s_add_i32 m0, s18, 0x2000
	s_nop 0
	global_load_lds_dwordx4 v136, s[14:15]
	s_waitcnt vmcnt(6)
	s_barrier
	v_mfma_f32_16x16x32_bf16 v[54:57], v[210:213], v[158:161], v[54:57]
	v_mfma_f32_16x16x32_bf16 v[50:53], v[218:221], v[158:161], v[50:53]
	v_mfma_f32_16x16x32_bf16 v[38:41], v[210:213], v[172:175], v[38:41]
	v_mfma_f32_16x16x32_bf16 v[34:37], v[218:221], v[172:175], v[34:37]
	v_mfma_f32_16x16x32_bf16 v[22:25], v[210:213], v[194:197], v[22:25]
	v_mfma_f32_16x16x32_bf16 v[18:21], v[218:221], v[194:197], v[18:21]
	v_mfma_f32_16x16x32_bf16 v[6:9], v[210:213], v[202:205], v[6:9]
	v_mfma_f32_16x16x32_bf16 v[2:5], v[218:221], v[202:205], v[2:5]
	v_mfma_f32_16x16x32_bf16 v[54:57], v[214:217], v[168:171], v[54:57]
	v_mfma_f32_16x16x32_bf16 v[50:53], v[222:225], v[168:171], v[50:53]
	v_mfma_f32_16x16x32_bf16 v[38:41], v[214:217], v[190:193], v[38:41]
	v_mfma_f32_16x16x32_bf16 v[34:37], v[222:225], v[190:193], v[34:37]
	v_mfma_f32_16x16x32_bf16 v[22:25], v[214:217], v[198:201], v[22:25]
	v_mfma_f32_16x16x32_bf16 v[18:21], v[222:225], v[198:201], v[18:21]
	v_mfma_f32_16x16x32_bf16 v[6:9], v[214:217], v[206:209], v[6:9]
	v_mfma_f32_16x16x32_bf16 v[2:5], v[222:225], v[206:209], v[2:5]
	s_barrier
	s_add_i32 s48, s48, 2
	s_add_u32 s46, s46, 0x100
	s_addc_u32 s47, s47, 0
	s_cmp_gt_u32 s48, 41
	s_mov_b64 s[14:15], s[16:17]
	s_cbranch_scc0 .LBB0_374
	s_ashr_i32 s14, s33, 5
	s_mul_hi_i32 s15, s14, 0x9000
	s_mul_i32 s14, s14, 0x9000
	v_lshl_or_b32 v158, s45, 8, v165
	s_add_u32 s14, s26, s14
	s_addc_u32 s15, s27, s15
	v_ashrrev_i32_e32 v159, 31, v158
	v_lshl_add_u64 v[160:161], v[158:159], 2, s[14:15]
	global_load_dwordx4 v[142:145], v[160:161], off offset:16
	global_load_dwordx4 v[146:149], v[160:161], off
	v_lshl_add_u32 v162, s33, 8, v1
	v_ashrrev_i32_e32 v163, 31, v162
	s_mov_b64 s[14:15], 0x80000
	s_and_b64 vcc, exec, s[4:5]
	s_mov_b32 s45, s43
	s_mov_b32 s33, s44
	s_mov_b64 s[16:17], s[8:9]
	s_waitcnt vmcnt(0)
	v_pk_add_f32 v[144:145], v[144:145], 1.0 op_sel_hi:[1,0]
	v_pk_add_f32 v[148:149], v[148:149], 1.0 op_sel_hi:[1,0]
	v_pk_add_f32 v[146:147], v[146:147], 1.0 op_sel_hi:[1,0]
	v_pk_add_f32 v[142:143], v[142:143], 1.0 op_sel_hi:[1,0]
	v_pk_mul_f32 v[152:153], v[148:149], 0.5 op_sel_hi:[1,0]
	v_pk_mul_f32 v[156:157], v[146:147], 0.5 op_sel_hi:[1,0]
	v_pk_mul_f32 v[150:151], v[144:145], 0.5 op_sel_hi:[1,0]
	v_pk_mul_f32 v[154:155], v[142:143], 0.5 op_sel_hi:[1,0]
	global_load_dwordx4 v[142:145], v[160:161], off offset:528
	global_load_dwordx4 v[146:149], v[160:161], off offset:512
	s_waitcnt vmcnt(0)
	v_pk_add_f32 v[144:145], v[144:145], 1.0 op_sel_hi:[1,0]
	v_pk_add_f32 v[148:149], v[148:149], 1.0 op_sel_hi:[1,0]
	v_pk_add_f32 v[160:161], v[146:147], 1.0 op_sel_hi:[1,0]
	v_pk_mul_f32 v[146:147], v[148:149], 0.5 op_sel_hi:[1,0]
	v_pk_mul_f32 v[148:149], v[160:161], 0.5 op_sel_hi:[1,0]
	v_pk_add_f32 v[160:161], v[142:143], 1.0 op_sel_hi:[1,0]
	v_pk_mul_f32 v[142:143], v[144:145], 0.5 op_sel_hi:[1,0]
	v_pk_mul_f32 v[144:145], v[160:161], 0.5 op_sel_hi:[1,0]
	v_lshlrev_b64 v[160:161], 12, v[162:163]
	v_lshl_add_u64 v[168:169], s[12:13], 0, v[160:161]
	v_lshlrev_b64 v[160:161], 1, v[158:159]
	v_lshl_add_u64 v[158:159], v[168:169], 0, v[160:161]
	global_load_dwordx4 v[168:171], v[158:159], off offset:2048
	s_waitcnt vmcnt(0)
	v_lshlrev_b32_e32 v172, 16, v168
	v_and_b32_e32 v173, 0xffff0000, v168
	v_lshlrev_b32_e32 v168, 16, v169
	v_and_b32_e32 v169, 0xffff0000, v169
	v_pk_fma_f32 v[128:129], v[128:129], v[152:153], v[168:169]
	v_lshlrev_b32_e32 v168, 16, v170
	v_and_b32_e32 v169, 0xffff0000, v170
	v_pk_fma_f32 v[168:169], v[122:123], v[154:155], v[168:169]
	v_lshlrev_b32_e32 v122, 16, v171
	v_and_b32_e32 v123, 0xffff0000, v171
	v_pk_fma_f32 v[126:127], v[126:127], v[156:157], v[172:173]
	v_pk_fma_f32 v[170:171], v[124:125], v[150:151], v[122:123]
	v_cvt_pk_bf16_f32 v122, v126, v127
	v_cvt_pk_bf16_f32 v123, v128, v129
	v_cvt_pk_bf16_f32 v124, v168, v169
	v_cvt_pk_bf16_f32 v125, v170, v171
	global_store_dwordx4 v[158:159], v[122:125], off offset:2048
	global_load_dwordx4 v[122:125], v[158:159], off offset:2304
	s_waitcnt vmcnt(0)
	v_lshlrev_b32_e32 v126, 16, v122
	v_and_b32_e32 v127, 0xffff0000, v122
	v_lshlrev_b32_e32 v122, 16, v123
	v_and_b32_e32 v123, 0xffff0000, v123
	v_pk_fma_f32 v[120:121], v[120:121], v[146:147], v[122:123]
	v_lshlrev_b32_e32 v122, 16, v124
	v_and_b32_e32 v123, 0xffff0000, v124
	v_pk_fma_f32 v[122:123], v[114:115], v[144:145], v[122:123]
	v_lshlrev_b32_e32 v114, 16, v125
	v_and_b32_e32 v115, 0xffff0000, v125
	v_pk_fma_f32 v[118:119], v[118:119], v[148:149], v[126:127]
	v_pk_fma_f32 v[124:125], v[116:117], v[142:143], v[114:115]
	v_cvt_pk_bf16_f32 v114, v118, v119
	v_cvt_pk_bf16_f32 v115, v120, v121
	v_cvt_pk_bf16_f32 v116, v122, v123
	v_cvt_pk_bf16_f32 v117, v124, v125
	global_store_dwordx4 v[158:159], v[114:117], off offset:2304
	s_nop 1
	v_or_b32_e32 v114, 16, v162
	v_ashrrev_i32_e32 v115, 31, v114
	v_lshlrev_b64 v[114:115], 12, v[114:115]
	v_lshl_add_u64 v[114:115], s[12:13], 0, v[114:115]
	v_lshl_add_u64 v[118:119], v[114:115], 0, v[160:161]
	global_load_dwordx4 v[114:117], v[118:119], off offset:2048
	s_waitcnt vmcnt(0)
	v_lshlrev_b32_e32 v120, 16, v114
	v_and_b32_e32 v121, 0xffff0000, v114
	v_lshlrev_b32_e32 v114, 16, v115
	v_and_b32_e32 v115, 0xffff0000, v115
	v_pk_fma_f32 v[112:113], v[112:113], v[152:153], v[114:115]
	v_lshlrev_b32_e32 v114, 16, v116
	v_and_b32_e32 v115, 0xffff0000, v116
	v_pk_fma_f32 v[114:115], v[106:107], v[154:155], v[114:115]
	v_lshlrev_b32_e32 v106, 16, v117
	v_and_b32_e32 v107, 0xffff0000, v117
	v_pk_fma_f32 v[110:111], v[110:111], v[156:157], v[120:121]
	v_pk_fma_f32 v[116:117], v[108:109], v[150:151], v[106:107]
	v_cvt_pk_bf16_f32 v106, v110, v111
	v_cvt_pk_bf16_f32 v107, v112, v113
	v_cvt_pk_bf16_f32 v108, v114, v115
	v_cvt_pk_bf16_f32 v109, v116, v117
	global_store_dwordx4 v[118:119], v[106:109], off offset:2048
	global_load_dwordx4 v[106:109], v[118:119], off offset:2304
	s_waitcnt vmcnt(0)
	v_lshlrev_b32_e32 v110, 16, v106
	v_and_b32_e32 v111, 0xffff0000, v106
	v_lshlrev_b32_e32 v106, 16, v107
	v_and_b32_e32 v107, 0xffff0000, v107
	v_pk_fma_f32 v[104:105], v[104:105], v[146:147], v[106:107]
	v_lshlrev_b32_e32 v106, 16, v108
	v_and_b32_e32 v107, 0xffff0000, v108
	v_pk_fma_f32 v[106:107], v[98:99], v[144:145], v[106:107]
	v_lshlrev_b32_e32 v98, 16, v109
	v_and_b32_e32 v99, 0xffff0000, v109
	v_pk_fma_f32 v[102:103], v[102:103], v[148:149], v[110:111]
	v_pk_fma_f32 v[108:109], v[100:101], v[142:143], v[98:99]
	v_cvt_pk_bf16_f32 v98, v102, v103
	v_cvt_pk_bf16_f32 v99, v104, v105
	v_cvt_pk_bf16_f32 v100, v106, v107
	v_cvt_pk_bf16_f32 v101, v108, v109
	global_store_dwordx4 v[118:119], v[98:101], off offset:2304
	s_nop 1
	v_or_b32_e32 v98, 32, v162
	v_ashrrev_i32_e32 v99, 31, v98
	v_lshlrev_b64 v[98:99], 12, v[98:99]
	v_lshl_add_u64 v[98:99], s[12:13], 0, v[98:99]
	v_lshl_add_u64 v[102:103], v[98:99], 0, v[160:161]
	global_load_dwordx4 v[98:101], v[102:103], off offset:2048
	s_waitcnt vmcnt(0)
	v_lshlrev_b32_e32 v104, 16, v98
	v_and_b32_e32 v105, 0xffff0000, v98
	v_lshlrev_b32_e32 v98, 16, v99
	v_and_b32_e32 v99, 0xffff0000, v99
	v_pk_fma_f32 v[96:97], v[96:97], v[152:153], v[98:99]
	v_lshlrev_b32_e32 v98, 16, v100
	v_and_b32_e32 v99, 0xffff0000, v100
	v_pk_fma_f32 v[98:99], v[90:91], v[154:155], v[98:99]
	v_lshlrev_b32_e32 v90, 16, v101
	v_and_b32_e32 v91, 0xffff0000, v101
	v_pk_fma_f32 v[94:95], v[94:95], v[156:157], v[104:105]
	v_pk_fma_f32 v[100:101], v[92:93], v[150:151], v[90:91]
	v_cvt_pk_bf16_f32 v90, v94, v95
	v_cvt_pk_bf16_f32 v91, v96, v97
	v_cvt_pk_bf16_f32 v92, v98, v99
	v_cvt_pk_bf16_f32 v93, v100, v101
	global_store_dwordx4 v[102:103], v[90:93], off offset:2048
	global_load_dwordx4 v[90:93], v[102:103], off offset:2304
	s_waitcnt vmcnt(0)
	v_lshlrev_b32_e32 v94, 16, v90
	v_and_b32_e32 v95, 0xffff0000, v90
	v_lshlrev_b32_e32 v90, 16, v91
	v_and_b32_e32 v91, 0xffff0000, v91
	v_pk_fma_f32 v[88:89], v[88:89], v[146:147], v[90:91]
	v_lshlrev_b32_e32 v90, 16, v92
	v_and_b32_e32 v91, 0xffff0000, v92
	v_pk_fma_f32 v[90:91], v[82:83], v[144:145], v[90:91]
	v_lshlrev_b32_e32 v82, 16, v93
	v_and_b32_e32 v83, 0xffff0000, v93
	v_pk_fma_f32 v[86:87], v[86:87], v[148:149], v[94:95]
	v_pk_fma_f32 v[92:93], v[84:85], v[142:143], v[82:83]
	v_cvt_pk_bf16_f32 v82, v86, v87
	v_cvt_pk_bf16_f32 v83, v88, v89
	v_cvt_pk_bf16_f32 v84, v90, v91
	v_cvt_pk_bf16_f32 v85, v92, v93
	global_store_dwordx4 v[102:103], v[82:85], off offset:2304
	s_nop 1
	v_or_b32_e32 v82, 48, v162
	v_ashrrev_i32_e32 v83, 31, v82
	v_lshlrev_b64 v[82:83], 12, v[82:83]
	v_lshl_add_u64 v[82:83], s[12:13], 0, v[82:83]
	v_lshl_add_u64 v[82:83], v[82:83], 0, v[160:161]
	global_load_dwordx4 v[84:87], v[82:83], off offset:2048
	s_waitcnt vmcnt(0)
	v_lshlrev_b32_e32 v88, 16, v84
	v_and_b32_e32 v89, 0xffff0000, v84
	v_lshlrev_b32_e32 v84, 16, v85
	v_and_b32_e32 v85, 0xffff0000, v85
	v_pk_fma_f32 v[80:81], v[80:81], v[152:153], v[84:85]
	v_lshlrev_b32_e32 v84, 16, v86
	v_and_b32_e32 v85, 0xffff0000, v86
	v_pk_fma_f32 v[84:85], v[74:75], v[154:155], v[84:85]
	v_lshlrev_b32_e32 v74, 16, v87
	v_and_b32_e32 v75, 0xffff0000, v87
	v_pk_fma_f32 v[78:79], v[78:79], v[156:157], v[88:89]
	v_pk_fma_f32 v[86:87], v[76:77], v[150:151], v[74:75]
	v_cvt_pk_bf16_f32 v74, v78, v79
	v_cvt_pk_bf16_f32 v75, v80, v81
	v_cvt_pk_bf16_f32 v76, v84, v85
	v_cvt_pk_bf16_f32 v77, v86, v87
	global_store_dwordx4 v[82:83], v[74:77], off offset:2048
	global_load_dwordx4 v[74:77], v[82:83], off offset:2304
	s_waitcnt vmcnt(0)
	v_lshlrev_b32_e32 v78, 16, v74
	v_and_b32_e32 v79, 0xffff0000, v74
	v_lshlrev_b32_e32 v74, 16, v75
	v_and_b32_e32 v75, 0xffff0000, v75
	v_pk_fma_f32 v[72:73], v[72:73], v[146:147], v[74:75]
	v_lshlrev_b32_e32 v74, 16, v76
	v_and_b32_e32 v75, 0xffff0000, v76
	v_pk_fma_f32 v[74:75], v[66:67], v[144:145], v[74:75]
	v_lshlrev_b32_e32 v66, 16, v77
	v_and_b32_e32 v67, 0xffff0000, v77
	v_pk_fma_f32 v[70:71], v[70:71], v[148:149], v[78:79]
	v_pk_fma_f32 v[76:77], v[68:69], v[142:143], v[66:67]
	v_cvt_pk_bf16_f32 v66, v70, v71
	v_cvt_pk_bf16_f32 v67, v72, v73
	v_cvt_pk_bf16_f32 v68, v74, v75
	v_cvt_pk_bf16_f32 v69, v76, v77
	v_lshl_add_u64 v[70:71], v[158:159], 0, s[14:15]
	global_store_dwordx4 v[82:83], v[66:69], off offset:2304
	global_load_dwordx4 v[66:69], v[70:71], off offset:2048
	s_mov_b64 s[14:15], 0x90000
	s_waitcnt vmcnt(0)
	v_lshlrev_b32_e32 v72, 16, v66
	v_and_b32_e32 v73, 0xffff0000, v66
	v_lshlrev_b32_e32 v66, 16, v67
	v_and_b32_e32 v67, 0xffff0000, v67
	v_pk_fma_f32 v[64:65], v[64:65], v[152:153], v[66:67]
	v_lshlrev_b32_e32 v66, 16, v68
	v_and_b32_e32 v67, 0xffff0000, v68
	v_pk_fma_f32 v[66:67], v[58:59], v[154:155], v[66:67]
	v_lshlrev_b32_e32 v58, 16, v69
	v_and_b32_e32 v59, 0xffff0000, v69
	v_pk_fma_f32 v[62:63], v[62:63], v[156:157], v[72:73]
	v_pk_fma_f32 v[68:69], v[60:61], v[150:151], v[58:59]
	v_cvt_pk_bf16_f32 v58, v62, v63
	v_cvt_pk_bf16_f32 v59, v64, v65
	v_cvt_pk_bf16_f32 v60, v66, v67
	v_cvt_pk_bf16_f32 v61, v68, v69
	global_store_dwordx4 v[70:71], v[58:61], off offset:2048
	global_load_dwordx4 v[58:61], v[70:71], off offset:2304
	s_waitcnt vmcnt(0)
	v_lshlrev_b32_e32 v62, 16, v58
	v_and_b32_e32 v63, 0xffff0000, v58
	v_lshlrev_b32_e32 v58, 16, v59
	v_and_b32_e32 v59, 0xffff0000, v59
	v_pk_fma_f32 v[56:57], v[56:57], v[146:147], v[58:59]
	v_lshlrev_b32_e32 v58, 16, v60
	v_and_b32_e32 v59, 0xffff0000, v60
	v_pk_fma_f32 v[58:59], v[50:51], v[144:145], v[58:59]
	v_lshlrev_b32_e32 v50, 16, v61
	v_and_b32_e32 v51, 0xffff0000, v61
	v_pk_fma_f32 v[54:55], v[54:55], v[148:149], v[62:63]
	v_pk_fma_f32 v[60:61], v[52:53], v[142:143], v[50:51]
	v_cvt_pk_bf16_f32 v50, v54, v55
	v_cvt_pk_bf16_f32 v51, v56, v57
	v_cvt_pk_bf16_f32 v52, v58, v59
	v_cvt_pk_bf16_f32 v53, v60, v61
	v_lshl_add_u64 v[54:55], v[158:159], 0, s[14:15]
	global_store_dwordx4 v[70:71], v[50:53], off offset:2304
	global_load_dwordx4 v[50:53], v[54:55], off offset:2048
	s_mov_b64 s[14:15], 0xa0000
	s_waitcnt vmcnt(0)
	v_lshlrev_b32_e32 v56, 16, v50
	v_and_b32_e32 v57, 0xffff0000, v50
	v_lshlrev_b32_e32 v50, 16, v51
	v_and_b32_e32 v51, 0xffff0000, v51
	v_pk_fma_f32 v[48:49], v[48:49], v[152:153], v[50:51]
	v_lshlrev_b32_e32 v50, 16, v52
	v_and_b32_e32 v51, 0xffff0000, v52
	v_pk_fma_f32 v[50:51], v[42:43], v[154:155], v[50:51]
	v_lshlrev_b32_e32 v42, 16, v53
	v_and_b32_e32 v43, 0xffff0000, v53
	v_pk_fma_f32 v[46:47], v[46:47], v[156:157], v[56:57]
	v_pk_fma_f32 v[52:53], v[44:45], v[150:151], v[42:43]
	v_cvt_pk_bf16_f32 v42, v46, v47
	v_cvt_pk_bf16_f32 v43, v48, v49
	v_cvt_pk_bf16_f32 v44, v50, v51
	v_cvt_pk_bf16_f32 v45, v52, v53
	global_store_dwordx4 v[54:55], v[42:45], off offset:2048
	global_load_dwordx4 v[42:45], v[54:55], off offset:2304
	s_waitcnt vmcnt(0)
	v_lshlrev_b32_e32 v46, 16, v42
	v_and_b32_e32 v47, 0xffff0000, v42
	v_lshlrev_b32_e32 v42, 16, v43
	v_and_b32_e32 v43, 0xffff0000, v43
	v_pk_fma_f32 v[40:41], v[40:41], v[146:147], v[42:43]
	v_lshlrev_b32_e32 v42, 16, v44
	v_and_b32_e32 v43, 0xffff0000, v44
	v_pk_fma_f32 v[42:43], v[34:35], v[144:145], v[42:43]
	v_lshlrev_b32_e32 v34, 16, v45
	v_and_b32_e32 v35, 0xffff0000, v45
	v_pk_fma_f32 v[38:39], v[38:39], v[148:149], v[46:47]
	v_pk_fma_f32 v[44:45], v[36:37], v[142:143], v[34:35]
	v_cvt_pk_bf16_f32 v34, v38, v39
	v_cvt_pk_bf16_f32 v35, v40, v41
	v_cvt_pk_bf16_f32 v36, v42, v43
	v_cvt_pk_bf16_f32 v37, v44, v45
	v_lshl_add_u64 v[38:39], v[158:159], 0, s[14:15]
	global_store_dwordx4 v[54:55], v[34:37], off offset:2304
	global_load_dwordx4 v[34:37], v[38:39], off offset:2048
	s_mov_b64 s[14:15], 0xb0000
	s_waitcnt vmcnt(0)
	v_lshlrev_b32_e32 v40, 16, v34
	v_and_b32_e32 v41, 0xffff0000, v34
	v_lshlrev_b32_e32 v34, 16, v35
	v_and_b32_e32 v35, 0xffff0000, v35
	v_pk_fma_f32 v[32:33], v[32:33], v[152:153], v[34:35]
	v_lshlrev_b32_e32 v34, 16, v36
	v_and_b32_e32 v35, 0xffff0000, v36
	v_pk_fma_f32 v[34:35], v[26:27], v[154:155], v[34:35]
	v_lshlrev_b32_e32 v26, 16, v37
	v_and_b32_e32 v27, 0xffff0000, v37
	v_pk_fma_f32 v[30:31], v[30:31], v[156:157], v[40:41]
	v_pk_fma_f32 v[36:37], v[28:29], v[150:151], v[26:27]
	v_cvt_pk_bf16_f32 v26, v30, v31
	v_cvt_pk_bf16_f32 v27, v32, v33
	v_cvt_pk_bf16_f32 v28, v34, v35
	v_cvt_pk_bf16_f32 v29, v36, v37
	global_store_dwordx4 v[38:39], v[26:29], off offset:2048
	global_load_dwordx4 v[26:29], v[38:39], off offset:2304
	s_waitcnt vmcnt(0)
	v_lshlrev_b32_e32 v30, 16, v26
	v_and_b32_e32 v31, 0xffff0000, v26
	v_lshlrev_b32_e32 v26, 16, v27
	v_and_b32_e32 v27, 0xffff0000, v27
	v_pk_fma_f32 v[24:25], v[24:25], v[146:147], v[26:27]
	v_lshlrev_b32_e32 v26, 16, v28
	v_and_b32_e32 v27, 0xffff0000, v28
	v_pk_fma_f32 v[26:27], v[18:19], v[144:145], v[26:27]
	v_lshlrev_b32_e32 v18, 16, v29
	v_and_b32_e32 v19, 0xffff0000, v29
	v_pk_fma_f32 v[22:23], v[22:23], v[148:149], v[30:31]
	v_pk_fma_f32 v[28:29], v[20:21], v[142:143], v[18:19]
	v_cvt_pk_bf16_f32 v18, v22, v23
	v_cvt_pk_bf16_f32 v19, v24, v25
	v_cvt_pk_bf16_f32 v20, v26, v27
	v_cvt_pk_bf16_f32 v21, v28, v29
	global_store_dwordx4 v[38:39], v[18:21], off offset:2304
	s_nop 1
	v_lshl_add_u64 v[18:19], v[158:159], 0, s[14:15]
	global_load_dwordx4 v[20:23], v[18:19], off offset:2048
	s_mov_b64 s[14:15], s[6:7]
	s_waitcnt vmcnt(0)
	v_lshlrev_b32_e32 v24, 16, v20
	v_and_b32_e32 v25, 0xffff0000, v20
	v_lshlrev_b32_e32 v20, 16, v21
	v_and_b32_e32 v21, 0xffff0000, v21
	v_pk_fma_f32 v[16:17], v[16:17], v[152:153], v[20:21]
	v_lshlrev_b32_e32 v20, 16, v22
	v_and_b32_e32 v21, 0xffff0000, v22
	v_pk_fma_f32 v[20:21], v[10:11], v[154:155], v[20:21]
	v_lshlrev_b32_e32 v10, 16, v23
	v_and_b32_e32 v11, 0xffff0000, v23
	v_pk_fma_f32 v[14:15], v[14:15], v[156:157], v[24:25]
	v_pk_fma_f32 v[22:23], v[12:13], v[150:151], v[10:11]
	v_cvt_pk_bf16_f32 v10, v14, v15
	v_cvt_pk_bf16_f32 v11, v16, v17
	v_cvt_pk_bf16_f32 v12, v20, v21
	v_cvt_pk_bf16_f32 v13, v22, v23
	global_store_dwordx4 v[18:19], v[10:13], off offset:2048
	global_load_dwordx4 v[10:13], v[18:19], off offset:2304
	s_waitcnt vmcnt(0)
	v_lshlrev_b32_e32 v14, 16, v10
	v_and_b32_e32 v15, 0xffff0000, v10
	v_lshlrev_b32_e32 v10, 16, v11
	v_and_b32_e32 v11, 0xffff0000, v11
	v_pk_fma_f32 v[8:9], v[8:9], v[146:147], v[10:11]
	v_lshlrev_b32_e32 v10, 16, v12
	v_and_b32_e32 v11, 0xffff0000, v12
	v_pk_fma_f32 v[10:11], v[2:3], v[144:145], v[10:11]
	v_lshlrev_b32_e32 v2, 16, v13
	v_and_b32_e32 v3, 0xffff0000, v13
	v_pk_fma_f32 v[6:7], v[6:7], v[148:149], v[14:15]
	v_pk_fma_f32 v[12:13], v[4:5], v[142:143], v[2:3]
	v_cvt_pk_bf16_f32 v2, v6, v7
	v_cvt_pk_bf16_f32 v3, v8, v9
	v_cvt_pk_bf16_f32 v4, v10, v11
	v_cvt_pk_bf16_f32 v5, v12, v13
	global_store_dwordx4 v[18:19], v[2:5], off offset:2304
	s_cbranch_vccz .LBB0_363
	s_waitcnt vmcnt(0)
	s_cmpk_gt_u32 s30, 0xff
	s_cbranch_scc1 .LBB0_378
	s_barrier

.LBB0_400:
	s_add_u32 s16, s14, 0x100
	s_addc_u32 s17, s15, 0
	s_add_i32 s49, 0, 0x10000
	v_add_u32_e32 v154, s49, v164
	ds_read_b128 v[142:145], v154
	ds_read_b128 v[146:149], v154 offset:1024
	ds_read_b128 v[150:153], v154 offset:2048
	ds_read_b128 v[154:157], v154 offset:3072
	s_cmp_eq_u32 s48, 40
	s_cselect_b32 s21, s7, s17
	s_cselect_b32 s20, s6, s16
	s_cselect_b32 s19, s9, s47
	s_cselect_b32 s18, s8, s46
	v_lshl_add_u64 v[162:163], s[14:15], 0, v[138:139]
	s_add_i32 m0, s34, 0xc000
	ds_read_b128 v[158:161], v166
	ds_read_b128 v[168:171], v166 offset:1024
	ds_read_b128 v[172:175], v166 offset:2048
	ds_read_b128 v[190:193], v166 offset:3072
	ds_read_b128 v[194:197], v166 offset:4096
	ds_read_b128 v[198:201], v166 offset:5120
	ds_read_b128 v[202:205], v166 offset:6144
	ds_read_b128 v[206:209], v166 offset:7168
	global_load_lds_dwordx4 v[162:163], off
	v_lshl_add_u64 v[162:163], s[14:15], 0, v[140:141]
	s_add_i32 m0, s34, 0xe000
	s_nop 0
	global_load_lds_dwordx4 v[162:163], off
	s_waitcnt lgkmcnt(8)
	s_barrier
	s_waitcnt lgkmcnt(0)
	s_waitcnt lgkmcnt(0)
	v_mfma_f32_16x16x32_bf16 v[126:129], v[142:145], v[158:161], v[126:129]
	v_mfma_f32_16x16x32_bf16 v[122:125], v[150:153], v[158:161], v[122:125]
	v_mfma_f32_16x16x32_bf16 v[110:113], v[142:145], v[172:175], v[110:113]
	v_mfma_f32_16x16x32_bf16 v[106:109], v[150:153], v[172:175], v[106:109]
	v_mfma_f32_16x16x32_bf16 v[94:97], v[142:145], v[194:197], v[94:97]
	v_mfma_f32_16x16x32_bf16 v[90:93], v[150:153], v[194:197], v[90:93]
	v_mfma_f32_16x16x32_bf16 v[78:81], v[142:145], v[202:205], v[78:81]
	v_mfma_f32_16x16x32_bf16 v[74:77], v[150:153], v[202:205], v[74:77]
	v_mfma_f32_16x16x32_bf16 v[126:129], v[146:149], v[168:171], v[126:129]
	v_mfma_f32_16x16x32_bf16 v[122:125], v[154:157], v[168:171], v[122:125]
	v_mfma_f32_16x16x32_bf16 v[110:113], v[146:149], v[190:193], v[110:113]
	v_mfma_f32_16x16x32_bf16 v[106:109], v[154:157], v[190:193], v[106:109]
	v_mfma_f32_16x16x32_bf16 v[94:97], v[146:149], v[198:201], v[94:97]
	v_mfma_f32_16x16x32_bf16 v[90:93], v[154:157], v[198:201], v[90:93]
	v_mfma_f32_16x16x32_bf16 v[78:81], v[146:149], v[206:209], v[78:81]
	v_mfma_f32_16x16x32_bf16 v[74:77], v[154:157], v[206:209], v[74:77]
	s_barrier
	s_add_i32 s50, 0, 0x14000
	v_add_u32_e32 v162, s50, v164
	s_add_i32 s14, s49, s33
	ds_read_b128 v[210:213], v162
	ds_read_b128 v[214:217], v162 offset:1024
	ds_read_b128 v[218:221], v162 offset:2048
	ds_read_b128 v[222:225], v162 offset:3072
	s_add_u32 s64, s18, 0x80
	s_addc_u32 s65, s19, 0
	s_mov_b32 m0, s14
	s_nop 0
	global_load_lds_dwordx4 v132, s[18:19]
	s_add_i32 m0, s14, 0x2000
	s_nop 0
	global_load_lds_dwordx4 v136, s[18:19]
	s_barrier
	s_waitcnt lgkmcnt(0)
	s_waitcnt lgkmcnt(0)
	v_mfma_f32_16x16x32_bf16 v[118:121], v[210:213], v[158:161], v[118:121]
	v_mfma_f32_16x16x32_bf16 v[114:117], v[218:221], v[158:161], v[114:117]
	v_mfma_f32_16x16x32_bf16 v[102:105], v[210:213], v[172:175], v[102:105]
	v_mfma_f32_16x16x32_bf16 v[98:101], v[218:221], v[172:175], v[98:101]
	v_mfma_f32_16x16x32_bf16 v[86:89], v[210:213], v[194:197], v[86:89]
	v_mfma_f32_16x16x32_bf16 v[82:85], v[218:221], v[194:197], v[82:85]
	v_mfma_f32_16x16x32_bf16 v[70:73], v[210:213], v[202:205], v[70:73]
	v_mfma_f32_16x16x32_bf16 v[66:69], v[218:221], v[202:205], v[66:69]
	v_mfma_f32_16x16x32_bf16 v[118:121], v[214:217], v[168:171], v[118:121]
	v_mfma_f32_16x16x32_bf16 v[114:117], v[222:225], v[168:171], v[114:117]
	v_mfma_f32_16x16x32_bf16 v[102:105], v[214:217], v[190:193], v[102:105]
	v_mfma_f32_16x16x32_bf16 v[98:101], v[222:225], v[190:193], v[98:101]
	v_mfma_f32_16x16x32_bf16 v[86:89], v[214:217], v[198:201], v[86:89]
	v_mfma_f32_16x16x32_bf16 v[82:85], v[222:225], v[198:201], v[82:85]
	v_mfma_f32_16x16x32_bf16 v[70:73], v[214:217], v[206:209], v[70:73]
	v_mfma_f32_16x16x32_bf16 v[66:69], v[222:225], v[206:209], v[66:69]
	s_barrier
	s_mov_b32 m0, s34
	s_add_u32 s62, s20, 0x80
	s_addc_u32 s63, s21, 0
	ds_read_b128 v[158:161], v166 offset:16384
	ds_read_b128 v[168:171], v166 offset:17408
	ds_read_b128 v[172:175], v166 offset:18432
	ds_read_b128 v[190:193], v166 offset:19456
	ds_read_b128 v[194:197], v166 offset:20480
	ds_read_b128 v[198:201], v166 offset:21504
	ds_read_b128 v[202:205], v166 offset:22528
	ds_read_b128 v[206:209], v166 offset:23552
	global_load_lds_dwordx4 v130, s[20:21]
	s_mov_b32 m0, s35
	s_nop 0
	global_load_lds_dwordx4 v134, s[20:21]
	s_barrier
	s_waitcnt lgkmcnt(0)
	s_waitcnt lgkmcnt(0)
	v_mfma_f32_16x16x32_bf16 v[62:65], v[142:145], v[158:161], v[62:65]
	v_mfma_f32_16x16x32_bf16 v[58:61], v[150:153], v[158:161], v[58:61]
	v_mfma_f32_16x16x32_bf16 v[46:49], v[142:145], v[172:175], v[46:49]
	v_mfma_f32_16x16x32_bf16 v[42:45], v[150:153], v[172:175], v[42:45]
	v_mfma_f32_16x16x32_bf16 v[30:33], v[142:145], v[194:197], v[30:33]
	v_mfma_f32_16x16x32_bf16 v[26:29], v[150:153], v[194:197], v[26:29]
	v_mfma_f32_16x16x32_bf16 v[14:17], v[142:145], v[202:205], v[14:17]
	v_mfma_f32_16x16x32_bf16 v[10:13], v[150:153], v[202:205], v[10:13]
	v_mfma_f32_16x16x32_bf16 v[62:65], v[146:149], v[168:171], v[62:65]
	v_mfma_f32_16x16x32_bf16 v[58:61], v[154:157], v[168:171], v[58:61]
	v_mfma_f32_16x16x32_bf16 v[46:49], v[146:149], v[190:193], v[46:49]
	v_mfma_f32_16x16x32_bf16 v[42:45], v[154:157], v[190:193], v[42:45]
	v_mfma_f32_16x16x32_bf16 v[30:33], v[146:149], v[198:201], v[30:33]
	v_mfma_f32_16x16x32_bf16 v[26:29], v[154:157], v[198:201], v[26:29]
	v_mfma_f32_16x16x32_bf16 v[14:17], v[146:149], v[206:209], v[14:17]
	v_mfma_f32_16x16x32_bf16 v[10:13], v[154:157], v[206:209], v[10:13]
	s_barrier
	s_add_u32 s14, s18, 0xb0000
	s_addc_u32 s15, s19, 0
	s_add_i32 s49, s50, s33
	s_mov_b32 m0, s49
	s_nop 0
	global_load_lds_dwordx4 v132, s[14:15]
	s_add_i32 m0, s49, 0x2000
	s_nop 0
	global_load_lds_dwordx4 v136, s[14:15]
	s_waitcnt vmcnt(6)
	s_barrier
	v_mfma_f32_16x16x32_bf16 v[54:57], v[210:213], v[158:161], v[54:57]
	v_mfma_f32_16x16x32_bf16 v[50:53], v[218:221], v[158:161], v[50:53]
	v_mfma_f32_16x16x32_bf16 v[38:41], v[210:213], v[172:175], v[38:41]
	v_mfma_f32_16x16x32_bf16 v[34:37], v[218:221], v[172:175], v[34:37]
	v_mfma_f32_16x16x32_bf16 v[22:25], v[210:213], v[194:197], v[22:25]
	v_mfma_f32_16x16x32_bf16 v[18:21], v[218:221], v[194:197], v[18:21]
	v_mfma_f32_16x16x32_bf16 v[6:9], v[210:213], v[202:205], v[6:9]
	v_mfma_f32_16x16x32_bf16 v[2:5], v[218:221], v[202:205], v[2:5]
	v_mfma_f32_16x16x32_bf16 v[54:57], v[214:217], v[168:171], v[54:57]
	v_mfma_f32_16x16x32_bf16 v[50:53], v[222:225], v[168:171], v[50:53]
	v_mfma_f32_16x16x32_bf16 v[38:41], v[214:217], v[190:193], v[38:41]
	v_mfma_f32_16x16x32_bf16 v[34:37], v[222:225], v[190:193], v[34:37]
	v_mfma_f32_16x16x32_bf16 v[22:25], v[214:217], v[198:201], v[22:25]
	v_mfma_f32_16x16x32_bf16 v[18:21], v[222:225], v[198:201], v[18:21]
	v_mfma_f32_16x16x32_bf16 v[6:9], v[214:217], v[206:209], v[6:9]
	v_mfma_f32_16x16x32_bf16 v[2:5], v[222:225], v[206:209], v[2:5]
	s_barrier
	s_add_i32 s49, 0, 0x18000
	v_add_u32_e32 v154, s49, v164
	ds_read_b128 v[142:145], v154
	ds_read_b128 v[146:149], v154 offset:1024
	ds_read_b128 v[150:153], v154 offset:2048
	ds_read_b128 v[154:157], v154 offset:3072
	s_add_u32 s14, s20, 0xb8000
	s_addc_u32 s15, s21, 0
	s_mov_b32 m0, s36
	ds_read_b128 v[158:161], v166 offset:32768
	ds_read_b128 v[168:171], v166 offset:33792
	ds_read_b128 v[172:175], v166 offset:34816
	ds_read_b128 v[190:193], v166 offset:35840
	ds_read_b128 v[194:197], v166 offset:36864
	ds_read_b128 v[198:201], v166 offset:37888
	ds_read_b128 v[202:205], v166 offset:38912
	ds_read_b128 v[206:209], v166 offset:39936
	global_load_lds_dwordx4 v130, s[14:15]
	s_mov_b32 m0, s37
	s_nop 0
	global_load_lds_dwordx4 v134, s[14:15]
	s_waitcnt lgkmcnt(8)
	s_barrier
	s_waitcnt lgkmcnt(0)
	s_waitcnt lgkmcnt(0)
	v_mfma_f32_16x16x32_bf16 v[126:129], v[142:145], v[158:161], v[126:129]
	v_mfma_f32_16x16x32_bf16 v[122:125], v[150:153], v[158:161], v[122:125]
	v_mfma_f32_16x16x32_bf16 v[110:113], v[142:145], v[172:175], v[110:113]
	v_mfma_f32_16x16x32_bf16 v[106:109], v[150:153], v[172:175], v[106:109]
	v_mfma_f32_16x16x32_bf16 v[94:97], v[142:145], v[194:197], v[94:97]
	v_mfma_f32_16x16x32_bf16 v[90:93], v[150:153], v[194:197], v[90:93]
	v_mfma_f32_16x16x32_bf16 v[78:81], v[142:145], v[202:205], v[78:81]
	v_mfma_f32_16x16x32_bf16 v[74:77], v[150:153], v[202:205], v[74:77]
	v_mfma_f32_16x16x32_bf16 v[126:129], v[146:149], v[168:171], v[126:129]
	v_mfma_f32_16x16x32_bf16 v[122:125], v[154:157], v[168:171], v[122:125]
	v_mfma_f32_16x16x32_bf16 v[110:113], v[146:149], v[190:193], v[110:113]
	v_mfma_f32_16x16x32_bf16 v[106:109], v[154:157], v[190:193], v[106:109]
	v_mfma_f32_16x16x32_bf16 v[94:97], v[146:149], v[198:201], v[94:97]
	v_mfma_f32_16x16x32_bf16 v[90:93], v[154:157], v[198:201], v[90:93]
	v_mfma_f32_16x16x32_bf16 v[78:81], v[146:149], v[206:209], v[78:81]
	v_mfma_f32_16x16x32_bf16 v[74:77], v[154:157], v[206:209], v[74:77]
	s_barrier
	s_add_i32 s20, 0, 0x1c000
	s_add_i32 s14, s49, s33
	v_add_u32_e32 v167, s20, v164
	s_mov_b32 m0, s14
	ds_read_b128 v[210:213], v167
	ds_read_b128 v[214:217], v167 offset:1024
	ds_read_b128 v[218:221], v167 offset:2048
	ds_read_b128 v[222:225], v167 offset:3072
	global_load_lds_dwordx4 v132, s[64:65]
	s_add_i32 m0, s14, 0x2000
	s_nop 0
	global_load_lds_dwordx4 v136, s[64:65]
	s_barrier
	s_waitcnt lgkmcnt(0)
	s_waitcnt lgkmcnt(0)
	v_mfma_f32_16x16x32_bf16 v[118:121], v[210:213], v[158:161], v[118:121]
	v_mfma_f32_16x16x32_bf16 v[114:117], v[218:221], v[158:161], v[114:117]
	v_mfma_f32_16x16x32_bf16 v[102:105], v[210:213], v[172:175], v[102:105]
	v_mfma_f32_16x16x32_bf16 v[98:101], v[218:221], v[172:175], v[98:101]
	v_mfma_f32_16x16x32_bf16 v[86:89], v[210:213], v[194:197], v[86:89]
	v_mfma_f32_16x16x32_bf16 v[82:85], v[218:221], v[194:197], v[82:85]
	v_mfma_f32_16x16x32_bf16 v[70:73], v[210:213], v[202:205], v[70:73]
	v_mfma_f32_16x16x32_bf16 v[66:69], v[218:221], v[202:205], v[66:69]
	v_mfma_f32_16x16x32_bf16 v[118:121], v[214:217], v[168:171], v[118:121]
	v_mfma_f32_16x16x32_bf16 v[114:117], v[222:225], v[168:171], v[114:117]
	v_mfma_f32_16x16x32_bf16 v[102:105], v[214:217], v[190:193], v[102:105]
	v_mfma_f32_16x16x32_bf16 v[98:101], v[222:225], v[190:193], v[98:101]
	v_mfma_f32_16x16x32_bf16 v[86:89], v[214:217], v[198:201], v[86:89]
	v_mfma_f32_16x16x32_bf16 v[82:85], v[222:225], v[198:201], v[82:85]
	v_mfma_f32_16x16x32_bf16 v[70:73], v[214:217], v[206:209], v[70:73]
	v_mfma_f32_16x16x32_bf16 v[66:69], v[222:225], v[206:209], v[66:69]
	s_barrier
	s_mov_b32 m0, s38
	ds_read_b128 v[158:161], v166 offset:49152
	ds_read_b128 v[168:171], v166 offset:50176
	ds_read_b128 v[172:175], v166 offset:51200
	ds_read_b128 v[190:193], v166 offset:52224
	ds_read_b128 v[194:197], v166 offset:53248
	ds_read_b128 v[198:201], v166 offset:54272
	ds_read_b128 v[202:205], v166 offset:55296
	ds_read_b128 v[206:209], v166 offset:56320
	global_load_lds_dwordx4 v130, s[62:63]
	s_mov_b32 m0, s39
	s_nop 0
	global_load_lds_dwordx4 v134, s[62:63]
	s_barrier
	s_waitcnt lgkmcnt(0)
	s_waitcnt lgkmcnt(0)
	v_mfma_f32_16x16x32_bf16 v[62:65], v[142:145], v[158:161], v[62:65]
	v_mfma_f32_16x16x32_bf16 v[58:61], v[150:153], v[158:161], v[58:61]
	v_mfma_f32_16x16x32_bf16 v[46:49], v[142:145], v[172:175], v[46:49]
	v_mfma_f32_16x16x32_bf16 v[42:45], v[150:153], v[172:175], v[42:45]
	v_mfma_f32_16x16x32_bf16 v[30:33], v[142:145], v[194:197], v[30:33]
	v_mfma_f32_16x16x32_bf16 v[26:29], v[150:153], v[194:197], v[26:29]
	v_mfma_f32_16x16x32_bf16 v[14:17], v[142:145], v[202:205], v[14:17]
	v_mfma_f32_16x16x32_bf16 v[10:13], v[150:153], v[202:205], v[10:13]
	v_mfma_f32_16x16x32_bf16 v[62:65], v[146:149], v[168:171], v[62:65]
	v_mfma_f32_16x16x32_bf16 v[58:61], v[154:157], v[168:171], v[58:61]
	v_mfma_f32_16x16x32_bf16 v[46:49], v[146:149], v[190:193], v[46:49]
	v_mfma_f32_16x16x32_bf16 v[42:45], v[154:157], v[190:193], v[42:45]
	v_mfma_f32_16x16x32_bf16 v[30:33], v[146:149], v[198:201], v[30:33]
	v_mfma_f32_16x16x32_bf16 v[26:29], v[154:157], v[198:201], v[26:29]
	v_mfma_f32_16x16x32_bf16 v[14:17], v[146:149], v[206:209], v[14:17]
	v_mfma_f32_16x16x32_bf16 v[10:13], v[154:157], v[206:209], v[10:13]
	s_barrier
	s_add_u32 s14, s18, 0xb0080
	s_addc_u32 s15, s19, 0
	s_add_i32 s18, s20, s33
	s_mov_b32 m0, s18
	s_nop 0
	global_load_lds_dwordx4 v132, s[14:15]
	s_add_i32 m0, s18, 0x2000
	s_nop 0
	global_load_lds_dwordx4 v136, s[14:15]
	s_waitcnt vmcnt(6)
	s_barrier
	v_mfma_f32_16x16x32_bf16 v[54:57], v[210:213], v[158:161], v[54:57]
	v_mfma_f32_16x16x32_bf16 v[50:53], v[218:221], v[158:161], v[50:53]
	v_mfma_f32_16x16x32_bf16 v[38:41], v[210:213], v[172:175], v[38:41]
	v_mfma_f32_16x16x32_bf16 v[34:37], v[218:221], v[172:175], v[34:37]
	v_mfma_f32_16x16x32_bf16 v[22:25], v[210:213], v[194:197], v[22:25]
	v_mfma_f32_16x16x32_bf16 v[18:21], v[218:221], v[194:197], v[18:21]
	v_mfma_f32_16x16x32_bf16 v[6:9], v[210:213], v[202:205], v[6:9]
	v_mfma_f32_16x16x32_bf16 v[2:5], v[218:221], v[202:205], v[2:5]
	v_mfma_f32_16x16x32_bf16 v[54:57], v[214:217], v[168:171], v[54:57]
	v_mfma_f32_16x16x32_bf16 v[50:53], v[222:225], v[168:171], v[50:53]
	v_mfma_f32_16x16x32_bf16 v[38:41], v[214:217], v[190:193], v[38:41]
	v_mfma_f32_16x16x32_bf16 v[34:37], v[222:225], v[190:193], v[34:37]
	v_mfma_f32_16x16x32_bf16 v[22:25], v[214:217], v[198:201], v[22:25]
	v_mfma_f32_16x16x32_bf16 v[18:21], v[222:225], v[198:201], v[18:21]
	v_mfma_f32_16x16x32_bf16 v[6:9], v[214:217], v[206:209], v[6:9]
	v_mfma_f32_16x16x32_bf16 v[2:5], v[222:225], v[206:209], v[2:5]
	s_barrier
	s_add_i32 s48, s48, 2
	s_add_u32 s46, s46, 0x100
	s_addc_u32 s47, s47, 0
	s_cmp_gt_u32 s48, 41
	s_mov_b64 s[14:15], s[16:17]
	s_cbranch_scc0 .LBB0_400
	s_ashr_i32 s14, s44, 5
	v_lshl_or_b32 v176, s45, 8, v165
	s_mul_hi_i32 s15, s14, 0x9000
	s_mul_i32 s14, s14, 0x9000
	s_add_u32 s14, s26, s14
	v_ashrrev_i32_e32 v177, 31, v176
	s_addc_u32 s15, s27, s15
	v_lshlrev_b64 v[158:159], 2, v[176:177]
	v_lshl_add_u64 v[160:161], s[14:15], 0, v[158:159]
	global_load_dwordx4 v[142:145], v[160:161], off offset:16
	global_load_dwordx4 v[146:149], v[160:161], off
	v_lshl_add_u32 v162, s44, 8, v1
	v_ashrrev_i32_e32 v163, 31, v162
	s_mov_b64 s[14:15], 0x80000
	s_and_b64 vcc, exec, s[4:5]
	s_mov_b32 s45, s42
	s_mov_b32 s44, s43
	s_mov_b64 s[16:17], s[8:9]
	s_waitcnt vmcnt(0)
	v_pk_add_f32 v[144:145], v[144:145], 1.0 op_sel_hi:[1,0]
	v_pk_add_f32 v[148:149], v[148:149], 1.0 op_sel_hi:[1,0]
	v_pk_add_f32 v[146:147], v[146:147], 1.0 op_sel_hi:[1,0]
	v_pk_add_f32 v[142:143], v[142:143], 1.0 op_sel_hi:[1,0]
	v_pk_mul_f32 v[150:151], v[148:149], 0.5 op_sel_hi:[1,0]
	v_pk_mul_f32 v[152:153], v[146:147], 0.5 op_sel_hi:[1,0]
	v_pk_mul_f32 v[154:155], v[144:145], 0.5 op_sel_hi:[1,0]
	v_pk_mul_f32 v[156:157], v[142:143], 0.5 op_sel_hi:[1,0]
	global_load_dwordx4 v[146:149], v[160:161], off offset:528
	global_load_dwordx4 v[142:145], v[160:161], off offset:512
	s_waitcnt vmcnt(0)
	v_pk_add_f32 v[148:149], v[148:149], 1.0 op_sel_hi:[1,0]
	v_pk_add_f32 v[144:145], v[144:145], 1.0 op_sel_hi:[1,0]
	v_pk_add_f32 v[160:161], v[142:143], 1.0 op_sel_hi:[1,0]
	v_pk_mul_f32 v[142:143], v[144:145], 0.5 op_sel_hi:[1,0]
	v_pk_mul_f32 v[144:145], v[160:161], 0.5 op_sel_hi:[1,0]
	v_pk_add_f32 v[160:161], v[146:147], 1.0 op_sel_hi:[1,0]
	v_pk_mul_f32 v[146:147], v[148:149], 0.5 op_sel_hi:[1,0]
	v_pk_mul_f32 v[148:149], v[160:161], 0.5 op_sel_hi:[1,0]
	v_lshlrev_b64 v[160:161], 12, v[162:163]
	v_lshl_add_u64 v[168:169], s[2:3], 0, v[160:161]
	v_lshl_add_u64 v[186:187], v[168:169], 0, v[158:159]
	global_load_dwordx4 v[168:171], v[186:187], off offset:16
	global_load_dwordx4 v[172:175], v[186:187], off
	s_waitcnt vmcnt(0)
	v_pk_fma_f32 v[122:123], v[122:123], v[156:157], v[168:169]
	v_pk_fma_f32 v[128:129], v[128:129], v[150:151], v[174:175]
	v_pk_fma_f32 v[126:127], v[126:127], v[152:153], v[172:173]
	v_pk_fma_f32 v[170:171], v[124:125], v[154:155], v[170:171]
	v_cvt_pk_bf16_f32 v124, v126, v127
	v_cvt_pk_bf16_f32 v125, v128, v129
	v_cvt_pk_bf16_f32 v126, v122, v123
	v_lshl_add_u64 v[128:129], s[12:13], 0, v[160:161]
	v_lshlrev_b64 v[122:123], 1, v[176:177]
	v_cvt_pk_bf16_f32 v127, v170, v171
	v_lshl_add_u64 v[128:129], v[128:129], 0, v[122:123]
	global_store_dwordx4 v[128:129], v[124:127], off offset:2048
	global_load_dwordx4 v[124:127], v[186:187], off offset:528
	s_nop 0
	global_load_dwordx4 v[168:171], v[186:187], off offset:512
	s_waitcnt vmcnt(0)
	v_pk_fma_f32 v[126:127], v[116:117], v[146:147], v[126:127]
	v_pk_fma_f32 v[120:121], v[120:121], v[142:143], v[170:171]
	v_pk_fma_f32 v[118:119], v[118:119], v[144:145], v[168:169]
	v_pk_fma_f32 v[116:117], v[114:115], v[148:149], v[124:125]
	v_cvt_pk_bf16_f32 v114, v118, v119
	v_cvt_pk_bf16_f32 v115, v120, v121
	v_cvt_pk_bf16_f32 v116, v116, v117
	v_cvt_pk_bf16_f32 v117, v126, v127
	global_store_dwordx4 v[128:129], v[114:117], off offset:2304
	s_nop 1
	v_or_b32_e32 v114, 16, v162
	v_ashrrev_i32_e32 v115, 31, v114
	v_lshlrev_b64 v[124:125], 12, v[114:115]
	v_lshl_add_u64 v[114:115], s[2:3], 0, v[124:125]
	v_lshl_add_u64 v[126:127], v[114:115], 0, v[158:159]
	global_load_dwordx4 v[114:117], v[126:127], off offset:16
	global_load_dwordx4 v[118:121], v[126:127], off
	s_waitcnt vmcnt(0)
	v_pk_fma_f32 v[116:117], v[108:109], v[154:155], v[116:117]
	v_pk_fma_f32 v[110:111], v[110:111], v[152:153], v[118:119]
	v_pk_fma_f32 v[112:113], v[112:113], v[150:151], v[120:121]
	v_pk_fma_f32 v[108:109], v[106:107], v[156:157], v[114:115]
	v_cvt_pk_bf16_f32 v106, v110, v111
	v_lshl_add_u64 v[110:111], s[12:13], 0, v[124:125]
	v_cvt_pk_bf16_f32 v107, v112, v113
	v_cvt_pk_bf16_f32 v108, v108, v109
	v_cvt_pk_bf16_f32 v109, v116, v117
	v_lshl_add_u64 v[114:115], v[110:111], 0, v[122:123]
	global_store_dwordx4 v[114:115], v[106:109], off offset:2048
	global_load_dwordx4 v[106:109], v[126:127], off offset:528
	s_nop 0
	global_load_dwordx4 v[110:113], v[126:127], off offset:512
	s_waitcnt vmcnt(0)
	v_pk_fma_f32 v[108:109], v[100:101], v[146:147], v[108:109]
	v_pk_fma_f32 v[104:105], v[104:105], v[142:143], v[112:113]
	v_pk_fma_f32 v[102:103], v[102:103], v[144:145], v[110:111]
	v_pk_fma_f32 v[100:101], v[98:99], v[148:149], v[106:107]
	v_cvt_pk_bf16_f32 v98, v102, v103
	v_cvt_pk_bf16_f32 v99, v104, v105
	v_cvt_pk_bf16_f32 v100, v100, v101
	v_cvt_pk_bf16_f32 v101, v108, v109
	global_store_dwordx4 v[114:115], v[98:101], off offset:2304
	s_nop 1
	v_or_b32_e32 v98, 32, v162
	v_ashrrev_i32_e32 v99, 31, v98
	v_lshlrev_b64 v[106:107], 12, v[98:99]
	v_lshl_add_u64 v[98:99], s[2:3], 0, v[106:107]
	v_lshl_add_u64 v[108:109], v[98:99], 0, v[158:159]
	global_load_dwordx4 v[98:101], v[108:109], off offset:16
	global_load_dwordx4 v[102:105], v[108:109], off
	s_waitcnt vmcnt(0)
	v_pk_fma_f32 v[100:101], v[92:93], v[154:155], v[100:101]
	v_pk_fma_f32 v[94:95], v[94:95], v[152:153], v[102:103]
	v_pk_fma_f32 v[96:97], v[96:97], v[150:151], v[104:105]
	v_pk_fma_f32 v[92:93], v[90:91], v[156:157], v[98:99]
	v_cvt_pk_bf16_f32 v90, v94, v95
	v_lshl_add_u64 v[94:95], s[12:13], 0, v[106:107]
	v_cvt_pk_bf16_f32 v91, v96, v97
	v_cvt_pk_bf16_f32 v92, v92, v93
	v_cvt_pk_bf16_f32 v93, v100, v101
	v_lshl_add_u64 v[98:99], v[94:95], 0, v[122:123]
	global_store_dwordx4 v[98:99], v[90:93], off offset:2048
	global_load_dwordx4 v[90:93], v[108:109], off offset:528
	s_nop 0
	global_load_dwordx4 v[94:97], v[108:109], off offset:512
	s_waitcnt vmcnt(0)
	v_pk_fma_f32 v[92:93], v[84:85], v[146:147], v[92:93]
	v_pk_fma_f32 v[88:89], v[88:89], v[142:143], v[96:97]
	v_pk_fma_f32 v[86:87], v[86:87], v[144:145], v[94:95]
	v_pk_fma_f32 v[84:85], v[82:83], v[148:149], v[90:91]
	v_cvt_pk_bf16_f32 v82, v86, v87
	v_cvt_pk_bf16_f32 v83, v88, v89
	v_cvt_pk_bf16_f32 v84, v84, v85
	v_cvt_pk_bf16_f32 v85, v92, v93
	global_store_dwordx4 v[98:99], v[82:85], off offset:2304
	s_nop 1
	v_or_b32_e32 v82, 48, v162
	v_ashrrev_i32_e32 v83, 31, v82
	v_lshlrev_b64 v[90:91], 12, v[82:83]
	v_lshl_add_u64 v[82:83], s[2:3], 0, v[90:91]
	v_lshl_add_u64 v[92:93], v[82:83], 0, v[158:159]
	global_load_dwordx4 v[82:85], v[92:93], off offset:16
	global_load_dwordx4 v[86:89], v[92:93], off
	s_waitcnt vmcnt(0)
	v_pk_fma_f32 v[84:85], v[76:77], v[154:155], v[84:85]
	v_pk_fma_f32 v[78:79], v[78:79], v[152:153], v[86:87]
	v_pk_fma_f32 v[80:81], v[80:81], v[150:151], v[88:89]
	v_pk_fma_f32 v[76:77], v[74:75], v[156:157], v[82:83]
	v_cvt_pk_bf16_f32 v74, v78, v79
	v_lshl_add_u64 v[78:79], s[12:13], 0, v[90:91]
	v_cvt_pk_bf16_f32 v75, v80, v81
	v_cvt_pk_bf16_f32 v76, v76, v77
	v_cvt_pk_bf16_f32 v77, v84, v85
	v_lshl_add_u64 v[82:83], v[78:79], 0, v[122:123]
	global_store_dwordx4 v[82:83], v[74:77], off offset:2048
	global_load_dwordx4 v[74:77], v[92:93], off offset:528
	s_nop 0
	global_load_dwordx4 v[78:81], v[92:93], off offset:512
	s_waitcnt vmcnt(0)
	v_pk_fma_f32 v[76:77], v[68:69], v[146:147], v[76:77]
	v_pk_fma_f32 v[72:73], v[72:73], v[142:143], v[80:81]
	v_pk_fma_f32 v[70:71], v[70:71], v[144:145], v[78:79]
	v_pk_fma_f32 v[68:69], v[66:67], v[148:149], v[74:75]
	v_cvt_pk_bf16_f32 v66, v70, v71
	v_cvt_pk_bf16_f32 v67, v72, v73
	v_cvt_pk_bf16_f32 v68, v68, v69
	v_cvt_pk_bf16_f32 v69, v76, v77
	v_lshl_add_u64 v[74:75], v[160:161], 0, s[14:15]
	global_store_dwordx4 v[82:83], v[66:69], off offset:2304
	s_mov_b64 s[14:15], 0x90000
	s_nop 0
	v_lshl_add_u64 v[66:67], s[2:3], 0, v[74:75]
	v_lshl_add_u64 v[76:77], v[66:67], 0, v[158:159]
	global_load_dwordx4 v[66:69], v[76:77], off offset:16
	global_load_dwordx4 v[70:73], v[76:77], off
	s_waitcnt vmcnt(0)
	v_pk_fma_f32 v[68:69], v[60:61], v[154:155], v[68:69]
	v_pk_fma_f32 v[62:63], v[62:63], v[152:153], v[70:71]
	v_pk_fma_f32 v[64:65], v[64:65], v[150:151], v[72:73]
	v_pk_fma_f32 v[60:61], v[58:59], v[156:157], v[66:67]
	v_cvt_pk_bf16_f32 v58, v62, v63
	v_lshl_add_u64 v[62:63], s[12:13], 0, v[74:75]
	v_cvt_pk_bf16_f32 v59, v64, v65
	v_cvt_pk_bf16_f32 v60, v60, v61
	v_cvt_pk_bf16_f32 v61, v68, v69
	v_lshl_add_u64 v[66:67], v[62:63], 0, v[122:123]
	global_store_dwordx4 v[66:67], v[58:61], off offset:2048
	global_load_dwordx4 v[58:61], v[76:77], off offset:528
	s_nop 0
	global_load_dwordx4 v[62:65], v[76:77], off offset:512
	s_waitcnt vmcnt(0)
	v_pk_fma_f32 v[60:61], v[52:53], v[146:147], v[60:61]
	v_pk_fma_f32 v[56:57], v[56:57], v[142:143], v[64:65]
	v_pk_fma_f32 v[54:55], v[54:55], v[144:145], v[62:63]
	v_pk_fma_f32 v[52:53], v[50:51], v[148:149], v[58:59]
	v_cvt_pk_bf16_f32 v50, v54, v55
	v_cvt_pk_bf16_f32 v51, v56, v57
	v_cvt_pk_bf16_f32 v52, v52, v53
	v_cvt_pk_bf16_f32 v53, v60, v61
	v_lshl_add_u64 v[58:59], v[160:161], 0, s[14:15]
	global_store_dwordx4 v[66:67], v[50:53], off offset:2304
	s_mov_b64 s[14:15], 0xa0000
	s_nop 0
	v_lshl_add_u64 v[50:51], s[2:3], 0, v[58:59]
	v_lshl_add_u64 v[60:61], v[50:51], 0, v[158:159]
	global_load_dwordx4 v[50:53], v[60:61], off offset:16
	global_load_dwordx4 v[54:57], v[60:61], off
	s_waitcnt vmcnt(0)
	v_pk_fma_f32 v[52:53], v[44:45], v[154:155], v[52:53]
	v_pk_fma_f32 v[46:47], v[46:47], v[152:153], v[54:55]
	v_pk_fma_f32 v[48:49], v[48:49], v[150:151], v[56:57]
	v_pk_fma_f32 v[44:45], v[42:43], v[156:157], v[50:51]
	v_cvt_pk_bf16_f32 v42, v46, v47
	v_lshl_add_u64 v[46:47], s[12:13], 0, v[58:59]
	v_cvt_pk_bf16_f32 v43, v48, v49
	v_cvt_pk_bf16_f32 v44, v44, v45
	v_cvt_pk_bf16_f32 v45, v52, v53
	v_lshl_add_u64 v[50:51], v[46:47], 0, v[122:123]
	global_store_dwordx4 v[50:51], v[42:45], off offset:2048
	global_load_dwordx4 v[42:45], v[60:61], off offset:528
	s_nop 0
	global_load_dwordx4 v[46:49], v[60:61], off offset:512
	s_waitcnt vmcnt(0)
	v_pk_fma_f32 v[44:45], v[36:37], v[146:147], v[44:45]
	v_pk_fma_f32 v[40:41], v[40:41], v[142:143], v[48:49]
	v_pk_fma_f32 v[38:39], v[38:39], v[144:145], v[46:47]
	v_pk_fma_f32 v[36:37], v[34:35], v[148:149], v[42:43]
	v_cvt_pk_bf16_f32 v34, v38, v39
	v_cvt_pk_bf16_f32 v35, v40, v41
	v_cvt_pk_bf16_f32 v36, v36, v37
	v_cvt_pk_bf16_f32 v37, v44, v45
	v_lshl_add_u64 v[42:43], v[160:161], 0, s[14:15]
	global_store_dwordx4 v[50:51], v[34:37], off offset:2304
	s_mov_b64 s[14:15], 0xb0000
	s_nop 0
	v_lshl_add_u64 v[34:35], s[2:3], 0, v[42:43]
	v_lshl_add_u64 v[44:45], v[34:35], 0, v[158:159]
	global_load_dwordx4 v[34:37], v[44:45], off offset:16
	global_load_dwordx4 v[38:41], v[44:45], off
	s_waitcnt vmcnt(0)
	v_pk_fma_f32 v[36:37], v[28:29], v[154:155], v[36:37]
	v_pk_fma_f32 v[30:31], v[30:31], v[152:153], v[38:39]
	v_pk_fma_f32 v[32:33], v[32:33], v[150:151], v[40:41]
	v_pk_fma_f32 v[28:29], v[26:27], v[156:157], v[34:35]
	v_cvt_pk_bf16_f32 v26, v30, v31
	v_lshl_add_u64 v[30:31], s[12:13], 0, v[42:43]
	v_cvt_pk_bf16_f32 v27, v32, v33
	v_cvt_pk_bf16_f32 v28, v28, v29
	v_cvt_pk_bf16_f32 v29, v36, v37
	v_lshl_add_u64 v[34:35], v[30:31], 0, v[122:123]
	global_store_dwordx4 v[34:35], v[26:29], off offset:2048
	global_load_dwordx4 v[26:29], v[44:45], off offset:528
	s_nop 0
	global_load_dwordx4 v[30:33], v[44:45], off offset:512
	s_waitcnt vmcnt(0)
	v_pk_fma_f32 v[28:29], v[20:21], v[146:147], v[28:29]
	v_pk_fma_f32 v[24:25], v[24:25], v[142:143], v[32:33]
	v_pk_fma_f32 v[22:23], v[22:23], v[144:145], v[30:31]
	v_pk_fma_f32 v[20:21], v[18:19], v[148:149], v[26:27]
	v_cvt_pk_bf16_f32 v18, v22, v23
	v_cvt_pk_bf16_f32 v19, v24, v25
	v_cvt_pk_bf16_f32 v20, v20, v21
	v_cvt_pk_bf16_f32 v21, v28, v29
	v_lshl_add_u64 v[26:27], v[160:161], 0, s[14:15]
	global_store_dwordx4 v[34:35], v[18:21], off offset:2304
	s_mov_b64 s[14:15], s[6:7]
	s_nop 0
	v_lshl_add_u64 v[18:19], s[2:3], 0, v[26:27]
	v_lshl_add_u64 v[28:29], v[18:19], 0, v[158:159]
	global_load_dwordx4 v[18:21], v[28:29], off offset:16
	global_load_dwordx4 v[22:25], v[28:29], off
	s_waitcnt vmcnt(0)
	v_pk_fma_f32 v[20:21], v[12:13], v[154:155], v[20:21]
	v_pk_fma_f32 v[14:15], v[14:15], v[152:153], v[22:23]
	v_pk_fma_f32 v[16:17], v[16:17], v[150:151], v[24:25]
	v_pk_fma_f32 v[12:13], v[10:11], v[156:157], v[18:19]
	v_cvt_pk_bf16_f32 v10, v14, v15
	v_lshl_add_u64 v[14:15], s[12:13], 0, v[26:27]
	v_cvt_pk_bf16_f32 v11, v16, v17
	v_cvt_pk_bf16_f32 v12, v12, v13
	v_cvt_pk_bf16_f32 v13, v20, v21
	v_lshl_add_u64 v[18:19], v[14:15], 0, v[122:123]
	global_store_dwordx4 v[18:19], v[10:13], off offset:2048
	global_load_dwordx4 v[10:13], v[28:29], off offset:528
	s_nop 0
	global_load_dwordx4 v[14:17], v[28:29], off offset:512
	s_waitcnt vmcnt(0)
	v_pk_fma_f32 v[12:13], v[4:5], v[146:147], v[12:13]
	v_pk_fma_f32 v[8:9], v[8:9], v[142:143], v[16:17]
	v_pk_fma_f32 v[6:7], v[6:7], v[144:145], v[14:15]
	v_pk_fma_f32 v[4:5], v[2:3], v[148:149], v[10:11]
	v_cvt_pk_bf16_f32 v2, v6, v7
	v_cvt_pk_bf16_f32 v3, v8, v9
	v_cvt_pk_bf16_f32 v4, v4, v5
	v_cvt_pk_bf16_f32 v5, v12, v13
	global_store_dwordx4 v[18:19], v[2:5], off offset:2304
	s_cbranch_vccz .LBB0_389
	s_waitcnt vmcnt(0)
	s_cmpk_gt_u32 s30, 0xff
	s_cbranch_scc1 .LBB0_404
	s_barrier

.LBB0_528:
	s_add_u32 s22, s20, 0xfffc0080
	s_addc_u32 s23, s21, -1
	s_add_i32 s55, 0, 0x10000
	v_add_u32_e32 v144, s55, v146
	ds_read_b128 v[150:153], v144
	ds_read_b128 v[154:157], v144 offset:1024
	ds_read_b128 v[158:161], v144 offset:2048
	ds_read_b128 v[162:165], v144 offset:3072
	s_cmp_eq_u32 s54, 12
	s_cselect_b32 s25, s11, s23
	s_cselect_b32 s24, s15, s22
	s_cselect_b32 s23, s13, s53
	s_cselect_b32 s22, s51, s52
	s_add_i32 m0, s41, 0xc000
	ds_read_b128 v[166:169], v148
	ds_read_b128 v[170:173], v148 offset:1024
	ds_read_b128 v[174:177], v148 offset:2048
	ds_read_b128 v[190:193], v148 offset:3072
	ds_read_b128 v[194:197], v148 offset:4096
	ds_read_b128 v[198:201], v148 offset:5120
	ds_read_b128 v[202:205], v148 offset:6144
	ds_read_b128 v[206:209], v148 offset:7168
	global_load_lds_dwordx4 v140, s[20:21]
	v_lshl_add_u64 v[144:145], s[20:21], 0, v[142:143]
	s_add_i32 m0, s41, 0xe000
	s_nop 0
	global_load_lds_dwordx4 v[144:145], off
	s_waitcnt lgkmcnt(8)
	s_barrier
	s_waitcnt lgkmcnt(0)
	s_waitcnt lgkmcnt(0)
	v_mfma_f32_16x16x32_bf16 v[86:89], v[150:153], v[166:169], v[86:89]
	v_mfma_f32_16x16x32_bf16 v[82:85], v[158:161], v[166:169], v[82:85]
	v_mfma_f32_16x16x32_bf16 v[78:81], v[150:153], v[174:177], v[78:81]
	v_mfma_f32_16x16x32_bf16 v[74:77], v[158:161], v[174:177], v[74:77]
	v_mfma_f32_16x16x32_bf16 v[62:65], v[150:153], v[194:197], v[62:65]
	v_mfma_f32_16x16x32_bf16 v[58:61], v[158:161], v[194:197], v[58:61]
	v_mfma_f32_16x16x32_bf16 v[54:57], v[150:153], v[202:205], v[54:57]
	v_mfma_f32_16x16x32_bf16 v[50:53], v[158:161], v[202:205], v[50:53]
	v_mfma_f32_16x16x32_bf16 v[86:89], v[154:157], v[170:173], v[86:89]
	v_mfma_f32_16x16x32_bf16 v[82:85], v[162:165], v[170:173], v[82:85]
	v_mfma_f32_16x16x32_bf16 v[78:81], v[154:157], v[190:193], v[78:81]
	v_mfma_f32_16x16x32_bf16 v[74:77], v[162:165], v[190:193], v[74:77]
	v_mfma_f32_16x16x32_bf16 v[62:65], v[154:157], v[198:201], v[62:65]
	v_mfma_f32_16x16x32_bf16 v[58:61], v[162:165], v[198:201], v[58:61]
	v_mfma_f32_16x16x32_bf16 v[54:57], v[154:157], v[206:209], v[54:57]
	v_mfma_f32_16x16x32_bf16 v[50:53], v[162:165], v[206:209], v[50:53]
	s_barrier
	s_add_i32 s58, 0, 0x14000
	v_add_u32_e32 v144, s58, v146
	s_add_i32 s55, s55, s35
	ds_read_b128 v[210:213], v144
	ds_read_b128 v[214:217], v144 offset:1024
	ds_read_b128 v[218:221], v144 offset:2048
	ds_read_b128 v[222:225], v144 offset:3072
	s_add_u32 s64, s22, 0x80
	s_addc_u32 s65, s23, 0
	s_mov_b32 m0, s55
	s_nop 0
	global_load_lds_dwordx4 v134, s[22:23]
	s_add_i32 m0, s55, 0x2000
	s_nop 0
	global_load_lds_dwordx4 v130, s[22:23]
	s_barrier
	s_waitcnt lgkmcnt(0)
	s_waitcnt lgkmcnt(0)
	v_mfma_f32_16x16x32_bf16 v[126:129], v[210:213], v[166:169], v[126:129]
	v_mfma_f32_16x16x32_bf16 v[122:125], v[218:221], v[166:169], v[122:125]
	v_mfma_f32_16x16x32_bf16 v[118:121], v[210:213], v[174:177], v[118:121]
	v_mfma_f32_16x16x32_bf16 v[114:117], v[218:221], v[174:177], v[114:117]
	v_mfma_f32_16x16x32_bf16 v[110:113], v[210:213], v[194:197], v[110:113]
	v_mfma_f32_16x16x32_bf16 v[106:109], v[218:221], v[194:197], v[106:109]
	v_mfma_f32_16x16x32_bf16 v[102:105], v[210:213], v[202:205], v[102:105]
	v_mfma_f32_16x16x32_bf16 v[98:101], v[218:221], v[202:205], v[98:101]
	v_mfma_f32_16x16x32_bf16 v[126:129], v[214:217], v[170:173], v[126:129]
	v_mfma_f32_16x16x32_bf16 v[122:125], v[222:225], v[170:173], v[122:125]
	v_mfma_f32_16x16x32_bf16 v[118:121], v[214:217], v[190:193], v[118:121]
	v_mfma_f32_16x16x32_bf16 v[114:117], v[222:225], v[190:193], v[114:117]
	v_mfma_f32_16x16x32_bf16 v[110:113], v[214:217], v[198:201], v[110:113]
	v_mfma_f32_16x16x32_bf16 v[106:109], v[222:225], v[198:201], v[106:109]
	v_mfma_f32_16x16x32_bf16 v[102:105], v[214:217], v[206:209], v[102:105]
	v_mfma_f32_16x16x32_bf16 v[98:101], v[222:225], v[206:209], v[98:101]
	s_barrier
	s_mov_b32 m0, s41
	s_add_u32 s62, s24, 0x80
	s_addc_u32 s63, s25, 0
	ds_read_b128 v[166:169], v148 offset:16384
	ds_read_b128 v[170:173], v148 offset:17408
	ds_read_b128 v[174:177], v148 offset:18432
	ds_read_b128 v[190:193], v148 offset:19456
	ds_read_b128 v[194:197], v148 offset:20480
	ds_read_b128 v[198:201], v148 offset:21504
	ds_read_b128 v[202:205], v148 offset:22528
	ds_read_b128 v[206:209], v148 offset:23552
	global_load_lds_dwordx4 v136, s[24:25]
	s_mov_b32 m0, s42
	s_nop 0
	global_load_lds_dwordx4 v132, s[24:25]
	s_barrier
	s_waitcnt lgkmcnt(0)
	s_waitcnt lgkmcnt(0)
	v_mfma_f32_16x16x32_bf16 v[34:37], v[150:153], v[166:169], v[34:37]
	v_mfma_f32_16x16x32_bf16 v[26:29], v[158:161], v[166:169], v[26:29]
	v_mfma_f32_16x16x32_bf16 v[22:25], v[150:153], v[174:177], v[22:25]
	v_mfma_f32_16x16x32_bf16 v[18:21], v[158:161], v[174:177], v[18:21]
	v_mfma_f32_16x16x32_bf16 v[14:17], v[150:153], v[194:197], v[14:17]
	v_mfma_f32_16x16x32_bf16 v[10:13], v[158:161], v[194:197], v[10:13]
	v_mfma_f32_16x16x32_bf16 v[6:9], v[150:153], v[202:205], v[6:9]
	v_mfma_f32_16x16x32_bf16 v[2:5], v[158:161], v[202:205], v[2:5]
	v_mfma_f32_16x16x32_bf16 v[34:37], v[154:157], v[170:173], v[34:37]
	v_mfma_f32_16x16x32_bf16 v[26:29], v[162:165], v[170:173], v[26:29]
	v_mfma_f32_16x16x32_bf16 v[22:25], v[154:157], v[190:193], v[22:25]
	v_mfma_f32_16x16x32_bf16 v[18:21], v[162:165], v[190:193], v[18:21]
	v_mfma_f32_16x16x32_bf16 v[14:17], v[154:157], v[198:201], v[14:17]
	v_mfma_f32_16x16x32_bf16 v[10:13], v[162:165], v[198:201], v[10:13]
	v_mfma_f32_16x16x32_bf16 v[6:9], v[154:157], v[206:209], v[6:9]
	v_mfma_f32_16x16x32_bf16 v[2:5], v[162:165], v[206:209], v[2:5]
	s_barrier
	s_add_u32 s56, s22, 0x40000
	s_addc_u32 s57, s23, 0
	s_add_i32 s55, s58, s35
	s_mov_b32 m0, s55
	s_nop 0
	global_load_lds_dwordx4 v134, s[56:57]
	s_add_i32 m0, s55, 0x2000
	s_nop 0
	global_load_lds_dwordx4 v130, s[56:57]
	s_waitcnt vmcnt(6)
	s_barrier
	v_mfma_f32_16x16x32_bf16 v[94:97], v[210:213], v[166:169], v[94:97]
	v_mfma_f32_16x16x32_bf16 v[90:93], v[218:221], v[166:169], v[90:93]
	v_mfma_f32_16x16x32_bf16 v[70:73], v[210:213], v[174:177], v[70:73]
	v_mfma_f32_16x16x32_bf16 v[66:69], v[218:221], v[174:177], v[66:69]
	v_mfma_f32_16x16x32_bf16 v[46:49], v[210:213], v[194:197], v[46:49]
	v_mfma_f32_16x16x32_bf16 v[42:45], v[218:221], v[194:197], v[42:45]
	v_mfma_f32_16x16x32_bf16 v[38:41], v[210:213], v[202:205], v[38:41]
	v_mfma_f32_16x16x32_bf16 v[30:33], v[218:221], v[202:205], v[30:33]
	v_mfma_f32_16x16x32_bf16 v[94:97], v[214:217], v[170:173], v[94:97]
	v_mfma_f32_16x16x32_bf16 v[90:93], v[222:225], v[170:173], v[90:93]
	v_mfma_f32_16x16x32_bf16 v[70:73], v[214:217], v[190:193], v[70:73]
	v_mfma_f32_16x16x32_bf16 v[66:69], v[222:225], v[190:193], v[66:69]
	v_mfma_f32_16x16x32_bf16 v[46:49], v[214:217], v[198:201], v[46:49]
	v_mfma_f32_16x16x32_bf16 v[42:45], v[222:225], v[198:201], v[42:45]
	v_mfma_f32_16x16x32_bf16 v[38:41], v[214:217], v[206:209], v[38:41]
	v_mfma_f32_16x16x32_bf16 v[30:33], v[222:225], v[206:209], v[30:33]
	s_barrier
	s_add_i32 s55, 0, 0x18000
	v_add_u32_e32 v149, s55, v146
	ds_read_b128 v[150:153], v149
	ds_read_b128 v[154:157], v149 offset:1024
	ds_read_b128 v[158:161], v149 offset:2048
	ds_read_b128 v[162:165], v149 offset:3072
	s_add_u32 s24, s24, 0x40000
	s_addc_u32 s25, s25, 0
	s_mov_b32 m0, s43
	ds_read_b128 v[166:169], v148 offset:32768
	ds_read_b128 v[170:173], v148 offset:33792
	ds_read_b128 v[174:177], v148 offset:34816
	ds_read_b128 v[190:193], v148 offset:35840
	ds_read_b128 v[194:197], v148 offset:36864
	ds_read_b128 v[198:201], v148 offset:37888
	ds_read_b128 v[202:205], v148 offset:38912
	ds_read_b128 v[206:209], v148 offset:39936
	global_load_lds_dwordx4 v136, s[24:25]
	s_mov_b32 m0, s44
	s_nop 0
	global_load_lds_dwordx4 v132, s[24:25]
	s_waitcnt lgkmcnt(8)
	s_barrier
	s_waitcnt lgkmcnt(0)
	s_waitcnt lgkmcnt(0)
	v_mfma_f32_16x16x32_bf16 v[86:89], v[150:153], v[166:169], v[86:89]
	v_mfma_f32_16x16x32_bf16 v[82:85], v[158:161], v[166:169], v[82:85]
	v_mfma_f32_16x16x32_bf16 v[78:81], v[150:153], v[174:177], v[78:81]
	v_mfma_f32_16x16x32_bf16 v[74:77], v[158:161], v[174:177], v[74:77]
	v_mfma_f32_16x16x32_bf16 v[62:65], v[150:153], v[194:197], v[62:65]
	v_mfma_f32_16x16x32_bf16 v[58:61], v[158:161], v[194:197], v[58:61]
	v_mfma_f32_16x16x32_bf16 v[54:57], v[150:153], v[202:205], v[54:57]
	v_mfma_f32_16x16x32_bf16 v[50:53], v[158:161], v[202:205], v[50:53]
	v_mfma_f32_16x16x32_bf16 v[86:89], v[154:157], v[170:173], v[86:89]
	v_mfma_f32_16x16x32_bf16 v[82:85], v[162:165], v[170:173], v[82:85]
	v_mfma_f32_16x16x32_bf16 v[78:81], v[154:157], v[190:193], v[78:81]
	v_mfma_f32_16x16x32_bf16 v[74:77], v[162:165], v[190:193], v[74:77]
	v_mfma_f32_16x16x32_bf16 v[62:65], v[154:157], v[198:201], v[62:65]
	v_mfma_f32_16x16x32_bf16 v[58:61], v[162:165], v[198:201], v[58:61]
	v_mfma_f32_16x16x32_bf16 v[54:57], v[154:157], v[206:209], v[54:57]
	v_mfma_f32_16x16x32_bf16 v[50:53], v[162:165], v[206:209], v[50:53]
	s_barrier
	s_add_i32 s24, 0, 0x1c000
	s_add_i32 s25, s55, s35
	v_add_u32_e32 v149, s24, v146
	s_mov_b32 m0, s25
	ds_read_b128 v[210:213], v149
	ds_read_b128 v[214:217], v149 offset:1024
	ds_read_b128 v[218:221], v149 offset:2048
	ds_read_b128 v[222:225], v149 offset:3072
	global_load_lds_dwordx4 v134, s[64:65]
	s_add_i32 m0, s25, 0x2000
	s_nop 0
	global_load_lds_dwordx4 v130, s[64:65]
	s_barrier
	s_waitcnt lgkmcnt(0)
	s_waitcnt lgkmcnt(0)
	v_mfma_f32_16x16x32_bf16 v[126:129], v[210:213], v[166:169], v[126:129]
	v_mfma_f32_16x16x32_bf16 v[122:125], v[218:221], v[166:169], v[122:125]
	v_mfma_f32_16x16x32_bf16 v[118:121], v[210:213], v[174:177], v[118:121]
	v_mfma_f32_16x16x32_bf16 v[114:117], v[218:221], v[174:177], v[114:117]
	v_mfma_f32_16x16x32_bf16 v[110:113], v[210:213], v[194:197], v[110:113]
	v_mfma_f32_16x16x32_bf16 v[106:109], v[218:221], v[194:197], v[106:109]
	v_mfma_f32_16x16x32_bf16 v[102:105], v[210:213], v[202:205], v[102:105]
	v_mfma_f32_16x16x32_bf16 v[98:101], v[218:221], v[202:205], v[98:101]
	v_mfma_f32_16x16x32_bf16 v[126:129], v[214:217], v[170:173], v[126:129]
	v_mfma_f32_16x16x32_bf16 v[122:125], v[222:225], v[170:173], v[122:125]
	v_mfma_f32_16x16x32_bf16 v[118:121], v[214:217], v[190:193], v[118:121]
	v_mfma_f32_16x16x32_bf16 v[114:117], v[222:225], v[190:193], v[114:117]
	v_mfma_f32_16x16x32_bf16 v[110:113], v[214:217], v[198:201], v[110:113]
	v_mfma_f32_16x16x32_bf16 v[106:109], v[222:225], v[198:201], v[106:109]
	v_mfma_f32_16x16x32_bf16 v[102:105], v[214:217], v[206:209], v[102:105]
	v_mfma_f32_16x16x32_bf16 v[98:101], v[222:225], v[206:209], v[98:101]
	s_barrier
	s_mov_b32 m0, s46
	ds_read_b128 v[166:169], v148 offset:49152
	ds_read_b128 v[170:173], v148 offset:50176
	ds_read_b128 v[174:177], v148 offset:51200
	ds_read_b128 v[190:193], v148 offset:52224
	ds_read_b128 v[194:197], v148 offset:53248
	ds_read_b128 v[198:201], v148 offset:54272
	ds_read_b128 v[202:205], v148 offset:55296
	ds_read_b128 v[206:209], v148 offset:56320
	global_load_lds_dwordx4 v136, s[62:63]
	s_mov_b32 m0, s47
	s_nop 0
	global_load_lds_dwordx4 v132, s[62:63]
	s_barrier
	s_waitcnt lgkmcnt(0)
	s_waitcnt lgkmcnt(0)
	v_mfma_f32_16x16x32_bf16 v[34:37], v[150:153], v[166:169], v[34:37]
	v_mfma_f32_16x16x32_bf16 v[26:29], v[158:161], v[166:169], v[26:29]
	v_mfma_f32_16x16x32_bf16 v[22:25], v[150:153], v[174:177], v[22:25]
	v_mfma_f32_16x16x32_bf16 v[18:21], v[158:161], v[174:177], v[18:21]
	v_mfma_f32_16x16x32_bf16 v[14:17], v[150:153], v[194:197], v[14:17]
	v_mfma_f32_16x16x32_bf16 v[10:13], v[158:161], v[194:197], v[10:13]
	v_mfma_f32_16x16x32_bf16 v[6:9], v[150:153], v[202:205], v[6:9]
	v_mfma_f32_16x16x32_bf16 v[2:5], v[158:161], v[202:205], v[2:5]
	v_mfma_f32_16x16x32_bf16 v[34:37], v[154:157], v[170:173], v[34:37]
	v_mfma_f32_16x16x32_bf16 v[26:29], v[162:165], v[170:173], v[26:29]
	v_mfma_f32_16x16x32_bf16 v[22:25], v[154:157], v[190:193], v[22:25]
	v_mfma_f32_16x16x32_bf16 v[18:21], v[162:165], v[190:193], v[18:21]
	v_mfma_f32_16x16x32_bf16 v[14:17], v[154:157], v[198:201], v[14:17]
	v_mfma_f32_16x16x32_bf16 v[10:13], v[162:165], v[198:201], v[10:13]
	v_mfma_f32_16x16x32_bf16 v[6:9], v[154:157], v[206:209], v[6:9]
	v_mfma_f32_16x16x32_bf16 v[2:5], v[162:165], v[206:209], v[2:5]
	s_barrier
	s_add_u32 s22, s22, 0x40080
	s_addc_u32 s23, s23, 0
	s_add_i32 s24, s24, s35
	s_mov_b32 m0, s24
	s_nop 0
	global_load_lds_dwordx4 v134, s[22:23]
	v_lshl_add_u64 v[144:145], s[22:23], 0, v[130:131]
	s_add_i32 m0, s24, 0x2000
	s_nop 0
	global_load_lds_dwordx4 v[144:145], off
	s_waitcnt vmcnt(6)
	s_barrier
	v_mfma_f32_16x16x32_bf16 v[94:97], v[210:213], v[166:169], v[94:97]
	v_mfma_f32_16x16x32_bf16 v[90:93], v[218:221], v[166:169], v[90:93]
	v_mfma_f32_16x16x32_bf16 v[70:73], v[210:213], v[174:177], v[70:73]
	v_mfma_f32_16x16x32_bf16 v[66:69], v[218:221], v[174:177], v[66:69]
	v_mfma_f32_16x16x32_bf16 v[46:49], v[210:213], v[194:197], v[46:49]
	v_mfma_f32_16x16x32_bf16 v[42:45], v[218:221], v[194:197], v[42:45]
	v_mfma_f32_16x16x32_bf16 v[38:41], v[210:213], v[202:205], v[38:41]
	v_mfma_f32_16x16x32_bf16 v[30:33], v[218:221], v[202:205], v[30:33]
	v_mfma_f32_16x16x32_bf16 v[94:97], v[214:217], v[170:173], v[94:97]
	v_mfma_f32_16x16x32_bf16 v[90:93], v[222:225], v[170:173], v[90:93]
	v_mfma_f32_16x16x32_bf16 v[70:73], v[214:217], v[190:193], v[70:73]
	v_mfma_f32_16x16x32_bf16 v[66:69], v[222:225], v[190:193], v[66:69]
	v_mfma_f32_16x16x32_bf16 v[46:49], v[214:217], v[198:201], v[46:49]
	v_mfma_f32_16x16x32_bf16 v[42:45], v[222:225], v[198:201], v[42:45]
	v_mfma_f32_16x16x32_bf16 v[38:41], v[214:217], v[206:209], v[38:41]
	v_mfma_f32_16x16x32_bf16 v[30:33], v[222:225], v[206:209], v[30:33]
	s_barrier
	s_add_i32 s54, s54, 2
	s_add_u32 s20, s20, 0x100
	s_addc_u32 s21, s21, 0
	s_add_u32 s52, s52, 0x100
	s_addc_u32 s53, s53, 0
	s_cmp_gt_u32 s54, 13
	s_cbranch_scc0 .LBB0_528
	v_lshl_add_u32 v144, s10, 8, v1
	s_cmp_lg_u32 s50, s45
	s_mov_b64 s[10:11], -1
	s_cbranch_scc0 .LBB0_531
	v_lshl_or_b32 v154, s50, 8, v147
	v_readlane_b32 s13, v255, 32
	v_ashrrev_i32_e32 v155, 31, v154
	v_lshlrev_b64 v[154:155], 1, v[154:155]
	v_mad_i64_i32 v[156:157], s[10:11], v144, s13, 0
	v_lshl_add_u64 v[156:157], v[156:157], 1, s[6:7]
	v_lshl_add_u64 v[156:157], v[156:157], 0, v[154:155]
	v_cvt_pk_bf16_f32 v126, v126, v127
	v_cvt_pk_bf16_f32 v127, v128, v129
	v_cvt_pk_bf16_f32 v128, v122, v123
	v_cvt_pk_bf16_f32 v129, v124, v125
	global_store_dwordx4 v[156:157], v[126:129], off offset:256
	v_cvt_pk_bf16_f32 v150, v86, v87
	v_cvt_pk_bf16_f32 v151, v88, v89
	v_or_b32_e32 v126, 16, v144
	v_mad_i64_i32 v[126:127], s[10:11], v126, s13, 0
	v_lshl_add_u64 v[126:127], v[126:127], 1, s[6:7]
	v_cvt_pk_bf16_f32 v152, v82, v83
	v_cvt_pk_bf16_f32 v153, v84, v85
	v_lshl_add_u64 v[126:127], v[126:127], 0, v[154:155]
	v_cvt_pk_bf16_f32 v118, v118, v119
	v_cvt_pk_bf16_f32 v119, v120, v121
	v_cvt_pk_bf16_f32 v120, v114, v115
	v_cvt_pk_bf16_f32 v121, v116, v117
	global_store_dwordx4 v[156:157], v[150:153], off
	global_store_dwordx4 v[126:127], v[118:121], off offset:256
	v_cvt_pk_bf16_f32 v122, v78, v79
	v_cvt_pk_bf16_f32 v123, v80, v81
	v_or_b32_e32 v118, 32, v144
	v_mad_i64_i32 v[118:119], s[10:11], v118, s13, 0
	v_lshl_add_u64 v[118:119], v[118:119], 1, s[6:7]
	v_cvt_pk_bf16_f32 v124, v74, v75
	v_cvt_pk_bf16_f32 v125, v76, v77
	v_lshl_add_u64 v[118:119], v[118:119], 0, v[154:155]
	v_cvt_pk_bf16_f32 v110, v110, v111
	v_cvt_pk_bf16_f32 v111, v112, v113
	v_cvt_pk_bf16_f32 v112, v106, v107
	v_cvt_pk_bf16_f32 v113, v108, v109
	global_store_dwordx4 v[126:127], v[122:125], off
	global_store_dwordx4 v[118:119], v[110:113], off offset:256
	v_cvt_pk_bf16_f32 v114, v62, v63
	v_cvt_pk_bf16_f32 v115, v64, v65
	v_or_b32_e32 v110, 48, v144
	v_mad_i64_i32 v[110:111], s[10:11], v110, s13, 0
	v_lshl_add_u64 v[110:111], v[110:111], 1, s[6:7]
	v_cvt_pk_bf16_f32 v116, v58, v59
	v_cvt_pk_bf16_f32 v117, v60, v61
	v_lshl_add_u64 v[110:111], v[110:111], 0, v[154:155]
	v_cvt_pk_bf16_f32 v102, v102, v103
	v_cvt_pk_bf16_f32 v103, v104, v105
	v_cvt_pk_bf16_f32 v104, v98, v99
	v_cvt_pk_bf16_f32 v105, v100, v101
	global_store_dwordx4 v[118:119], v[114:117], off
	global_store_dwordx4 v[110:111], v[102:105], off offset:256
	v_cvt_pk_bf16_f32 v106, v54, v55
	v_cvt_pk_bf16_f32 v107, v56, v57
	v_add_u32_e32 v102, 0x80, v144
	v_mad_i64_i32 v[102:103], s[10:11], v102, s13, 0
	v_lshl_add_u64 v[102:103], v[102:103], 1, s[6:7]
	v_cvt_pk_bf16_f32 v108, v50, v51
	v_cvt_pk_bf16_f32 v109, v52, v53
	v_lshl_add_u64 v[102:103], v[102:103], 0, v[154:155]
	v_cvt_pk_bf16_f32 v94, v94, v95
	v_cvt_pk_bf16_f32 v95, v96, v97
	v_cvt_pk_bf16_f32 v96, v90, v91
	v_cvt_pk_bf16_f32 v97, v92, v93
	global_store_dwordx4 v[110:111], v[106:109], off
	global_store_dwordx4 v[102:103], v[94:97], off offset:256
	v_cvt_pk_bf16_f32 v98, v34, v35
	v_cvt_pk_bf16_f32 v99, v36, v37
	v_add_u32_e32 v94, 0x90, v144
	v_mad_i64_i32 v[94:95], s[10:11], v94, s13, 0
	v_lshl_add_u64 v[94:95], v[94:95], 1, s[6:7]
	v_cvt_pk_bf16_f32 v100, v26, v27
	v_cvt_pk_bf16_f32 v101, v28, v29
	v_lshl_add_u64 v[94:95], v[94:95], 0, v[154:155]
	v_cvt_pk_bf16_f32 v70, v70, v71
	v_cvt_pk_bf16_f32 v71, v72, v73
	v_cvt_pk_bf16_f32 v72, v66, v67
	v_cvt_pk_bf16_f32 v73, v68, v69
	global_store_dwordx4 v[102:103], v[98:101], off
	global_store_dwordx4 v[94:95], v[70:73], off offset:256
	v_cvt_pk_bf16_f32 v90, v22, v23
	v_cvt_pk_bf16_f32 v91, v24, v25
	v_add_u32_e32 v70, 0xa0, v144
	v_mad_i64_i32 v[70:71], s[10:11], v70, s13, 0
	v_lshl_add_u64 v[70:71], v[70:71], 1, s[6:7]
	v_cvt_pk_bf16_f32 v92, v18, v19
	v_cvt_pk_bf16_f32 v93, v20, v21
	v_lshl_add_u64 v[70:71], v[70:71], 0, v[154:155]
	v_cvt_pk_bf16_f32 v46, v46, v47
	v_cvt_pk_bf16_f32 v47, v48, v49
	v_cvt_pk_bf16_f32 v48, v42, v43
	v_cvt_pk_bf16_f32 v49, v44, v45
	global_store_dwordx4 v[94:95], v[90:93], off
	global_store_dwordx4 v[70:71], v[46:49], off offset:256
	v_cvt_pk_bf16_f32 v66, v14, v15
	v_cvt_pk_bf16_f32 v67, v16, v17
	v_add_u32_e32 v46, 0xb0, v144
	v_mad_i64_i32 v[46:47], s[10:11], v46, s13, 0
	v_lshl_add_u64 v[46:47], v[46:47], 1, s[6:7]
	v_cvt_pk_bf16_f32 v68, v10, v11
	v_cvt_pk_bf16_f32 v69, v12, v13
	v_cvt_pk_bf16_f32 v42, v6, v7
	v_cvt_pk_bf16_f32 v43, v8, v9
	v_cvt_pk_bf16_f32 v44, v2, v3
	v_cvt_pk_bf16_f32 v45, v4, v5
	v_lshl_add_u64 v[46:47], v[46:47], 0, v[154:155]
	v_cvt_pk_bf16_f32 v38, v38, v39
	v_cvt_pk_bf16_f32 v39, v40, v41
	v_cvt_pk_bf16_f32 v40, v30, v31
	v_cvt_pk_bf16_f32 v41, v32, v33
	global_store_dwordx4 v[70:71], v[66:69], off
	global_store_dwordx4 v[46:47], v[42:45], off
	global_store_dwordx4 v[46:47], v[38:41], off offset:256
	s_mov_b64 s[10:11], 0

.LBB0_1408:
	s_add_u32 s16, s14, s6
	s_addc_u32 s17, s15, s7
	s_add_u32 s16, s16, 0x100
	s_addc_u32 s17, s17, 0
	s_add_u32 s48, s45, s6
	s_addc_u32 s49, s46, s7
	s_add_i32 s50, 0, 0x10000
	v_add_u32_e32 v158, s50, v164
	ds_read_b128 v[146:149], v158
	ds_read_b128 v[150:153], v158 offset:1024
	ds_read_b128 v[154:157], v158 offset:2048
	ds_read_b128 v[158:161], v158 offset:3072
	s_cmpk_eq_i32 s6, 0xf00
	s_cselect_b32 s19, s11, s17
	s_cselect_b32 s18, s10, s16
	s_cselect_b32 s17, s3, s49
	s_cselect_b32 s16, s44, s48
	v_lshl_add_u64 v[162:163], v[142:143], 0, s[6:7]
	s_add_i32 m0, s30, 0xc000
	ds_read_b128 v[168:171], v166
	ds_read_b128 v[172:175], v166 offset:1024
	ds_read_b128 v[186:189], v166 offset:2048
	ds_read_b128 v[190:193], v166 offset:3072
	ds_read_b128 v[194:197], v166 offset:4096
	ds_read_b128 v[198:201], v166 offset:5120
	ds_read_b128 v[202:205], v166 offset:6144
	ds_read_b128 v[206:209], v166 offset:7168
	global_load_lds_dwordx4 v[162:163], off
	v_lshl_add_u64 v[162:163], v[144:145], 0, s[6:7]
	s_add_i32 m0, s30, 0xe000
	s_nop 0
	global_load_lds_dwordx4 v[162:163], off
	s_waitcnt lgkmcnt(8)
	s_barrier
	s_waitcnt lgkmcnt(0)
	s_waitcnt lgkmcnt(0)
	v_mfma_f32_16x16x32_bf16 v[126:129], v[146:149], v[168:171], v[126:129]
	v_mfma_f32_16x16x32_bf16 v[122:125], v[154:157], v[168:171], v[122:125]
	v_mfma_f32_16x16x32_bf16 v[110:113], v[146:149], v[186:189], v[110:113]
	v_mfma_f32_16x16x32_bf16 v[106:109], v[154:157], v[186:189], v[106:109]
	v_mfma_f32_16x16x32_bf16 v[94:97], v[146:149], v[194:197], v[94:97]
	v_mfma_f32_16x16x32_bf16 v[90:93], v[154:157], v[194:197], v[90:93]
	v_mfma_f32_16x16x32_bf16 v[78:81], v[146:149], v[202:205], v[78:81]
	v_mfma_f32_16x16x32_bf16 v[74:77], v[154:157], v[202:205], v[74:77]
	v_mfma_f32_16x16x32_bf16 v[126:129], v[150:153], v[172:175], v[126:129]
	v_mfma_f32_16x16x32_bf16 v[122:125], v[158:161], v[172:175], v[122:125]
	v_mfma_f32_16x16x32_bf16 v[110:113], v[150:153], v[190:193], v[110:113]
	v_mfma_f32_16x16x32_bf16 v[106:109], v[158:161], v[190:193], v[106:109]
	v_mfma_f32_16x16x32_bf16 v[94:97], v[150:153], v[198:201], v[94:97]
	v_mfma_f32_16x16x32_bf16 v[90:93], v[158:161], v[198:201], v[90:93]
	v_mfma_f32_16x16x32_bf16 v[78:81], v[150:153], v[206:209], v[78:81]
	v_mfma_f32_16x16x32_bf16 v[74:77], v[158:161], v[206:209], v[74:77]
	s_barrier
	s_add_i32 s51, 0, 0x14000
	v_add_u32_e32 v162, s51, v164
	s_add_i32 s48, s50, s29
	ds_read_b128 v[210:213], v162
	ds_read_b128 v[214:217], v162 offset:1024
	ds_read_b128 v[218:221], v162 offset:2048
	ds_read_b128 v[222:225], v162 offset:3072
	s_add_u32 s64, s16, 0x80
	s_addc_u32 s65, s17, 0
	s_mov_b32 m0, s48
	s_nop 0
	global_load_lds_dwordx4 v132, s[16:17]
	s_add_i32 m0, s48, 0x2000
	s_nop 0
	global_load_lds_dwordx4 v136, s[16:17]
	s_barrier
	s_waitcnt lgkmcnt(0)
	s_waitcnt lgkmcnt(0)
	v_mfma_f32_16x16x32_bf16 v[118:121], v[210:213], v[168:171], v[118:121]
	v_mfma_f32_16x16x32_bf16 v[114:117], v[218:221], v[168:171], v[114:117]
	v_mfma_f32_16x16x32_bf16 v[102:105], v[210:213], v[186:189], v[102:105]
	v_mfma_f32_16x16x32_bf16 v[98:101], v[218:221], v[186:189], v[98:101]
	v_mfma_f32_16x16x32_bf16 v[86:89], v[210:213], v[194:197], v[86:89]
	v_mfma_f32_16x16x32_bf16 v[82:85], v[218:221], v[194:197], v[82:85]
	v_mfma_f32_16x16x32_bf16 v[70:73], v[210:213], v[202:205], v[70:73]
	v_mfma_f32_16x16x32_bf16 v[66:69], v[218:221], v[202:205], v[66:69]
	v_mfma_f32_16x16x32_bf16 v[118:121], v[214:217], v[172:175], v[118:121]
	v_mfma_f32_16x16x32_bf16 v[114:117], v[222:225], v[172:175], v[114:117]
	v_mfma_f32_16x16x32_bf16 v[102:105], v[214:217], v[190:193], v[102:105]
	v_mfma_f32_16x16x32_bf16 v[98:101], v[222:225], v[190:193], v[98:101]
	v_mfma_f32_16x16x32_bf16 v[86:89], v[214:217], v[198:201], v[86:89]
	v_mfma_f32_16x16x32_bf16 v[82:85], v[222:225], v[198:201], v[82:85]
	v_mfma_f32_16x16x32_bf16 v[70:73], v[214:217], v[206:209], v[70:73]
	v_mfma_f32_16x16x32_bf16 v[66:69], v[222:225], v[206:209], v[66:69]
	s_barrier
	s_mov_b32 m0, s30
	s_add_u32 s62, s18, 0x80
	s_addc_u32 s63, s19, 0
	ds_read_b128 v[168:171], v166 offset:16384
	ds_read_b128 v[172:175], v166 offset:17408
	ds_read_b128 v[186:189], v166 offset:18432
	ds_read_b128 v[190:193], v166 offset:19456
	ds_read_b128 v[194:197], v166 offset:20480
	ds_read_b128 v[198:201], v166 offset:21504
	ds_read_b128 v[202:205], v166 offset:22528
	ds_read_b128 v[206:209], v166 offset:23552
	global_load_lds_dwordx4 v130, s[18:19]
	s_mov_b32 m0, s31
	s_nop 0
	global_load_lds_dwordx4 v134, s[18:19]
	s_barrier
	s_waitcnt lgkmcnt(0)
	s_waitcnt lgkmcnt(0)
	v_mfma_f32_16x16x32_bf16 v[62:65], v[146:149], v[168:171], v[62:65]
	v_mfma_f32_16x16x32_bf16 v[58:61], v[154:157], v[168:171], v[58:61]
	v_mfma_f32_16x16x32_bf16 v[46:49], v[146:149], v[186:189], v[46:49]
	v_mfma_f32_16x16x32_bf16 v[42:45], v[154:157], v[186:189], v[42:45]
	v_mfma_f32_16x16x32_bf16 v[30:33], v[146:149], v[194:197], v[30:33]
	v_mfma_f32_16x16x32_bf16 v[26:29], v[154:157], v[194:197], v[26:29]
	v_mfma_f32_16x16x32_bf16 v[14:17], v[146:149], v[202:205], v[14:17]
	v_mfma_f32_16x16x32_bf16 v[10:13], v[154:157], v[202:205], v[10:13]
	v_mfma_f32_16x16x32_bf16 v[62:65], v[150:153], v[172:175], v[62:65]
	v_mfma_f32_16x16x32_bf16 v[58:61], v[158:161], v[172:175], v[58:61]
	v_mfma_f32_16x16x32_bf16 v[46:49], v[150:153], v[190:193], v[46:49]
	v_mfma_f32_16x16x32_bf16 v[42:45], v[158:161], v[190:193], v[42:45]
	v_mfma_f32_16x16x32_bf16 v[30:33], v[150:153], v[198:201], v[30:33]
	v_mfma_f32_16x16x32_bf16 v[26:29], v[158:161], v[198:201], v[26:29]
	v_mfma_f32_16x16x32_bf16 v[14:17], v[150:153], v[206:209], v[14:17]
	v_mfma_f32_16x16x32_bf16 v[10:13], v[158:161], v[206:209], v[10:13]
	s_barrier
	s_add_u32 s48, s16, 0x80000
	s_addc_u32 s49, s17, 0
	s_add_i32 s50, s51, s29
	s_mov_b32 m0, s50
	s_nop 0
	global_load_lds_dwordx4 v132, s[48:49]
	s_add_i32 m0, s50, 0x2000
	s_nop 0
	global_load_lds_dwordx4 v136, s[48:49]
	s_waitcnt vmcnt(6)
	s_barrier
	v_mfma_f32_16x16x32_bf16 v[54:57], v[210:213], v[168:171], v[54:57]
	v_mfma_f32_16x16x32_bf16 v[50:53], v[218:221], v[168:171], v[50:53]
	v_mfma_f32_16x16x32_bf16 v[38:41], v[210:213], v[186:189], v[38:41]
	v_mfma_f32_16x16x32_bf16 v[34:37], v[218:221], v[186:189], v[34:37]
	v_mfma_f32_16x16x32_bf16 v[22:25], v[210:213], v[194:197], v[22:25]
	v_mfma_f32_16x16x32_bf16 v[18:21], v[218:221], v[194:197], v[18:21]
	v_mfma_f32_16x16x32_bf16 v[6:9], v[210:213], v[202:205], v[6:9]
	v_mfma_f32_16x16x32_bf16 v[2:5], v[218:221], v[202:205], v[2:5]
	v_mfma_f32_16x16x32_bf16 v[54:57], v[214:217], v[172:175], v[54:57]
	v_mfma_f32_16x16x32_bf16 v[50:53], v[222:225], v[172:175], v[50:53]
	v_mfma_f32_16x16x32_bf16 v[38:41], v[214:217], v[190:193], v[38:41]
	v_mfma_f32_16x16x32_bf16 v[34:37], v[222:225], v[190:193], v[34:37]
	v_mfma_f32_16x16x32_bf16 v[22:25], v[214:217], v[198:201], v[22:25]
	v_mfma_f32_16x16x32_bf16 v[18:21], v[222:225], v[198:201], v[18:21]
	v_mfma_f32_16x16x32_bf16 v[6:9], v[214:217], v[206:209], v[6:9]
	v_mfma_f32_16x16x32_bf16 v[2:5], v[222:225], v[206:209], v[2:5]
	s_barrier
	s_add_i32 s48, 0, 0x18000
	v_add_u32_e32 v158, s48, v164
	ds_read_b128 v[146:149], v158
	ds_read_b128 v[150:153], v158 offset:1024
	ds_read_b128 v[154:157], v158 offset:2048
	ds_read_b128 v[158:161], v158 offset:3072
	s_add_u32 s18, s18, s80
	s_addc_u32 s19, s19, 0
	s_mov_b32 m0, s34
	ds_read_b128 v[168:171], v166 offset:32768
	ds_read_b128 v[172:175], v166 offset:33792
	ds_read_b128 v[186:189], v166 offset:34816
	ds_read_b128 v[190:193], v166 offset:35840
	ds_read_b128 v[194:197], v166 offset:36864
	ds_read_b128 v[198:201], v166 offset:37888
	ds_read_b128 v[202:205], v166 offset:38912
	ds_read_b128 v[206:209], v166 offset:39936
	global_load_lds_dwordx4 v130, s[18:19]
	s_mov_b32 m0, s35
	s_nop 0
	global_load_lds_dwordx4 v134, s[18:19]
	s_waitcnt lgkmcnt(8)
	s_barrier
	s_waitcnt lgkmcnt(0)
	s_waitcnt lgkmcnt(0)
	v_mfma_f32_16x16x32_bf16 v[126:129], v[146:149], v[168:171], v[126:129]
	v_mfma_f32_16x16x32_bf16 v[122:125], v[154:157], v[168:171], v[122:125]
	v_mfma_f32_16x16x32_bf16 v[110:113], v[146:149], v[186:189], v[110:113]
	v_mfma_f32_16x16x32_bf16 v[106:109], v[154:157], v[186:189], v[106:109]
	v_mfma_f32_16x16x32_bf16 v[94:97], v[146:149], v[194:197], v[94:97]
	v_mfma_f32_16x16x32_bf16 v[90:93], v[154:157], v[194:197], v[90:93]
	v_mfma_f32_16x16x32_bf16 v[78:81], v[146:149], v[202:205], v[78:81]
	v_mfma_f32_16x16x32_bf16 v[74:77], v[154:157], v[202:205], v[74:77]
	v_mfma_f32_16x16x32_bf16 v[126:129], v[150:153], v[172:175], v[126:129]
	v_mfma_f32_16x16x32_bf16 v[122:125], v[158:161], v[172:175], v[122:125]
	v_mfma_f32_16x16x32_bf16 v[110:113], v[150:153], v[190:193], v[110:113]
	v_mfma_f32_16x16x32_bf16 v[106:109], v[158:161], v[190:193], v[106:109]
	v_mfma_f32_16x16x32_bf16 v[94:97], v[150:153], v[198:201], v[94:97]
	v_mfma_f32_16x16x32_bf16 v[90:93], v[158:161], v[198:201], v[90:93]
	v_mfma_f32_16x16x32_bf16 v[78:81], v[150:153], v[206:209], v[78:81]
	v_mfma_f32_16x16x32_bf16 v[74:77], v[158:161], v[206:209], v[74:77]
	s_barrier
	s_add_i32 s18, 0, 0x1c000
	s_add_i32 s19, s48, s29
	v_add_u32_e32 v167, s18, v164
	s_mov_b32 m0, s19
	ds_read_b128 v[210:213], v167
	ds_read_b128 v[214:217], v167 offset:1024
	ds_read_b128 v[218:221], v167 offset:2048
	ds_read_b128 v[222:225], v167 offset:3072
	global_load_lds_dwordx4 v132, s[64:65]
	s_add_i32 m0, s19, 0x2000
	s_nop 0
	global_load_lds_dwordx4 v136, s[64:65]
	s_barrier
	s_waitcnt lgkmcnt(0)
	s_waitcnt lgkmcnt(0)
	v_mfma_f32_16x16x32_bf16 v[118:121], v[210:213], v[168:171], v[118:121]
	v_mfma_f32_16x16x32_bf16 v[114:117], v[218:221], v[168:171], v[114:117]
	v_mfma_f32_16x16x32_bf16 v[102:105], v[210:213], v[186:189], v[102:105]
	v_mfma_f32_16x16x32_bf16 v[98:101], v[218:221], v[186:189], v[98:101]
	v_mfma_f32_16x16x32_bf16 v[86:89], v[210:213], v[194:197], v[86:89]
	v_mfma_f32_16x16x32_bf16 v[82:85], v[218:221], v[194:197], v[82:85]
	v_mfma_f32_16x16x32_bf16 v[70:73], v[210:213], v[202:205], v[70:73]
	v_mfma_f32_16x16x32_bf16 v[66:69], v[218:221], v[202:205], v[66:69]
	v_mfma_f32_16x16x32_bf16 v[118:121], v[214:217], v[172:175], v[118:121]
	v_mfma_f32_16x16x32_bf16 v[114:117], v[222:225], v[172:175], v[114:117]
	v_mfma_f32_16x16x32_bf16 v[102:105], v[214:217], v[190:193], v[102:105]
	v_mfma_f32_16x16x32_bf16 v[98:101], v[222:225], v[190:193], v[98:101]
	v_mfma_f32_16x16x32_bf16 v[86:89], v[214:217], v[198:201], v[86:89]
	v_mfma_f32_16x16x32_bf16 v[82:85], v[222:225], v[198:201], v[82:85]
	v_mfma_f32_16x16x32_bf16 v[70:73], v[214:217], v[206:209], v[70:73]
	v_mfma_f32_16x16x32_bf16 v[66:69], v[222:225], v[206:209], v[66:69]
	s_barrier
	s_mov_b32 m0, s38
	ds_read_b128 v[168:171], v166 offset:49152
	ds_read_b128 v[172:175], v166 offset:50176
	ds_read_b128 v[186:189], v166 offset:51200
	ds_read_b128 v[190:193], v166 offset:52224
	ds_read_b128 v[194:197], v166 offset:53248
	ds_read_b128 v[198:201], v166 offset:54272
	ds_read_b128 v[202:205], v166 offset:55296
	ds_read_b128 v[206:209], v166 offset:56320
	global_load_lds_dwordx4 v130, s[62:63]
	s_mov_b32 m0, s39
	s_nop 0
	global_load_lds_dwordx4 v134, s[62:63]
	s_barrier
	s_waitcnt lgkmcnt(0)
	s_waitcnt lgkmcnt(0)
	v_mfma_f32_16x16x32_bf16 v[62:65], v[146:149], v[168:171], v[62:65]
	v_mfma_f32_16x16x32_bf16 v[58:61], v[154:157], v[168:171], v[58:61]
	v_mfma_f32_16x16x32_bf16 v[46:49], v[146:149], v[186:189], v[46:49]
	v_mfma_f32_16x16x32_bf16 v[42:45], v[154:157], v[186:189], v[42:45]
	v_mfma_f32_16x16x32_bf16 v[30:33], v[146:149], v[194:197], v[30:33]
	v_mfma_f32_16x16x32_bf16 v[26:29], v[154:157], v[194:197], v[26:29]
	v_mfma_f32_16x16x32_bf16 v[14:17], v[146:149], v[202:205], v[14:17]
	v_mfma_f32_16x16x32_bf16 v[10:13], v[154:157], v[202:205], v[10:13]
	v_mfma_f32_16x16x32_bf16 v[62:65], v[150:153], v[172:175], v[62:65]
	v_mfma_f32_16x16x32_bf16 v[58:61], v[158:161], v[172:175], v[58:61]
	v_mfma_f32_16x16x32_bf16 v[46:49], v[150:153], v[190:193], v[46:49]
	v_mfma_f32_16x16x32_bf16 v[42:45], v[158:161], v[190:193], v[42:45]
	v_mfma_f32_16x16x32_bf16 v[30:33], v[150:153], v[198:201], v[30:33]
	v_mfma_f32_16x16x32_bf16 v[26:29], v[158:161], v[198:201], v[26:29]
	v_mfma_f32_16x16x32_bf16 v[14:17], v[150:153], v[206:209], v[14:17]
	v_mfma_f32_16x16x32_bf16 v[10:13], v[158:161], v[206:209], v[10:13]
	s_barrier
	s_add_u32 s16, s16, 0x80080
	s_addc_u32 s17, s17, 0
	s_add_i32 s18, s18, s29
	s_mov_b32 m0, s18
	s_nop 0
	global_load_lds_dwordx4 v132, s[16:17]
	s_add_i32 m0, s18, 0x2000
	s_nop 0
	global_load_lds_dwordx4 v136, s[16:17]
	s_waitcnt vmcnt(6)
	s_barrier
	v_mfma_f32_16x16x32_bf16 v[54:57], v[210:213], v[168:171], v[54:57]
	v_mfma_f32_16x16x32_bf16 v[50:53], v[218:221], v[168:171], v[50:53]
	v_mfma_f32_16x16x32_bf16 v[38:41], v[210:213], v[186:189], v[38:41]
	v_mfma_f32_16x16x32_bf16 v[34:37], v[218:221], v[186:189], v[34:37]
	v_mfma_f32_16x16x32_bf16 v[22:25], v[210:213], v[194:197], v[22:25]
	v_mfma_f32_16x16x32_bf16 v[18:21], v[218:221], v[194:197], v[18:21]
	v_mfma_f32_16x16x32_bf16 v[6:9], v[210:213], v[202:205], v[6:9]
	v_mfma_f32_16x16x32_bf16 v[2:5], v[218:221], v[202:205], v[2:5]
	v_mfma_f32_16x16x32_bf16 v[54:57], v[214:217], v[172:175], v[54:57]
	v_mfma_f32_16x16x32_bf16 v[50:53], v[222:225], v[172:175], v[50:53]
	v_mfma_f32_16x16x32_bf16 v[38:41], v[214:217], v[190:193], v[38:41]
	v_mfma_f32_16x16x32_bf16 v[34:37], v[222:225], v[190:193], v[34:37]
	v_mfma_f32_16x16x32_bf16 v[22:25], v[214:217], v[198:201], v[22:25]
	v_mfma_f32_16x16x32_bf16 v[18:21], v[222:225], v[198:201], v[18:21]
	v_mfma_f32_16x16x32_bf16 v[6:9], v[214:217], v[206:209], v[6:9]
	v_mfma_f32_16x16x32_bf16 v[2:5], v[222:225], v[206:209], v[2:5]
	s_barrier
	s_add_i32 s47, s47, 2
	s_add_u32 s6, s6, 0x100
	s_addc_u32 s7, s7, 0
	s_cmp_gt_u32 s47, 29
	s_cbranch_scc0 .LBB0_1408
	s_ashr_i32 s3, s33, 5
	s_mul_hi_i32 s7, s3, 0x9000
	s_mul_i32 s3, s3, 0x9000
	v_lshl_or_b32 v168, s43, 8, v165
	s_add_u32 s6, s36, s3
	s_addc_u32 s7, s37, s7
	v_ashrrev_i32_e32 v169, 31, v168
	v_lshl_add_u64 v[162:163], v[168:169], 2, s[6:7]
	global_load_dwordx4 v[142:145], v[162:163], off offset:16
	global_load_dwordx4 v[146:149], v[162:163], off
	s_mov_b64 s[6:7], 0x80000
	s_and_b64 vcc, exec, s[4:5]
	s_mov_b32 s43, s2
	s_mov_b64 s[16:17], s[12:13]
	s_mov_b64 s[14:15], s[10:11]
	s_waitcnt vmcnt(0)
	v_pk_add_f32 v[150:151], v[144:145], 1.0 op_sel_hi:[1,0]
	v_pk_add_f32 v[154:155], v[142:143], 1.0 op_sel_hi:[1,0]
	global_load_dwordx4 v[158:161], v[162:163], off offset:528
	global_load_dwordx4 v[142:145], v[162:163], off offset:512
	v_lshl_add_u32 v162, s33, 8, v1
	v_ashrrev_i32_e32 v163, 31, v162
	v_pk_add_f32 v[156:157], v[146:147], 1.0 op_sel_hi:[1,0]
	v_pk_add_f32 v[152:153], v[148:149], 1.0 op_sel_hi:[1,0]
	s_mov_b32 s33, s42
	s_waitcnt vmcnt(0)
	v_pk_add_f32 v[146:147], v[144:145], 1.0 op_sel_hi:[1,0]
	v_pk_add_f32 v[144:145], v[158:159], 1.0 op_sel_hi:[1,0]
	v_lshlrev_b64 v[158:159], 12, v[162:163]
	v_pk_add_f32 v[148:149], v[142:143], 1.0 op_sel_hi:[1,0]
	v_pk_add_f32 v[142:143], v[160:161], 1.0 op_sel_hi:[1,0]
	v_lshl_add_u64 v[158:159], s[8:9], 0, v[158:159]
	v_lshlrev_b64 v[160:161], 1, v[168:169]
	v_lshl_add_u64 v[158:159], v[158:159], 0, v[160:161]
	global_load_dwordx4 v[168:171], v[158:159], off offset:2048
	s_waitcnt vmcnt(0)
	v_lshlrev_b32_e32 v172, 16, v168
	v_and_b32_e32 v173, 0xffff0000, v168
	v_lshlrev_b32_e32 v168, 16, v169
	v_and_b32_e32 v169, 0xffff0000, v169
	v_pk_fma_f32 v[128:129], v[128:129], v[152:153], v[168:169]
	v_lshlrev_b32_e32 v168, 16, v170
	v_and_b32_e32 v169, 0xffff0000, v170
	v_pk_fma_f32 v[168:169], v[122:123], v[154:155], v[168:169]
	v_lshlrev_b32_e32 v122, 16, v171
	v_and_b32_e32 v123, 0xffff0000, v171
	v_pk_fma_f32 v[126:127], v[126:127], v[156:157], v[172:173]
	v_pk_fma_f32 v[170:171], v[124:125], v[150:151], v[122:123]
	v_cvt_pk_bf16_f32 v122, v126, v127
	v_cvt_pk_bf16_f32 v123, v128, v129
	v_cvt_pk_bf16_f32 v124, v168, v169
	v_cvt_pk_bf16_f32 v125, v170, v171
	global_store_dwordx4 v[158:159], v[122:125], off offset:2048
	global_load_dwordx4 v[122:125], v[158:159], off offset:2304
	s_waitcnt vmcnt(0)
	v_lshlrev_b32_e32 v126, 16, v122
	v_and_b32_e32 v127, 0xffff0000, v122
	v_lshlrev_b32_e32 v122, 16, v123
	v_and_b32_e32 v123, 0xffff0000, v123
	v_pk_fma_f32 v[120:121], v[120:121], v[146:147], v[122:123]
	v_lshlrev_b32_e32 v122, 16, v124
	v_and_b32_e32 v123, 0xffff0000, v124
	v_pk_fma_f32 v[122:123], v[114:115], v[144:145], v[122:123]
	v_lshlrev_b32_e32 v114, 16, v125
	v_and_b32_e32 v115, 0xffff0000, v125
	v_pk_fma_f32 v[118:119], v[118:119], v[148:149], v[126:127]
	v_pk_fma_f32 v[124:125], v[116:117], v[142:143], v[114:115]
	v_cvt_pk_bf16_f32 v114, v118, v119
	v_cvt_pk_bf16_f32 v115, v120, v121
	v_cvt_pk_bf16_f32 v116, v122, v123
	v_cvt_pk_bf16_f32 v117, v124, v125
	global_store_dwordx4 v[158:159], v[114:117], off offset:2304
	s_nop 1
	v_or_b32_e32 v114, 16, v162
	v_ashrrev_i32_e32 v115, 31, v114
	v_lshlrev_b64 v[114:115], 12, v[114:115]
	v_lshl_add_u64 v[114:115], s[8:9], 0, v[114:115]
	v_lshl_add_u64 v[118:119], v[114:115], 0, v[160:161]
	global_load_dwordx4 v[114:117], v[118:119], off offset:2048
	s_waitcnt vmcnt(0)
	v_lshlrev_b32_e32 v120, 16, v114
	v_and_b32_e32 v121, 0xffff0000, v114
	v_lshlrev_b32_e32 v114, 16, v115
	v_and_b32_e32 v115, 0xffff0000, v115
	v_pk_fma_f32 v[112:113], v[112:113], v[152:153], v[114:115]
	v_lshlrev_b32_e32 v114, 16, v116
	v_and_b32_e32 v115, 0xffff0000, v116
	v_pk_fma_f32 v[114:115], v[106:107], v[154:155], v[114:115]
	v_lshlrev_b32_e32 v106, 16, v117
	v_and_b32_e32 v107, 0xffff0000, v117
	v_pk_fma_f32 v[110:111], v[110:111], v[156:157], v[120:121]
	v_pk_fma_f32 v[116:117], v[108:109], v[150:151], v[106:107]
	v_cvt_pk_bf16_f32 v106, v110, v111
	v_cvt_pk_bf16_f32 v107, v112, v113
	v_cvt_pk_bf16_f32 v108, v114, v115
	v_cvt_pk_bf16_f32 v109, v116, v117
	global_store_dwordx4 v[118:119], v[106:109], off offset:2048
	global_load_dwordx4 v[106:109], v[118:119], off offset:2304
	s_waitcnt vmcnt(0)
	v_lshlrev_b32_e32 v110, 16, v106
	v_and_b32_e32 v111, 0xffff0000, v106
	v_lshlrev_b32_e32 v106, 16, v107
	v_and_b32_e32 v107, 0xffff0000, v107
	v_pk_fma_f32 v[104:105], v[104:105], v[146:147], v[106:107]
	v_lshlrev_b32_e32 v106, 16, v108
	v_and_b32_e32 v107, 0xffff0000, v108
	v_pk_fma_f32 v[106:107], v[98:99], v[144:145], v[106:107]
	v_lshlrev_b32_e32 v98, 16, v109
	v_and_b32_e32 v99, 0xffff0000, v109
	v_pk_fma_f32 v[102:103], v[102:103], v[148:149], v[110:111]
	v_pk_fma_f32 v[108:109], v[100:101], v[142:143], v[98:99]
	v_cvt_pk_bf16_f32 v98, v102, v103
	v_cvt_pk_bf16_f32 v99, v104, v105
	v_cvt_pk_bf16_f32 v100, v106, v107
	v_cvt_pk_bf16_f32 v101, v108, v109
	global_store_dwordx4 v[118:119], v[98:101], off offset:2304
	s_nop 1
	v_or_b32_e32 v98, 32, v162
	v_ashrrev_i32_e32 v99, 31, v98
	v_lshlrev_b64 v[98:99], 12, v[98:99]
	v_lshl_add_u64 v[98:99], s[8:9], 0, v[98:99]
	v_lshl_add_u64 v[102:103], v[98:99], 0, v[160:161]
	global_load_dwordx4 v[98:101], v[102:103], off offset:2048
	s_waitcnt vmcnt(0)
	v_lshlrev_b32_e32 v104, 16, v98
	v_and_b32_e32 v105, 0xffff0000, v98
	v_lshlrev_b32_e32 v98, 16, v99
	v_and_b32_e32 v99, 0xffff0000, v99
	v_pk_fma_f32 v[96:97], v[96:97], v[152:153], v[98:99]
	v_lshlrev_b32_e32 v98, 16, v100
	v_and_b32_e32 v99, 0xffff0000, v100
	v_pk_fma_f32 v[98:99], v[90:91], v[154:155], v[98:99]
	v_lshlrev_b32_e32 v90, 16, v101
	v_and_b32_e32 v91, 0xffff0000, v101
	v_pk_fma_f32 v[94:95], v[94:95], v[156:157], v[104:105]
	v_pk_fma_f32 v[100:101], v[92:93], v[150:151], v[90:91]
	v_cvt_pk_bf16_f32 v90, v94, v95
	v_cvt_pk_bf16_f32 v91, v96, v97
	v_cvt_pk_bf16_f32 v92, v98, v99
	v_cvt_pk_bf16_f32 v93, v100, v101
	global_store_dwordx4 v[102:103], v[90:93], off offset:2048
	global_load_dwordx4 v[90:93], v[102:103], off offset:2304
	s_waitcnt vmcnt(0)
	v_lshlrev_b32_e32 v94, 16, v90
	v_and_b32_e32 v95, 0xffff0000, v90
	v_lshlrev_b32_e32 v90, 16, v91
	v_and_b32_e32 v91, 0xffff0000, v91
	v_pk_fma_f32 v[88:89], v[88:89], v[146:147], v[90:91]
	v_lshlrev_b32_e32 v90, 16, v92
	v_and_b32_e32 v91, 0xffff0000, v92
	v_pk_fma_f32 v[90:91], v[82:83], v[144:145], v[90:91]
	v_lshlrev_b32_e32 v82, 16, v93
	v_and_b32_e32 v83, 0xffff0000, v93
	v_pk_fma_f32 v[86:87], v[86:87], v[148:149], v[94:95]
	v_pk_fma_f32 v[92:93], v[84:85], v[142:143], v[82:83]
	v_cvt_pk_bf16_f32 v82, v86, v87
	v_cvt_pk_bf16_f32 v83, v88, v89
	v_cvt_pk_bf16_f32 v84, v90, v91
	v_cvt_pk_bf16_f32 v85, v92, v93
	global_store_dwordx4 v[102:103], v[82:85], off offset:2304
	s_nop 1
	v_or_b32_e32 v82, 48, v162
	v_ashrrev_i32_e32 v83, 31, v82
	v_lshlrev_b64 v[82:83], 12, v[82:83]
	v_lshl_add_u64 v[82:83], s[8:9], 0, v[82:83]
	v_lshl_add_u64 v[82:83], v[82:83], 0, v[160:161]
	global_load_dwordx4 v[84:87], v[82:83], off offset:2048
	s_waitcnt vmcnt(0)
	v_lshlrev_b32_e32 v88, 16, v84
	v_and_b32_e32 v89, 0xffff0000, v84
	v_lshlrev_b32_e32 v84, 16, v85
	v_and_b32_e32 v85, 0xffff0000, v85
	v_pk_fma_f32 v[80:81], v[80:81], v[152:153], v[84:85]
	v_lshlrev_b32_e32 v84, 16, v86
	v_and_b32_e32 v85, 0xffff0000, v86
	v_pk_fma_f32 v[84:85], v[74:75], v[154:155], v[84:85]
	v_lshlrev_b32_e32 v74, 16, v87
	v_and_b32_e32 v75, 0xffff0000, v87
	v_pk_fma_f32 v[78:79], v[78:79], v[156:157], v[88:89]
	v_pk_fma_f32 v[86:87], v[76:77], v[150:151], v[74:75]
	v_cvt_pk_bf16_f32 v74, v78, v79
	v_cvt_pk_bf16_f32 v75, v80, v81
	v_cvt_pk_bf16_f32 v76, v84, v85
	v_cvt_pk_bf16_f32 v77, v86, v87
	global_store_dwordx4 v[82:83], v[74:77], off offset:2048
	global_load_dwordx4 v[74:77], v[82:83], off offset:2304
	s_waitcnt vmcnt(0)
	v_lshlrev_b32_e32 v78, 16, v74
	v_and_b32_e32 v79, 0xffff0000, v74
	v_lshlrev_b32_e32 v74, 16, v75
	v_and_b32_e32 v75, 0xffff0000, v75
	v_pk_fma_f32 v[72:73], v[72:73], v[146:147], v[74:75]
	v_lshlrev_b32_e32 v74, 16, v76
	v_and_b32_e32 v75, 0xffff0000, v76
	v_pk_fma_f32 v[74:75], v[66:67], v[144:145], v[74:75]
	v_lshlrev_b32_e32 v66, 16, v77
	v_and_b32_e32 v67, 0xffff0000, v77
	v_pk_fma_f32 v[70:71], v[70:71], v[148:149], v[78:79]
	v_pk_fma_f32 v[76:77], v[68:69], v[142:143], v[66:67]
	v_cvt_pk_bf16_f32 v66, v70, v71
	v_cvt_pk_bf16_f32 v67, v72, v73
	v_cvt_pk_bf16_f32 v68, v74, v75
	v_cvt_pk_bf16_f32 v69, v76, v77
	v_lshl_add_u64 v[70:71], v[158:159], 0, s[6:7]
	global_store_dwordx4 v[82:83], v[66:69], off offset:2304
	global_load_dwordx4 v[66:69], v[70:71], off offset:2048
	s_mov_b64 s[6:7], 0x90000
	s_waitcnt vmcnt(0)
	v_lshlrev_b32_e32 v72, 16, v66
	v_and_b32_e32 v73, 0xffff0000, v66
	v_lshlrev_b32_e32 v66, 16, v67
	v_and_b32_e32 v67, 0xffff0000, v67
	v_pk_fma_f32 v[64:65], v[64:65], v[152:153], v[66:67]
	v_lshlrev_b32_e32 v66, 16, v68
	v_and_b32_e32 v67, 0xffff0000, v68
	v_pk_fma_f32 v[66:67], v[58:59], v[154:155], v[66:67]
	v_lshlrev_b32_e32 v58, 16, v69
	v_and_b32_e32 v59, 0xffff0000, v69
	v_pk_fma_f32 v[62:63], v[62:63], v[156:157], v[72:73]
	v_pk_fma_f32 v[68:69], v[60:61], v[150:151], v[58:59]
	v_cvt_pk_bf16_f32 v58, v62, v63
	v_cvt_pk_bf16_f32 v59, v64, v65
	v_cvt_pk_bf16_f32 v60, v66, v67
	v_cvt_pk_bf16_f32 v61, v68, v69
	global_store_dwordx4 v[70:71], v[58:61], off offset:2048
	global_load_dwordx4 v[58:61], v[70:71], off offset:2304
	s_waitcnt vmcnt(0)
	v_lshlrev_b32_e32 v62, 16, v58
	v_and_b32_e32 v63, 0xffff0000, v58
	v_lshlrev_b32_e32 v58, 16, v59
	v_and_b32_e32 v59, 0xffff0000, v59
	v_pk_fma_f32 v[56:57], v[56:57], v[146:147], v[58:59]
	v_lshlrev_b32_e32 v58, 16, v60
	v_and_b32_e32 v59, 0xffff0000, v60
	v_pk_fma_f32 v[58:59], v[50:51], v[144:145], v[58:59]
	v_lshlrev_b32_e32 v50, 16, v61
	v_and_b32_e32 v51, 0xffff0000, v61
	v_pk_fma_f32 v[54:55], v[54:55], v[148:149], v[62:63]
	v_pk_fma_f32 v[60:61], v[52:53], v[142:143], v[50:51]
	v_cvt_pk_bf16_f32 v50, v54, v55
	v_cvt_pk_bf16_f32 v51, v56, v57
	v_cvt_pk_bf16_f32 v52, v58, v59
	v_cvt_pk_bf16_f32 v53, v60, v61
	v_lshl_add_u64 v[54:55], v[158:159], 0, s[6:7]
	global_store_dwordx4 v[70:71], v[50:53], off offset:2304
	global_load_dwordx4 v[50:53], v[54:55], off offset:2048
	s_mov_b64 s[6:7], 0xa0000
	s_waitcnt vmcnt(0)
	v_lshlrev_b32_e32 v56, 16, v50
	v_and_b32_e32 v57, 0xffff0000, v50
	v_lshlrev_b32_e32 v50, 16, v51
	v_and_b32_e32 v51, 0xffff0000, v51
	v_pk_fma_f32 v[48:49], v[48:49], v[152:153], v[50:51]
	v_lshlrev_b32_e32 v50, 16, v52
	v_and_b32_e32 v51, 0xffff0000, v52
	v_pk_fma_f32 v[50:51], v[42:43], v[154:155], v[50:51]
	v_lshlrev_b32_e32 v42, 16, v53
	v_and_b32_e32 v43, 0xffff0000, v53
	v_pk_fma_f32 v[46:47], v[46:47], v[156:157], v[56:57]
	v_pk_fma_f32 v[52:53], v[44:45], v[150:151], v[42:43]
	v_cvt_pk_bf16_f32 v42, v46, v47
	v_cvt_pk_bf16_f32 v43, v48, v49
	v_cvt_pk_bf16_f32 v44, v50, v51
	v_cvt_pk_bf16_f32 v45, v52, v53
	global_store_dwordx4 v[54:55], v[42:45], off offset:2048
	global_load_dwordx4 v[42:45], v[54:55], off offset:2304
	s_waitcnt vmcnt(0)
	v_lshlrev_b32_e32 v46, 16, v42
	v_and_b32_e32 v47, 0xffff0000, v42
	v_lshlrev_b32_e32 v42, 16, v43
	v_and_b32_e32 v43, 0xffff0000, v43
	v_pk_fma_f32 v[40:41], v[40:41], v[146:147], v[42:43]
	v_lshlrev_b32_e32 v42, 16, v44
	v_and_b32_e32 v43, 0xffff0000, v44
	v_pk_fma_f32 v[42:43], v[34:35], v[144:145], v[42:43]
	v_lshlrev_b32_e32 v34, 16, v45
	v_and_b32_e32 v35, 0xffff0000, v45
	v_pk_fma_f32 v[38:39], v[38:39], v[148:149], v[46:47]
	v_pk_fma_f32 v[44:45], v[36:37], v[142:143], v[34:35]
	v_cvt_pk_bf16_f32 v34, v38, v39
	v_cvt_pk_bf16_f32 v35, v40, v41
	v_cvt_pk_bf16_f32 v36, v42, v43
	v_cvt_pk_bf16_f32 v37, v44, v45
	v_lshl_add_u64 v[38:39], v[158:159], 0, s[6:7]
	global_store_dwordx4 v[54:55], v[34:37], off offset:2304
	global_load_dwordx4 v[34:37], v[38:39], off offset:2048
	s_mov_b64 s[6:7], 0xb0000
	s_waitcnt vmcnt(0)
	v_lshlrev_b32_e32 v40, 16, v34
	v_and_b32_e32 v41, 0xffff0000, v34
	v_lshlrev_b32_e32 v34, 16, v35
	v_and_b32_e32 v35, 0xffff0000, v35
	v_pk_fma_f32 v[32:33], v[32:33], v[152:153], v[34:35]
	v_lshlrev_b32_e32 v34, 16, v36
	v_and_b32_e32 v35, 0xffff0000, v36
	v_pk_fma_f32 v[34:35], v[26:27], v[154:155], v[34:35]
	v_lshlrev_b32_e32 v26, 16, v37
	v_and_b32_e32 v27, 0xffff0000, v37
	v_pk_fma_f32 v[30:31], v[30:31], v[156:157], v[40:41]
	v_pk_fma_f32 v[36:37], v[28:29], v[150:151], v[26:27]
	v_cvt_pk_bf16_f32 v26, v30, v31
	v_cvt_pk_bf16_f32 v27, v32, v33
	v_cvt_pk_bf16_f32 v28, v34, v35
	v_cvt_pk_bf16_f32 v29, v36, v37
	global_store_dwordx4 v[38:39], v[26:29], off offset:2048
	global_load_dwordx4 v[26:29], v[38:39], off offset:2304
	s_waitcnt vmcnt(0)
	v_lshlrev_b32_e32 v30, 16, v26
	v_and_b32_e32 v31, 0xffff0000, v26
	v_lshlrev_b32_e32 v26, 16, v27
	v_and_b32_e32 v27, 0xffff0000, v27
	v_pk_fma_f32 v[24:25], v[24:25], v[146:147], v[26:27]
	v_lshlrev_b32_e32 v26, 16, v28
	v_and_b32_e32 v27, 0xffff0000, v28
	v_pk_fma_f32 v[26:27], v[18:19], v[144:145], v[26:27]
	v_lshlrev_b32_e32 v18, 16, v29
	v_and_b32_e32 v19, 0xffff0000, v29
	v_pk_fma_f32 v[22:23], v[22:23], v[148:149], v[30:31]
	v_pk_fma_f32 v[28:29], v[20:21], v[142:143], v[18:19]
	v_cvt_pk_bf16_f32 v18, v22, v23
	v_cvt_pk_bf16_f32 v19, v24, v25
	v_cvt_pk_bf16_f32 v20, v26, v27
	v_cvt_pk_bf16_f32 v21, v28, v29
	global_store_dwordx4 v[38:39], v[18:21], off offset:2304
	s_nop 1
	v_lshl_add_u64 v[18:19], v[158:159], 0, s[6:7]
	global_load_dwordx4 v[20:23], v[18:19], off offset:2048
	s_waitcnt vmcnt(0)
	v_lshlrev_b32_e32 v24, 16, v20
	v_and_b32_e32 v25, 0xffff0000, v20
	v_lshlrev_b32_e32 v20, 16, v21
	v_and_b32_e32 v21, 0xffff0000, v21
	v_pk_fma_f32 v[16:17], v[16:17], v[152:153], v[20:21]
	v_lshlrev_b32_e32 v20, 16, v22
	v_and_b32_e32 v21, 0xffff0000, v22
	v_pk_fma_f32 v[20:21], v[10:11], v[154:155], v[20:21]
	v_lshlrev_b32_e32 v10, 16, v23
	v_and_b32_e32 v11, 0xffff0000, v23
	v_pk_fma_f32 v[14:15], v[14:15], v[156:157], v[24:25]
	v_pk_fma_f32 v[22:23], v[12:13], v[150:151], v[10:11]
	v_cvt_pk_bf16_f32 v10, v14, v15
	v_cvt_pk_bf16_f32 v11, v16, v17
	v_cvt_pk_bf16_f32 v12, v20, v21
	v_cvt_pk_bf16_f32 v13, v22, v23
	global_store_dwordx4 v[18:19], v[10:13], off offset:2048
	global_load_dwordx4 v[10:13], v[18:19], off offset:2304
	s_waitcnt vmcnt(0)
	v_lshlrev_b32_e32 v14, 16, v10
	v_and_b32_e32 v15, 0xffff0000, v10
	v_lshlrev_b32_e32 v10, 16, v11
	v_and_b32_e32 v11, 0xffff0000, v11
	v_pk_fma_f32 v[8:9], v[8:9], v[146:147], v[10:11]
	v_lshlrev_b32_e32 v10, 16, v12
	v_and_b32_e32 v11, 0xffff0000, v12
	v_pk_fma_f32 v[10:11], v[2:3], v[144:145], v[10:11]
	v_lshlrev_b32_e32 v2, 16, v13
	v_and_b32_e32 v3, 0xffff0000, v13
	v_pk_fma_f32 v[6:7], v[6:7], v[148:149], v[14:15]
	v_pk_fma_f32 v[12:13], v[4:5], v[142:143], v[2:3]
	v_cvt_pk_bf16_f32 v2, v6, v7
	v_cvt_pk_bf16_f32 v3, v8, v9
	v_cvt_pk_bf16_f32 v4, v10, v11
	v_cvt_pk_bf16_f32 v5, v12, v13
	global_store_dwordx4 v[18:19], v[2:5], off offset:2304
	s_cbranch_vccz .LBB0_1399
	s_waitcnt vmcnt(0)
	s_cmpk_gt_u32 s22, 0xff
	s_cbranch_scc1 .LBB0_1412
	s_barrier
